# v44: v43 + G2 tile loop restructured (next-tile prefetch before epilogue; hand-written GLU epilogue with hoisted bias, batched y/z loads, 16B stores)
# speedup vs baseline: 1.0605x; 1.0014x over previous
; DI unsigned pack2(float a, float b) { const hwf32x2 v = {a, b}; const hwbf16x2 r = __builtin_convertvector(v, hwbf16x2); return __builtin_bit_cast(unsigned, r); }
; DI void tile8_order(int L, int nM, int nN, int& pm, int& pn) {
;   const int t = tile_remap(L, nM * nN), nig = 8 * nN, gid = t / nig, fm = gid * 8, gsz = (nM - fm) < 8 ? (nM - fm) : 8;
;   pm = fm + ((t % nig) % gsz); pn = (t % nig) / gsz;
; }
; DI void st_bf4(bf16_t* p, float a, float b, float c, float d) { uint2 v; v.x = pack2(a, b); v.y = pack2(c, d); *(uint2*)p = v; }
; DI void ld_bf4(const bf16_t* p, float& a, float& b, float& c, float& d) {
;   const uint2 v = *(const uint2*)p; a = __uint_as_float(v.x << 16); b = __uint_as_float(v.x & 0xffff0000u); c = __uint_as_float(v.y << 16); d = __uint_as_float(v.y & 0xffff0000u);
; }
; template <class FL, class FS>
; DI void gemm_dispatch(const Sub& s, char* lds_all, const bf16_t* A, const bf16_t* Bt, const int nN256, FL fl, FS fs) {
;   if (!s.samp) {
;     const int nM = 256;
;     for (int L = blockIdx.x; L < nM * nN256; L += gridDim.x) {
;       int pm, pn; tile8_order(L, nM, nN256, pm, pn);
;       gemm8_tile(lds_all, A, Bt, D, pm * 256, pn * 256, fl, fs);
; DI void phase_g2(const Params& p, const Sub& s, char* lds_all) {
;   const bf16_t* A = (const bf16_t*)(p.ws + W_SLOT3);
;   const bf16_t* Bt = (const bf16_t*)(p.ws + W_GLU);
;   const bf16_t* z = (const bf16_t*)(p.ws + W_SLOT2);
;   bf16_t* y2 = (bf16_t*)(p.ws + W_SLOT0);
;   {
;     gemm_dispatch(s, lds_all, A, Bt, 4,
.LBB0_681:
	s_or_b64 exec, exec, s[4:5]
	v_readlane_b32 s0, v251, 0
	s_cmpk_lt_i32 s0, 0x400
	s_cselect_b64 s[6:7], -1, 0
	s_cmpk_gt_i32 s0, 0x3ff
	s_mov_b32 s33, 0
	s_mov_b32 s0, 0
	s_waitcnt lgkmcnt(0)
	v_mov_b32_e32 v0, v182
	s_barrier
	s_cbranch_scc1 .LBB0_690
	s_ashr_i32 s1, s0, 31
	v_readlane_b32 s2, v251, 3
	v_readlane_b32 s3, v251, 4
	s_add_u32 s0, s2, s0
	s_addc_u32 s1, s3, s1
	s_load_dwordx2 s[4:5], s[0:1], 0xf8
	s_load_dwordx2 s[8:9], s[0:1], 0xa8
	s_mov_b32 s46, 0x10000
	s_mov_b32 s47, 0x14000
	s_mov_b64 s[16:17], 0x80
	s_waitcnt lgkmcnt(0)
	s_add_u32 s10, s4, 0x19980000
	s_addc_u32 s11, s5, 0
	s_add_u32 s48, s4, 0x400000
	s_addc_u32 s49, s5, 0
	s_add_u32 s12, s4, 0x11900000
	s_addc_u32 s13, s5, 0
	s_add_u32 s14, s4, 0x1800000
	s_addc_u32 s15, s5, 0
	s_mov_b32 s50, 0x18000
	s_mov_b32 s51, 0x1c000
	s_mov_b64 s[18:19], 0x199c0080
	s_mov_b64 s[20:21], 0x400100
	s_mov_b64 s[22:23], 0x19980100
	s_mov_b64 s[24:25], 0x440100
	s_mov_b64 s[26:27], 0x199c0100
	s_mov_b64 s[28:29], 0x400180
	s_mov_b64 s[30:31], 0x19980180
	s_mov_b64 s[34:35], 0x440180
	s_mov_b64 s[36:37], 0x100
	s_mov_b64 s[38:39], 0x780
	s_movk_i32 s52, 0x100
	v_mov_b32_e32 v184, 1
	v_readlane_b32 s53, v251, 0
	s_mov_b32 s98, 0
	s_branch .LBB0_684
.LBB0_684:
	s_lshl_b32 s0, s53, 7
	s_and_b32 s0, s0, 0x380
	s_ashr_i32 s1, s53, 3
	s_add_i32 s0, s0, s1
	v_mov_b32_e32 v144, v182
	s_ashr_i32 s1, s0, 31
	s_lshr_b32 s1, s1, 27
	v_ashrrev_i32_e32 v200, 31, v144
	v_lshrrev_b32_e32 v200, 26, v200
	s_add_i32 s1, s0, s1
	v_add_u32_e32 v200, v144, v200
	s_and_b32 s2, s1, 0xffe0
	v_ashrrev_i32_e32 v201, 6, v200
	v_bfe_i32 v200, v144, 27, 1
	s_sub_i32 s0, s0, s2
	v_lshlrev_b32_e32 v140, 4, v144
	v_lshrrev_b32_e32 v200, 22, v200
	s_bfe_i32 s2, s0, 0x80000
	v_add_u32_e32 v200, v140, v200
	s_bfe_u32 s2, s2, 0x3000c
	v_and_b32_e32 v200, 0xfffffc00, v200
	s_add_i32 s2, s0, s2
	v_sub_u32_e32 v200, v140, v200
	s_bfe_i32 s3, s2, 0x80000
	s_and_b32 s2, s2, 0xf8
	v_lshrrev_b32_e32 v202, 4, v200
	s_sub_i32 s0, s0, s2
	v_bitop3_b32 v202, v202, v200, 32 bitop3:0x6c
	v_ashrrev_i32_e32 v200, 31, v200
	s_sext_i32_i8 s0, s0
	s_lshl_b32 s1, s1, 6
	v_lshrrev_b32_e32 v200, 26, v200
	s_sext_i32_i16 s3, s3
	s_and_b32 s1, s1, 0xfffff800
	s_lshl_b32 s0, s0, 8
	v_lshlrev_b32_e32 v203, 3, v201
	v_add_u32_e32 v200, v202, v200
	s_add_i32 s42, s0, s1
	s_lshl_b32 s0, s3, 5
	v_and_b32_e32 v203, -16, v203
	v_ashrrev_i32_e32 v204, 6, v200
	s_and_b32 s40, s0, 0xffffff00
	v_add_u32_e32 v200, v204, v203
	v_mul_i32_i24_e32 v203, 64, v204
	s_ashr_i32 s41, s40, 31
	v_lshlrev_b32_e32 v201, 5, v201
	v_sub_u32_e32 v202, v202, v203
	s_lshl_b64 s[0:1], s[40:41], 11
	v_and_b32_e32 v201, 32, v201
	v_ashrrev_i16_sdwa v202, v184, sext(v202) dst_sel:DWORD dst_unused:UNUSED_PAD src0_sel:DWORD src1_sel:BYTE_0
	s_add_u32 s2, s48, s0
	v_add_u32_sdwa v202, v201, sext(v202) dst_sel:DWORD dst_unused:UNUSED_PAD src0_sel:DWORD src1_sel:WORD_0
	v_ashrrev_i32_e32 v201, 31, v200
	s_addc_u32 s3, s49, s1
	v_lshlrev_b64 v[200:201], 11, v[200:201]
	v_ashrrev_i32_e32 v203, 31, v202
	v_lshl_add_u64 v[204:205], s[2:3], 0, v[200:201]
	v_lshlrev_b64 v[202:203], 1, v[202:203]
	v_add_u32_e32 v142, 0x2000, v140
	v_lshl_add_u64 v[208:209], v[204:205], 0, v[202:203]
	v_ashrrev_i32_e32 v204, 31, v142
	v_lshrrev_b32_e32 v204, 22, v204
	v_add_u32_e32 v204, v142, v204
	v_ashrrev_i32_e32 v205, 10, v204
	v_mul_i32_i24_e32 v204, 0x400, v205
	v_sub_u32_e32 v204, v142, v204
	v_lshrrev_b32_e32 v206, 4, v204
	v_bitop3_b32 v206, v206, v204, 32 bitop3:0x6c
	v_ashrrev_i32_e32 v207, 31, v206
	v_lshrrev_b32_e32 v207, 26, v207
	v_add_u32_e32 v207, v206, v207
	v_lshlrev_b32_e32 v204, 3, v205
	v_ashrrev_i32_e32 v210, 6, v207
	v_and_b32_e32 v207, 0xc0, v207
	v_and_b32_e32 v204, -16, v204
	v_lshlrev_b32_e32 v205, 5, v205
	v_sub_u32_e32 v206, v206, v207
	v_add_u32_e32 v204, v210, v204
	v_and_b32_e32 v205, 32, v205
	v_ashrrev_i16_sdwa v206, v184, sext(v206) dst_sel:DWORD dst_unused:UNUSED_PAD src0_sel:DWORD src1_sel:BYTE_0
	v_add_u32_e32 v141, 0x10000, v140
	v_add_u32_sdwa v206, v205, sext(v206) dst_sel:DWORD dst_unused:UNUSED_PAD src0_sel:DWORD src1_sel:WORD_0
	v_ashrrev_i32_e32 v205, 31, v204
	v_readfirstlane_b32 s41, v141
	v_lshlrev_b64 v[204:205], 11, v[204:205]
	v_add_u32_e32 v143, 0x12000, v140
	s_mov_b32 m0, s41
	v_lshl_add_u64 v[210:211], s[2:3], 0, v[204:205]
	v_readfirstlane_b32 s2, v143
	s_ashr_i32 s43, s42, 31
	global_load_lds_dwordx4 v[208:209], off
	s_mov_b32 m0, s2
	s_lshl_b64 s[2:3], s[42:43], 11
	s_add_u32 s44, s10, s2
	s_addc_u32 s45, s11, s3
	v_lshl_add_u64 v[212:213], s[44:45], 0, v[200:201]
	v_lshl_add_u64 v[214:215], s[44:45], 0, v[204:205]
	s_or_b32 s44, s40, 0x80
	s_ashr_i32 s45, s44, 31
	s_lshl_b64 s[44:45], s[44:45], 11
	s_add_u32 s44, s48, s44
	v_ashrrev_i32_e32 v207, 31, v206
	s_addc_u32 s45, s49, s45
	v_lshlrev_b64 v[206:207], 1, v[206:207]
; #define STAGE(P, BASE, br, kt) do { const long _g = (long)(br) * K + (long)(kt) * 64; \
;     _Pragma("unroll") for (int _i = 0; _i < 2; ++_i) { const int _b = tidx * 16 + _i * 8192; int _r, _c; stage_rc8(_b, _r, _c); \
;       __builtin_amdgcn_global_load_lds((const unsigned*)(BASE + _g + (long)_r * K + _c), (LAS unsigned*)((LAS char*)(P) + _b), 16, 0, 0); } } while (0)
; #define LDA(dst, b, h) _Pragma("unroll") for (int m = 0; m < 4; ++m) _Pragma("unroll") for (int k = 0; k < 2; ++k) \
;     dst[m][k] = *reinterpret_cast<const bf16x8*>((const char*)SA(b, h) + lds_byte8(wr * 64 + m * 16 + fr, k * 32 + fq * 8))
; #define LDB(dst, b, h) _Pragma("unroll") for (int n = 0; n < 2; ++n) _Pragma("unroll") for (int k = 0; k < 2; ++k) \
;     dst[n][k] = *reinterpret_cast<const bf16x8*>((const char*)SB(b, h) + lds_byte8(wc * 32 + n * 16 + fr, k * 32 + fq * 8))
; #define WAIT_V(n) asm volatile("s_waitcnt vmcnt(" #n ")" ::: "memory")
; #define BAR __builtin_amdgcn_s_barrier()
; #define SCHED __builtin_amdgcn_sched_barrier(0)
; template <class FL, class FS>
; DI void gemm8_tile(char* shmc, const bf16_t* __restrict__ A, const bf16_t* __restrict__ Bt, const int K, const int brow, const int bcol, FL fl, FS fs) {
;     ...
;   STAGE(SB(0, 0), Bt, bcol, 0); STAGE(SA(0, 0), A, brow, 0);
;   STAGE(SB(0, 1), Bt, bcol + HALF, 0); STAGE(SA(0, 1), A, brow + HALF, 0);
;   if (wr == 1) BAR;
;   WAIT_V(4); BAR;
;   STAGE(SB(1, 0), Bt, bcol, 1); STAGE(SA(1, 0), A, brow, 1); STAGE(SB(1, 1), Bt, bcol + HALF, 1);
;   WAIT_V(6); BAR;
;   for (int t = 0; t < nt - 2; t += 2) {
;     LDB(B0, 0, 0); SCHED; LDA(At, 0, 0); STAGE(SA(1, 1), A, brow + HALF, t + 1);
	v_lshl_add_u64 v[216:217], s[44:45], 0, v[200:201]
	v_lshl_add_u64 v[218:219], s[44:45], 0, v[204:205]
	s_or_b32 s44, s42, 0x80
	v_lshl_add_u64 v[210:211], v[210:211], 0, v[206:207]
	v_readfirstlane_b32 s41, v140
	s_ashr_i32 s45, s44, 31
	global_load_lds_dwordx4 v[210:211], off
	v_lshl_add_u64 v[212:213], v[212:213], 0, v[202:203]
	s_mov_b32 m0, s41
	v_readfirstlane_b32 s41, v142
	v_add_u32_e32 v155, 0x14000, v140
	s_lshl_b64 s[44:45], s[44:45], 11
	global_load_lds_dwordx4 v[212:213], off
	v_lshl_add_u64 v[214:215], v[214:215], 0, v[206:207]
	s_mov_b32 m0, s41
	v_readfirstlane_b32 s41, v155
	v_add_u32_e32 v156, 0x16000, v140
	s_add_u32 s44, s10, s44
	global_load_lds_dwordx4 v[214:215], off
	v_lshl_add_u64 v[216:217], v[216:217], 0, v[202:203]
	s_mov_b32 m0, s41
	v_readfirstlane_b32 s41, v156
	s_addc_u32 s45, s11, s45
	v_add_u32_e32 v157, 0x4000, v140
	global_load_lds_dwordx4 v[216:217], off
	v_lshl_add_u64 v[218:219], v[218:219], 0, v[206:207]
	s_mov_b32 m0, s41
	v_lshl_add_u64 v[220:221], s[44:45], 0, v[200:201]
	v_readfirstlane_b32 s41, v157
	v_add_u32_e32 v158, 0x6000, v140
	global_load_lds_dwordx4 v[218:219], off
	v_lshl_add_u64 v[128:129], v[220:221], 0, v[202:203]
	s_mov_b32 m0, s41
	v_lshl_add_u64 v[220:221], s[44:45], 0, v[204:205]
	v_readfirstlane_b32 s41, v158
	global_load_lds_dwordx4 v[128:129], off
	v_lshl_add_u64 v[130:131], v[220:221], 0, v[206:207]
	s_mov_b32 m0, s41
	v_ashrrev_i32_e32 v220, 8, v144
	global_load_lds_dwordx4 v[130:131], off
	v_add_u32_e32 v159, 0x18000, v140
	v_add_u32_e32 v160, 0x1a000, v140
	v_readfirstlane_b32 s41, v159
	v_lshl_add_u64 v[208:209], v[208:209], 0, s[16:17]
	s_mov_b32 m0, s41
	v_readfirstlane_b32 s41, v160
	v_add_u32_e32 v161, 0x8000, v140
	global_load_lds_dwordx4 v[208:209], off
	v_lshl_add_u64 v[208:209], v[210:211], 0, s[16:17]
	s_mov_b32 m0, s41
	v_readfirstlane_b32 s41, v161
	v_add_u32_e32 v162, 0xa000, v140
	global_load_lds_dwordx4 v[208:209], off
	v_lshl_add_u64 v[208:209], v[212:213], 0, s[16:17]
	s_mov_b32 m0, s41
	v_readfirstlane_b32 s41, v162
	v_add_u32_e32 v163, 0x1c000, v140
	global_load_lds_dwordx4 v[208:209], off
	v_lshl_add_u64 v[208:209], v[214:215], 0, s[16:17]
	s_mov_b32 m0, s41
	v_readfirstlane_b32 s41, v163
	v_add_u32_e32 v165, 0x1e000, v140
	global_load_lds_dwordx4 v[208:209], off
	v_lshl_add_u64 v[208:209], v[216:217], 0, s[16:17]
	s_mov_b32 m0, s41
	v_readfirstlane_b32 s41, v165
	global_load_lds_dwordx4 v[208:209], off
	v_lshl_add_u64 v[208:209], v[218:219], 0, s[16:17]
	s_mov_b32 m0, s41
	v_and_b32_e32 v147, 15, v144
	global_load_lds_dwordx4 v[208:209], off
	v_bfe_u32 v146, v144, 4, 2
	v_lshlrev_b32_e32 v212, 2, v144
	v_lshlrev_b32_e32 v208, 4, v146
	v_lshlrev_b32_e32 v209, 6, v147
	v_and_b32_e32 v212, 32, v212
	v_or_b32_e32 v211, v208, v209
	v_bitop3_b32 v213, v208, v212, v209 bitop3:0x36
	v_lshlrev_b32_e32 v209, 6, v144
	v_and_b32_e32 v209, 0x3c0, v209
	v_bitop3_b32 v214, v211, s46, v212 bitop3:0xde
	v_bitop3_b32 v215, v211, s47, v212 bitop3:0xde
	v_bitop3_b32 v216, v211, s50, v212 bitop3:0xde
	v_bitop3_b32 v211, v211, s51, v212 bitop3:0xde
	v_bitop3_b32 v212, v209, v212, v208 bitop3:0x36
	v_lshl_add_u64 v[208:209], s[0:1], 0, v[200:201]
	v_lshl_add_u64 v[200:201], s[2:3], 0, v[200:201]
	v_bfe_u32 v145, v144, 6, 2
	v_lshlrev_b32_e32 v217, 13, v220
	v_lshl_add_u64 v[136:137], v[200:201], 0, v[202:203]
	v_lshl_add_u64 v[200:201], s[2:3], 0, v[204:205]
	v_lshlrev_b32_e32 v210, 12, v145
	v_lshlrev_b32_e32 v148, 6, v220
	v_or_b32_e32 v218, 0x800, v217
	v_or_b32_e32 v219, 0x1000, v217
	v_or_b32_e32 v220, 0x1800, v217
	v_lshl_add_u64 v[132:133], v[208:209], 0, v[202:203]
	v_lshl_add_u64 v[208:209], s[0:1], 0, v[204:205]
	v_lshl_add_u64 v[138:139], v[200:201], 0, v[206:207]
	v_lshl_add_u64 v[134:135], v[208:209], 0, v[206:207]
	v_add_u32_e32 v168, v214, v210
	v_add_u32_e32 v152, v213, v217
	v_add_u32_e32 v151, v212, v218
	v_add_u32_e32 v150, v212, v219
	v_add_u32_e32 v149, v212, v220
	v_add_u32_e32 v167, 0xc000, v140
	v_add_u32_e32 v166, 0xe000, v140
	v_add_u32_e32 v164, v215, v210
	v_add_u32_e32 v154, v216, v210
	v_add_u32_e32 v153, v211, v210
	v_lshl_add_u64 v[222:223], s[4:5], 0, v[136:137]
	v_readfirstlane_b32 s1, v167
	v_lshl_add_u64 v[222:223], v[222:223], 0, s[18:19]
	s_mov_b32 m0, s1
	v_lshl_add_u64 v[224:225], s[4:5], 0, v[138:139]
	v_readfirstlane_b32 s1, v166
	global_load_lds_dwordx4 v[222:223], off
	v_lshl_add_u64 v[224:225], v[224:225], 0, s[18:19]
	s_mov_b32 m0, s1
	s_nop 0
	global_load_lds_dwordx4 v[224:225], off
	s_cmp_eq_u32 s98, 0
	s_cbranch_scc1 .Lg2_first
	s_mov_b32 s101, 0
	s_branch .Lg2_epi
.Lg2_epi_ret0:
	v_lshrrev_b32_e32 v222, 8, v182
	v_cmp_eq_u32_e32 vcc, 1, v222
	s_and_saveexec_b64 s[44:45], vcc
	s_cbranch_execz .Lg2_nba
	s_barrier
.Lg2_nba:
	s_or_b64 exec, exec, s[44:45]
	s_waitcnt vmcnt(28)
	s_barrier
	s_waitcnt vmcnt(24)
	s_branch .Lg2_zero

; #define STAGE(P, BASE, br, kt) do { const long _g = (long)(br) * K + (long)(kt) * 64; \
;     _Pragma("unroll") for (int _i = 0; _i < 2; ++_i) { const int _b = tidx * 16 + _i * 8192; int _r, _c; stage_rc8(_b, _r, _c); \
;       __builtin_amdgcn_global_load_lds((const unsigned*)(BASE + _g + (long)_r * K + _c), (LAS unsigned*)((LAS char*)(P) + _b), 16, 0, 0); } } while (0)
; #define WAIT_V(n) asm volatile("s_waitcnt vmcnt(" #n ")" ::: "memory")
; #define BAR __builtin_amdgcn_s_barrier()
; template <class FL, class FS>
; DI void gemm8_tile(char* shmc, const bf16_t* __restrict__ A, const bf16_t* __restrict__ Bt, const int K, const int brow, const int bcol, FL fl, FS fs) {
;     ...
;   if (wr == 1) BAR;
;   WAIT_V(4); BAR;
;   STAGE(SB(1, 0), Bt, bcol, 1); STAGE(SA(1, 0), A, brow, 1); STAGE(SB(1, 1), Bt, bcol + HALF, 1);
;   WAIT_V(6); BAR;
.Lg2_nbb:
	s_or_b64 exec, exec, s[44:45]
	s_waitcnt vmcnt(12)
	s_barrier
	s_waitcnt vmcnt(8)

; #define STAGE(P, BASE, br, kt) do { const long _g = (long)(br) * K + (long)(kt) * 64; \
;     _Pragma("unroll") for (int _i = 0; _i < 2; ++_i) { const int _b = tidx * 16 + _i * 8192; int _r, _c; stage_rc8(_b, _r, _c); \
;       __builtin_amdgcn_global_load_lds((const unsigned*)(BASE + _g + (long)_r * K + _c), (LAS unsigned*)((LAS char*)(P) + _b), 16, 0, 0); } } while (0)
; #define LDA(dst, b, h) _Pragma("unroll") for (int m = 0; m < 4; ++m) _Pragma("unroll") for (int k = 0; k < 2; ++k) \
;     dst[m][k] = *reinterpret_cast<const bf16x8*>((const char*)SA(b, h) + lds_byte8(wr * 64 + m * 16 + fr, k * 32 + fq * 8))
; #define LDB(dst, b, h) _Pragma("unroll") for (int n = 0; n < 2; ++n) _Pragma("unroll") for (int k = 0; k < 2; ++k) \
;     dst[n][k] = *reinterpret_cast<const bf16x8*>((const char*)SB(b, h) + lds_byte8(wc * 32 + n * 16 + fr, k * 32 + fq * 8))
; #define MMA(ai, bj, At_, Bt_) do { __builtin_amdgcn_s_setprio(1); \
;     _Pragma("unroll") for (int m = 0; m < 4; ++m) _Pragma("unroll") for (int n = 0; n < 2; ++n) _Pragma("unroll") for (int k = 0; k < 2; ++k) \
;       acc[ai][bj][m][n] = MFMA16(Bt_[n][k], At_[m][k], acc[ai][bj][m][n]); \
;     __builtin_amdgcn_s_setprio(0); } while (0)
; #define WAIT_V(n) asm volatile("s_waitcnt vmcnt(" #n ")" ::: "memory")
; #define WAIT_L(n) asm volatile("s_waitcnt lgkmcnt(" #n ")" ::: "memory")
; #define BAR __builtin_amdgcn_s_barrier()
; #define SCHED __builtin_amdgcn_sched_barrier(0)
; template <class FL, class FS>
; DI void gemm8_tile(char* shmc, const bf16_t* __restrict__ A, const bf16_t* __restrict__ Bt, const int K, const int brow, const int bcol, FL fl, FS fs) {
;     ...
;   for (int t = 0; t < nt - 2; t += 2) {
;     LDB(B0, 0, 0); SCHED; LDA(At, 0, 0); STAGE(SA(1, 1), A, brow + HALF, t + 1);
;     WAIT_L(8); BAR; WAIT_L(0); MMA(0, 0, At, B0); BAR; SCHED;
;     LDB(B1, 0, 1); STAGE(SB(0, 0), Bt, bcol, t + 2);
;     BAR; WAIT_L(0); MMA(0, 1, At, B1); BAR;
;     LDA(At, 0, 1); STAGE(SA(0, 0), A, brow, t + 2);
;     BAR; WAIT_L(0); MMA(1, 0, At, B0); BAR; SCHED;
;     STAGE(SB(0, 1), Bt, bcol + HALF, t + 2);
;     WAIT_V(6); BAR; MMA(1, 1, At, B1); BAR;
.LBB0_687:
	ds_read_b128 v[170:173], v168
	ds_read_b128 v[174:177], v168 offset:1024
	ds_read_b128 v[178:181], v168 offset:2048
	ds_read_b128 v[186:189], v168 offset:3072
	v_lshl_add_u64 v[238:239], s[4:5], 0, v[136:137]
	v_readfirstlane_b32 s1, v167
	v_lshl_add_u64 v[222:223], v[238:239], 0, s[18:19]
	s_mov_b32 m0, s1
	v_lshl_add_u64 v[240:241], s[4:5], 0, v[138:139]
	v_readfirstlane_b32 s1, v166
	ds_read_b128 v[190:193], v152
	ds_read_b128 v[194:197], v152 offset:1024
	ds_read_b128 v[198:201], v151
	ds_read_b128 v[202:205], v151 offset:1024
	ds_read_b128 v[206:209], v150
	ds_read_b128 v[210:213], v150 offset:1024
	ds_read_b128 v[214:217], v149
	ds_read_b128 v[218:221], v149 offset:1024
	s_cmp_eq_u32 s0, -2
	s_cbranch_scc1 .Lg2_p1skip
	global_load_lds_dwordx4 v[222:223], off
	v_lshl_add_u64 v[222:223], v[240:241], 0, s[18:19]
	s_mov_b32 m0, s1
	s_nop 0
	global_load_lds_dwordx4 v[222:223], off
.Lg2_p1skip:
	s_waitcnt lgkmcnt(8)
	s_barrier
	s_waitcnt lgkmcnt(0)
	s_setprio 1
	s_waitcnt lgkmcnt(0)
	v_mfma_f32_16x16x32_bf16 v[124:127], v[170:173], v[190:193], v[124:127]
	v_mfma_f32_16x16x32_bf16 v[120:123], v[178:181], v[190:193], v[120:123]
	v_mfma_f32_16x16x32_bf16 v[116:119], v[170:173], v[198:201], v[116:119]
	v_mfma_f32_16x16x32_bf16 v[112:115], v[178:181], v[198:201], v[112:115]
	v_mfma_f32_16x16x32_bf16 v[108:111], v[170:173], v[206:209], v[108:111]
	v_mfma_f32_16x16x32_bf16 v[104:107], v[178:181], v[206:209], v[104:107]
	v_mfma_f32_16x16x32_bf16 v[100:103], v[170:173], v[214:217], v[100:103]
	v_mfma_f32_16x16x32_bf16 v[96:99], v[178:181], v[214:217], v[96:99]
	v_mfma_f32_16x16x32_bf16 v[124:127], v[174:177], v[194:197], v[124:127]
	v_mfma_f32_16x16x32_bf16 v[120:123], v[186:189], v[194:197], v[120:123]
	v_mfma_f32_16x16x32_bf16 v[116:119], v[174:177], v[202:205], v[116:119]
	v_mfma_f32_16x16x32_bf16 v[112:115], v[186:189], v[202:205], v[112:115]
	v_mfma_f32_16x16x32_bf16 v[108:111], v[174:177], v[210:213], v[108:111]
	v_mfma_f32_16x16x32_bf16 v[104:107], v[186:189], v[210:213], v[104:107]
	v_mfma_f32_16x16x32_bf16 v[100:103], v[174:177], v[218:221], v[100:103]
	v_mfma_f32_16x16x32_bf16 v[96:99], v[186:189], v[218:221], v[96:99]
	s_setprio 0
	s_barrier
	v_lshl_add_u64 v[242:243], s[4:5], 0, v[132:133]
	v_readfirstlane_b32 s1, v141
	v_lshl_add_u64 v[244:245], v[242:243], 0, s[20:21]
	s_mov_b32 m0, s1
	ds_read_b128 v[222:225], v164
	ds_read_b128 v[226:229], v164 offset:1024
	ds_read_b128 v[230:233], v164 offset:2048
	ds_read_b128 v[234:237], v164 offset:3072
	global_load_lds_dwordx4 v[244:245], off
	v_lshl_add_u64 v[244:245], s[4:5], 0, v[134:135]
	v_readfirstlane_b32 s1, v143
	v_lshl_add_u64 v[246:247], v[244:245], 0, s[20:21]
	s_mov_b32 m0, s1
	s_nop 0
	global_load_lds_dwordx4 v[246:247], off
	s_barrier
	s_waitcnt lgkmcnt(0)
	s_setprio 1
	s_waitcnt lgkmcnt(0)
	v_mfma_f32_16x16x32_bf16 v[92:95], v[222:225], v[190:193], v[92:95]
	v_mfma_f32_16x16x32_bf16 v[88:91], v[230:233], v[190:193], v[88:91]
	v_mfma_f32_16x16x32_bf16 v[84:87], v[222:225], v[198:201], v[84:87]
	v_mfma_f32_16x16x32_bf16 v[80:83], v[230:233], v[198:201], v[80:83]
	v_mfma_f32_16x16x32_bf16 v[76:79], v[222:225], v[206:209], v[76:79]
	v_mfma_f32_16x16x32_bf16 v[72:75], v[230:233], v[206:209], v[72:75]
	v_mfma_f32_16x16x32_bf16 v[68:71], v[222:225], v[214:217], v[68:71]
	v_mfma_f32_16x16x32_bf16 v[64:67], v[230:233], v[214:217], v[64:67]
	v_mfma_f32_16x16x32_bf16 v[92:95], v[226:229], v[194:197], v[92:95]
	v_mfma_f32_16x16x32_bf16 v[88:91], v[234:237], v[194:197], v[88:91]
	v_mfma_f32_16x16x32_bf16 v[84:87], v[226:229], v[202:205], v[84:87]
	v_mfma_f32_16x16x32_bf16 v[80:83], v[234:237], v[202:205], v[80:83]
	v_mfma_f32_16x16x32_bf16 v[76:79], v[226:229], v[210:213], v[76:79]
	v_mfma_f32_16x16x32_bf16 v[72:75], v[234:237], v[210:213], v[72:75]
	v_mfma_f32_16x16x32_bf16 v[68:71], v[226:229], v[218:221], v[68:71]
	v_mfma_f32_16x16x32_bf16 v[64:67], v[234:237], v[218:221], v[64:67]
	s_setprio 0
	v_readfirstlane_b32 s1, v140
	v_lshl_add_u64 v[246:247], v[238:239], 0, s[22:23]
	s_mov_b32 m0, s1
	v_readfirstlane_b32 s1, v142
	s_barrier
	ds_read_b128 v[190:193], v152 offset:16384
	ds_read_b128 v[194:197], v152 offset:17408
	ds_read_b128 v[198:201], v151 offset:16384
	ds_read_b128 v[202:205], v151 offset:17408
	ds_read_b128 v[206:209], v150 offset:16384
	ds_read_b128 v[210:213], v150 offset:17408
	ds_read_b128 v[214:217], v149 offset:16384
	ds_read_b128 v[218:221], v149 offset:17408
	global_load_lds_dwordx4 v[246:247], off
	v_lshl_add_u64 v[246:247], v[240:241], 0, s[22:23]
	s_mov_b32 m0, s1
	s_nop 0
	global_load_lds_dwordx4 v[246:247], off
	s_barrier
	s_waitcnt lgkmcnt(0)
	s_setprio 1
	s_waitcnt lgkmcnt(0)
	v_mfma_f32_16x16x32_bf16 v[60:63], v[170:173], v[190:193], v[60:63]
	v_mfma_f32_16x16x32_bf16 v[56:59], v[178:181], v[190:193], v[56:59]
	v_mfma_f32_16x16x32_bf16 v[52:55], v[170:173], v[198:201], v[52:55]
	v_mfma_f32_16x16x32_bf16 v[48:51], v[178:181], v[198:201], v[48:51]
	v_mfma_f32_16x16x32_bf16 v[44:47], v[170:173], v[206:209], v[44:47]
	v_mfma_f32_16x16x32_bf16 v[40:43], v[178:181], v[206:209], v[40:43]
	v_mfma_f32_16x16x32_bf16 v[36:39], v[170:173], v[214:217], v[36:39]
	v_mfma_f32_16x16x32_bf16 v[32:35], v[178:181], v[214:217], v[32:35]
	v_mfma_f32_16x16x32_bf16 v[60:63], v[174:177], v[194:197], v[60:63]
	v_mfma_f32_16x16x32_bf16 v[56:59], v[186:189], v[194:197], v[56:59]
	v_mfma_f32_16x16x32_bf16 v[52:55], v[174:177], v[202:205], v[52:55]
	v_mfma_f32_16x16x32_bf16 v[48:51], v[186:189], v[202:205], v[48:51]
	v_mfma_f32_16x16x32_bf16 v[44:47], v[174:177], v[210:213], v[44:47]
	v_mfma_f32_16x16x32_bf16 v[40:43], v[186:189], v[210:213], v[40:43]
	v_mfma_f32_16x16x32_bf16 v[36:39], v[174:177], v[218:221], v[36:39]
	v_mfma_f32_16x16x32_bf16 v[32:35], v[186:189], v[218:221], v[32:35]
	s_setprio 0
	s_barrier
	v_readfirstlane_b32 s1, v155
	v_lshl_add_u64 v[170:171], v[242:243], 0, s[24:25]
	s_mov_b32 m0, s1
	v_readfirstlane_b32 s1, v156
	global_load_lds_dwordx4 v[170:171], off
	v_lshl_add_u64 v[170:171], v[244:245], 0, s[24:25]
	s_mov_b32 m0, s1
	s_nop 0
	global_load_lds_dwordx4 v[170:171], off
	s_cmp_eq_u32 s0, -2
	s_cselect_b32 s101, s98, 0
	s_cmp_lg_u32 s101, 0
	s_cbranch_scc1 .Lg2_w22
	s_waitcnt vmcnt(6)
; #define STAGE(P, BASE, br, kt) do { const long _g = (long)(br) * K + (long)(kt) * 64; \
;     _Pragma("unroll") for (int _i = 0; _i < 2; ++_i) { const int _b = tidx * 16 + _i * 8192; int _r, _c; stage_rc8(_b, _r, _c); \
;       __builtin_amdgcn_global_load_lds((const unsigned*)(BASE + _g + (long)_r * K + _c), (LAS unsigned*)((LAS char*)(P) + _b), 16, 0, 0); } } while (0)
; #define LDA(dst, b, h) _Pragma("unroll") for (int m = 0; m < 4; ++m) _Pragma("unroll") for (int k = 0; k < 2; ++k) \
;     dst[m][k] = *reinterpret_cast<const bf16x8*>((const char*)SA(b, h) + lds_byte8(wr * 64 + m * 16 + fr, k * 32 + fq * 8))
; #define LDB(dst, b, h) _Pragma("unroll") for (int n = 0; n < 2; ++n) _Pragma("unroll") for (int k = 0; k < 2; ++k) \
;     dst[n][k] = *reinterpret_cast<const bf16x8*>((const char*)SB(b, h) + lds_byte8(wc * 32 + n * 16 + fr, k * 32 + fq * 8))
; #define MMA(ai, bj, At_, Bt_) do { __builtin_amdgcn_s_setprio(1); \
;     _Pragma("unroll") for (int m = 0; m < 4; ++m) _Pragma("unroll") for (int n = 0; n < 2; ++n) _Pragma("unroll") for (int k = 0; k < 2; ++k) \
;       acc[ai][bj][m][n] = MFMA16(Bt_[n][k], At_[m][k], acc[ai][bj][m][n]); \
;     __builtin_amdgcn_s_setprio(0); } while (0)
; #define WAIT_V(n) asm volatile("s_waitcnt vmcnt(" #n ")" ::: "memory")
; #define WAIT_L(n) asm volatile("s_waitcnt lgkmcnt(" #n ")" ::: "memory")
; #define BAR __builtin_amdgcn_s_barrier()
; #define SCHED __builtin_amdgcn_sched_barrier(0)
; template <class FL, class FS>
; DI void gemm8_tile(char* shmc, const bf16_t* __restrict__ A, const bf16_t* __restrict__ Bt, const int K, const int brow, const int bcol, FL fl, FS fs) {
;     ...
;     WAIT_V(6); BAR; MMA(1, 1, At, B1); BAR;
;     LDB(B0, 1, 0); SCHED; LDA(At, 1, 0); STAGE(SA(0, 1), A, brow + HALF, t + 2);
;     WAIT_L(8); BAR; WAIT_L(0); MMA(0, 0, At, B0); BAR; SCHED;
;     LDB(B1, 1, 1); STAGE(SB(1, 0), Bt, bcol, t + 3);
;     BAR; WAIT_L(0); MMA(0, 1, At, B1); BAR;
;     LDA(At, 1, 1); STAGE(SA(1, 0), A, brow, t + 3);
;     BAR; WAIT_L(0); MMA(1, 0, At, B0); BAR; SCHED;
.Lg2_wd:
	s_barrier
	s_setprio 1
	v_mfma_f32_16x16x32_bf16 v[28:31], v[222:225], v[190:193], v[28:31]
	v_mfma_f32_16x16x32_bf16 v[24:27], v[230:233], v[190:193], v[24:27]
	v_mfma_f32_16x16x32_bf16 v[20:23], v[222:225], v[198:201], v[20:23]
	v_mfma_f32_16x16x32_bf16 v[16:19], v[230:233], v[198:201], v[16:19]
	v_mfma_f32_16x16x32_bf16 v[12:15], v[222:225], v[206:209], v[12:15]
	v_mfma_f32_16x16x32_bf16 v[8:11], v[230:233], v[206:209], v[8:11]
	v_mfma_f32_16x16x32_bf16 v[4:7], v[222:225], v[214:217], v[4:7]
	v_mfma_f32_16x16x32_bf16 v[0:3], v[230:233], v[214:217], v[0:3]
	v_mfma_f32_16x16x32_bf16 v[28:31], v[226:229], v[194:197], v[28:31]
	v_mfma_f32_16x16x32_bf16 v[24:27], v[234:237], v[194:197], v[24:27]
	v_mfma_f32_16x16x32_bf16 v[20:23], v[226:229], v[202:205], v[20:23]
	v_mfma_f32_16x16x32_bf16 v[16:19], v[234:237], v[202:205], v[16:19]
	v_mfma_f32_16x16x32_bf16 v[12:15], v[226:229], v[210:213], v[12:15]
	v_mfma_f32_16x16x32_bf16 v[8:11], v[234:237], v[210:213], v[8:11]
	v_mfma_f32_16x16x32_bf16 v[4:7], v[226:229], v[218:221], v[4:7]
	v_mfma_f32_16x16x32_bf16 v[0:3], v[234:237], v[218:221], v[0:3]
	s_setprio 0
	s_barrier
	ds_read_b128 v[170:173], v154
	ds_read_b128 v[174:177], v154 offset:1024
	ds_read_b128 v[178:181], v154 offset:2048
	ds_read_b128 v[186:189], v154 offset:3072
	v_readfirstlane_b32 s1, v157
	v_lshl_add_u64 v[222:223], v[238:239], 0, s[26:27]
	s_mov_b32 m0, s1
	v_readfirstlane_b32 s1, v158
	ds_read_b128 v[190:193], v152 offset:32768
	ds_read_b128 v[194:197], v152 offset:33792
	ds_read_b128 v[198:201], v151 offset:32768
	ds_read_b128 v[202:205], v151 offset:33792
	ds_read_b128 v[206:209], v150 offset:32768
	ds_read_b128 v[210:213], v150 offset:33792
	ds_read_b128 v[214:217], v149 offset:32768
	ds_read_b128 v[218:221], v149 offset:33792
	global_load_lds_dwordx4 v[222:223], off
	v_lshl_add_u64 v[222:223], v[240:241], 0, s[26:27]
	s_mov_b32 m0, s1
	s_nop 0
	global_load_lds_dwordx4 v[222:223], off
	s_waitcnt lgkmcnt(8)
	s_barrier
	s_waitcnt lgkmcnt(0)
	s_setprio 1
	s_waitcnt lgkmcnt(0)
	v_mfma_f32_16x16x32_bf16 v[124:127], v[170:173], v[190:193], v[124:127]
	v_mfma_f32_16x16x32_bf16 v[120:123], v[178:181], v[190:193], v[120:123]
	v_mfma_f32_16x16x32_bf16 v[116:119], v[170:173], v[198:201], v[116:119]
	v_mfma_f32_16x16x32_bf16 v[112:115], v[178:181], v[198:201], v[112:115]
	v_mfma_f32_16x16x32_bf16 v[108:111], v[170:173], v[206:209], v[108:111]
	v_mfma_f32_16x16x32_bf16 v[104:107], v[178:181], v[206:209], v[104:107]
	v_mfma_f32_16x16x32_bf16 v[100:103], v[170:173], v[214:217], v[100:103]
	v_mfma_f32_16x16x32_bf16 v[96:99], v[178:181], v[214:217], v[96:99]
	v_mfma_f32_16x16x32_bf16 v[124:127], v[174:177], v[194:197], v[124:127]
	v_mfma_f32_16x16x32_bf16 v[120:123], v[186:189], v[194:197], v[120:123]
	v_mfma_f32_16x16x32_bf16 v[116:119], v[174:177], v[202:205], v[116:119]
	v_mfma_f32_16x16x32_bf16 v[112:115], v[186:189], v[202:205], v[112:115]
	v_mfma_f32_16x16x32_bf16 v[108:111], v[174:177], v[210:213], v[108:111]
	v_mfma_f32_16x16x32_bf16 v[104:107], v[186:189], v[210:213], v[104:107]
	v_mfma_f32_16x16x32_bf16 v[100:103], v[174:177], v[218:221], v[100:103]
	v_mfma_f32_16x16x32_bf16 v[96:99], v[186:189], v[218:221], v[96:99]
	s_setprio 0
	s_barrier
	v_readfirstlane_b32 s1, v159
	v_lshl_add_u64 v[246:247], v[242:243], 0, s[28:29]
	s_mov_b32 m0, s1
	v_readfirstlane_b32 s1, v160
	ds_read_b128 v[222:225], v153
	ds_read_b128 v[226:229], v153 offset:1024
	ds_read_b128 v[230:233], v153 offset:2048
	ds_read_b128 v[234:237], v153 offset:3072
	global_load_lds_dwordx4 v[246:247], off
	v_lshl_add_u64 v[246:247], v[244:245], 0, s[28:29]
	s_mov_b32 m0, s1
	s_nop 0
	global_load_lds_dwordx4 v[246:247], off
	s_barrier
	s_waitcnt lgkmcnt(0)
	s_setprio 1
	s_waitcnt lgkmcnt(0)
	v_mfma_f32_16x16x32_bf16 v[92:95], v[222:225], v[190:193], v[92:95]
	v_mfma_f32_16x16x32_bf16 v[88:91], v[230:233], v[190:193], v[88:91]
	v_mfma_f32_16x16x32_bf16 v[84:87], v[222:225], v[198:201], v[84:87]
	v_mfma_f32_16x16x32_bf16 v[80:83], v[230:233], v[198:201], v[80:83]
	v_mfma_f32_16x16x32_bf16 v[76:79], v[222:225], v[206:209], v[76:79]
	v_mfma_f32_16x16x32_bf16 v[72:75], v[230:233], v[206:209], v[72:75]
	v_mfma_f32_16x16x32_bf16 v[68:71], v[222:225], v[214:217], v[68:71]
	v_mfma_f32_16x16x32_bf16 v[64:67], v[230:233], v[214:217], v[64:67]
	v_mfma_f32_16x16x32_bf16 v[92:95], v[226:229], v[194:197], v[92:95]
	v_mfma_f32_16x16x32_bf16 v[88:91], v[234:237], v[194:197], v[88:91]
	v_mfma_f32_16x16x32_bf16 v[84:87], v[226:229], v[202:205], v[84:87]
	v_mfma_f32_16x16x32_bf16 v[80:83], v[234:237], v[202:205], v[80:83]
	v_mfma_f32_16x16x32_bf16 v[76:79], v[226:229], v[210:213], v[76:79]
	v_mfma_f32_16x16x32_bf16 v[72:75], v[234:237], v[210:213], v[72:75]
	v_mfma_f32_16x16x32_bf16 v[68:71], v[226:229], v[218:221], v[68:71]
	v_mfma_f32_16x16x32_bf16 v[64:67], v[234:237], v[218:221], v[64:67]
	s_setprio 0
	v_readfirstlane_b32 s1, v161
	v_lshl_add_u64 v[238:239], v[238:239], 0, s[30:31]
	s_mov_b32 m0, s1
	v_readfirstlane_b32 s1, v162
	s_barrier
	ds_read_b128 v[190:193], v152 offset:49152
	ds_read_b128 v[194:197], v152 offset:50176
	ds_read_b128 v[198:201], v151 offset:49152
	ds_read_b128 v[202:205], v151 offset:50176
	ds_read_b128 v[206:209], v150 offset:49152
	ds_read_b128 v[210:213], v150 offset:50176
	ds_read_b128 v[214:217], v149 offset:49152
	ds_read_b128 v[218:221], v149 offset:50176
	global_load_lds_dwordx4 v[238:239], off
	v_lshl_add_u64 v[238:239], v[240:241], 0, s[30:31]
	s_mov_b32 m0, s1
	s_nop 0
	global_load_lds_dwordx4 v[238:239], off
	s_barrier
; #define STAGE(P, BASE, br, kt) do { const long _g = (long)(br) * K + (long)(kt) * 64; \
;     _Pragma("unroll") for (int _i = 0; _i < 2; ++_i) { const int _b = tidx * 16 + _i * 8192; int _r, _c; stage_rc8(_b, _r, _c); \
;       __builtin_amdgcn_global_load_lds((const unsigned*)(BASE + _g + (long)_r * K + _c), (LAS unsigned*)((LAS char*)(P) + _b), 16, 0, 0); } } while (0)
; #define LDA(dst, b, h) _Pragma("unroll") for (int m = 0; m < 4; ++m) _Pragma("unroll") for (int k = 0; k < 2; ++k) \
;     dst[m][k] = *reinterpret_cast<const bf16x8*>((const char*)SA(b, h) + lds_byte8(wr * 64 + m * 16 + fr, k * 32 + fq * 8))
; #define LDB(dst, b, h) _Pragma("unroll") for (int n = 0; n < 2; ++n) _Pragma("unroll") for (int k = 0; k < 2; ++k) \
;     dst[n][k] = *reinterpret_cast<const bf16x8*>((const char*)SB(b, h) + lds_byte8(wc * 32 + n * 16 + fr, k * 32 + fq * 8))
; #define MMA(ai, bj, At_, Bt_) do { __builtin_amdgcn_s_setprio(1); \
;     _Pragma("unroll") for (int m = 0; m < 4; ++m) _Pragma("unroll") for (int n = 0; n < 2; ++n) _Pragma("unroll") for (int k = 0; k < 2; ++k) \
;       acc[ai][bj][m][n] = MFMA16(Bt_[n][k], At_[m][k], acc[ai][bj][m][n]); \
;     __builtin_amdgcn_s_setprio(0); } while (0)
; #define WAIT_V(n) asm volatile("s_waitcnt vmcnt(" #n ")" ::: "memory")
; #define WAIT_L(n) asm volatile("s_waitcnt lgkmcnt(" #n ")" ::: "memory")
; #define BAR __builtin_amdgcn_s_barrier()
; #define SCHED __builtin_amdgcn_sched_barrier(0)
; template <class FL, class FS>
; DI void gemm8_tile(char* shmc, const bf16_t* __restrict__ A, const bf16_t* __restrict__ Bt, const int K, const int brow, const int bcol, FL fl, FS fs) {
;     ...
;     BAR; WAIT_L(0); MMA(1, 0, At, B0); BAR; SCHED;
;     STAGE(SB(1, 1), Bt, bcol + HALF, t + 3);
;     WAIT_V(6); BAR; MMA(1, 1, At, B1); BAR;
;   }
;   { LDB(B0, 0, 0); LDA(At, 0, 0); STAGE(SA(1, 1), A, brow + HALF, nt - 1);
;     BAR; WAIT_L(0); MMA(0, 0, At, B0); BAR;
;     LDB(B1, 0, 1); BAR; WAIT_L(0); MMA(0, 1, At, B1); BAR;
	s_waitcnt lgkmcnt(0)
	s_setprio 1
	s_waitcnt lgkmcnt(0)
	v_mfma_f32_16x16x32_bf16 v[60:63], v[170:173], v[190:193], v[60:63]
	v_mfma_f32_16x16x32_bf16 v[56:59], v[178:181], v[190:193], v[56:59]
	v_mfma_f32_16x16x32_bf16 v[52:55], v[170:173], v[198:201], v[52:55]
	v_mfma_f32_16x16x32_bf16 v[48:51], v[178:181], v[198:201], v[48:51]
	v_mfma_f32_16x16x32_bf16 v[44:47], v[170:173], v[206:209], v[44:47]
	v_mfma_f32_16x16x32_bf16 v[40:43], v[178:181], v[206:209], v[40:43]
	v_mfma_f32_16x16x32_bf16 v[36:39], v[170:173], v[214:217], v[36:39]
	v_mfma_f32_16x16x32_bf16 v[32:35], v[178:181], v[214:217], v[32:35]
	v_mfma_f32_16x16x32_bf16 v[60:63], v[174:177], v[194:197], v[60:63]
	v_mfma_f32_16x16x32_bf16 v[56:59], v[186:189], v[194:197], v[56:59]
	v_mfma_f32_16x16x32_bf16 v[52:55], v[174:177], v[202:205], v[52:55]
	v_mfma_f32_16x16x32_bf16 v[48:51], v[186:189], v[202:205], v[48:51]
	v_mfma_f32_16x16x32_bf16 v[44:47], v[174:177], v[210:213], v[44:47]
	v_mfma_f32_16x16x32_bf16 v[40:43], v[186:189], v[210:213], v[40:43]
	v_mfma_f32_16x16x32_bf16 v[36:39], v[174:177], v[218:221], v[36:39]
	v_mfma_f32_16x16x32_bf16 v[32:35], v[186:189], v[218:221], v[32:35]
	s_setprio 0
	s_barrier
	v_readfirstlane_b32 s1, v163
	v_lshl_add_u64 v[170:171], v[242:243], 0, s[34:35]
	s_mov_b32 m0, s1
	v_readfirstlane_b32 s1, v165
	global_load_lds_dwordx4 v[170:171], off
	v_lshl_add_u64 v[170:171], v[244:245], 0, s[34:35]
	s_mov_b32 m0, s1
	s_nop 0
	global_load_lds_dwordx4 v[170:171], off
	s_waitcnt vmcnt(6)
	s_barrier
	s_setprio 1
	v_mfma_f32_16x16x32_bf16 v[28:31], v[222:225], v[190:193], v[28:31]
	v_mfma_f32_16x16x32_bf16 v[24:27], v[230:233], v[190:193], v[24:27]
	v_mfma_f32_16x16x32_bf16 v[20:23], v[222:225], v[198:201], v[20:23]
	v_mfma_f32_16x16x32_bf16 v[16:19], v[230:233], v[198:201], v[16:19]
	v_mfma_f32_16x16x32_bf16 v[12:15], v[222:225], v[206:209], v[12:15]
	v_mfma_f32_16x16x32_bf16 v[8:11], v[230:233], v[206:209], v[8:11]
	v_mfma_f32_16x16x32_bf16 v[4:7], v[222:225], v[214:217], v[4:7]
	v_mfma_f32_16x16x32_bf16 v[0:3], v[230:233], v[214:217], v[0:3]
	v_mfma_f32_16x16x32_bf16 v[28:31], v[226:229], v[194:197], v[28:31]
	v_mfma_f32_16x16x32_bf16 v[24:27], v[234:237], v[194:197], v[24:27]
	v_mfma_f32_16x16x32_bf16 v[20:23], v[226:229], v[202:205], v[20:23]
	v_mfma_f32_16x16x32_bf16 v[16:19], v[234:237], v[202:205], v[16:19]
	v_mfma_f32_16x16x32_bf16 v[12:15], v[226:229], v[210:213], v[12:15]
	v_mfma_f32_16x16x32_bf16 v[8:11], v[234:237], v[210:213], v[8:11]
	v_mfma_f32_16x16x32_bf16 v[4:7], v[226:229], v[218:221], v[4:7]
	v_mfma_f32_16x16x32_bf16 v[0:3], v[234:237], v[218:221], v[0:3]
	s_setprio 0
	s_add_i32 s0, s0, 2
	v_lshl_add_u64 v[132:133], v[132:133], 0, s[36:37]
	v_lshl_add_u64 v[134:135], v[134:135], 0, s[36:37]
	v_lshl_add_u64 v[136:137], v[136:137], 0, s[36:37]
	s_cmp_lt_u32 s0, 12
	v_lshl_add_u64 v[138:139], v[138:139], 0, s[36:37]
	s_barrier
	s_cbranch_scc1 .LBB0_687
	v_readfirstlane_b32 s0, v167
	v_lshl_add_u64 v[128:129], v[128:129], 0, s[38:39]
	s_mov_b32 m0, s0
	v_readfirstlane_b32 s0, v166
	ds_read_b128 v[132:135], v168
	ds_read_b128 v[136:139], v168 offset:1024
	ds_read_b128 v[140:143], v168 offset:2048
	ds_read_b128 v[156:159], v168 offset:3072
	ds_read_b128 v[160:163], v152
	ds_read_b128 v[168:171], v152 offset:1024
	ds_read_b128 v[172:175], v151
	ds_read_b128 v[176:179], v151 offset:1024
	ds_read_b128 v[186:189], v150
	ds_read_b128 v[190:193], v150 offset:1024
	ds_read_b128 v[194:197], v149
	ds_read_b128 v[198:201], v149 offset:1024
	global_load_lds_dwordx4 v[128:129], off
	v_lshl_add_u64 v[128:129], v[130:131], 0, s[38:39]
	s_mov_b32 m0, s0
	s_nop 0
	global_load_lds_dwordx4 v[128:129], off
	s_barrier
	s_waitcnt lgkmcnt(0)
	s_setprio 1
	s_waitcnt lgkmcnt(0)
	v_mfma_f32_16x16x32_bf16 v[120:123], v[140:143], v[160:163], v[120:123]
	v_mfma_f32_16x16x32_bf16 v[100:103], v[132:135], v[194:197], v[100:103]
	v_mfma_f32_16x16x32_bf16 v[96:99], v[140:143], v[194:197], v[96:99]
	v_mfma_f32_16x16x32_bf16 v[124:127], v[132:135], v[160:163], v[124:127]
	v_mfma_f32_16x16x32_bf16 v[120:123], v[156:159], v[168:171], v[120:123]
	v_mfma_f32_16x16x32_bf16 v[116:119], v[132:135], v[172:175], v[116:119]
	v_mfma_f32_16x16x32_bf16 v[112:115], v[140:143], v[172:175], v[112:115]
	v_mfma_f32_16x16x32_bf16 v[108:111], v[132:135], v[186:189], v[108:111]
	v_mfma_f32_16x16x32_bf16 v[104:107], v[140:143], v[186:189], v[104:107]
	v_mfma_f32_16x16x32_bf16 v[100:103], v[136:139], v[198:201], v[100:103]
	v_mfma_f32_16x16x32_bf16 v[96:99], v[156:159], v[198:201], v[96:99]
	v_mfma_f32_16x16x32_bf16 v[124:127], v[136:139], v[168:171], v[124:127]
	v_mfma_f32_16x16x32_bf16 v[116:119], v[136:139], v[176:179], v[116:119]
	v_mfma_f32_16x16x32_bf16 v[128:131], v[156:159], v[176:179], v[112:115]
	v_mfma_f32_16x16x32_bf16 v[108:111], v[136:139], v[190:193], v[108:111]
	v_mfma_f32_16x16x32_bf16 v[202:205], v[156:159], v[190:193], v[104:107]
	s_setprio 0
	s_barrier
	ds_read_b128 v[104:107], v164
	ds_read_b128 v[112:115], v164 offset:1024
	ds_read_b128 v[206:209], v164 offset:2048
	ds_read_b128 v[164:167], v164 offset:3072
	s_barrier
; #define LDA(dst, b, h) _Pragma("unroll") for (int m = 0; m < 4; ++m) _Pragma("unroll") for (int k = 0; k < 2; ++k) \
;     dst[m][k] = *reinterpret_cast<const bf16x8*>((const char*)SA(b, h) + lds_byte8(wr * 64 + m * 16 + fr, k * 32 + fq * 8))
; #define LDB(dst, b, h) _Pragma("unroll") for (int n = 0; n < 2; ++n) _Pragma("unroll") for (int k = 0; k < 2; ++k) \
;     dst[n][k] = *reinterpret_cast<const bf16x8*>((const char*)SB(b, h) + lds_byte8(wc * 32 + n * 16 + fr, k * 32 + fq * 8))
; #define MMA(ai, bj, At_, Bt_) do { __builtin_amdgcn_s_setprio(1); \
;     _Pragma("unroll") for (int m = 0; m < 4; ++m) _Pragma("unroll") for (int n = 0; n < 2; ++n) _Pragma("unroll") for (int k = 0; k < 2; ++k) \
;       acc[ai][bj][m][n] = MFMA16(Bt_[n][k], At_[m][k], acc[ai][bj][m][n]); \
;     __builtin_amdgcn_s_setprio(0); } while (0)
; #define WAIT_V(n) asm volatile("s_waitcnt vmcnt(" #n ")" ::: "memory")
; #define WAIT_L(n) asm volatile("s_waitcnt lgkmcnt(" #n ")" ::: "memory")
; #define BAR __builtin_amdgcn_s_barrier()
; template <class FL, class FS>
; DI void gemm8_tile(char* shmc, const bf16_t* __restrict__ A, const bf16_t* __restrict__ Bt, const int K, const int brow, const int bcol, FL fl, FS fs) {
;     ...
;     LDB(B1, 0, 1); BAR; WAIT_L(0); MMA(0, 1, At, B1); BAR;
;     LDA(At, 0, 1); WAIT_V(4); BAR; WAIT_L(0); MMA(1, 0, At, B0); MMA(1, 1, At, B1); BAR; }
;   { LDB(B0, 1, 0); LDA(At, 1, 0); WAIT_V(2); BAR; WAIT_L(0); MMA(0, 0, At, B0); BAR;
;     LDB(B1, 1, 1); WAIT_V(0); BAR; WAIT_L(0); MMA(0, 1, At, B1); BAR;
	s_waitcnt lgkmcnt(0)
	s_setprio 1
	s_waitcnt lgkmcnt(3)
	v_mfma_f32_16x16x32_bf16 v[84:87], v[104:107], v[172:175], v[84:87]
	s_waitcnt lgkmcnt(1)
	v_mfma_f32_16x16x32_bf16 v[80:83], v[206:209], v[172:175], v[80:83]
	v_mfma_f32_16x16x32_bf16 v[68:71], v[104:107], v[194:197], v[68:71]
	v_mfma_f32_16x16x32_bf16 v[64:67], v[206:209], v[194:197], v[64:67]
	v_mfma_f32_16x16x32_bf16 v[92:95], v[104:107], v[160:163], v[92:95]
	v_mfma_f32_16x16x32_bf16 v[88:91], v[206:209], v[160:163], v[88:91]
	v_mfma_f32_16x16x32_bf16 v[84:87], v[112:115], v[176:179], v[84:87]
	s_waitcnt lgkmcnt(0)
	v_mfma_f32_16x16x32_bf16 v[80:83], v[164:167], v[176:179], v[80:83]
	v_mfma_f32_16x16x32_bf16 v[76:79], v[104:107], v[186:189], v[76:79]
	v_mfma_f32_16x16x32_bf16 v[72:75], v[206:209], v[186:189], v[72:75]
	v_mfma_f32_16x16x32_bf16 v[68:71], v[112:115], v[198:201], v[68:71]
	v_mfma_f32_16x16x32_bf16 v[64:67], v[164:167], v[198:201], v[64:67]
	v_mfma_f32_16x16x32_bf16 v[210:213], v[112:115], v[168:171], v[92:95]
	v_mfma_f32_16x16x32_bf16 v[160:163], v[164:167], v[168:171], v[88:91]
	v_mfma_f32_16x16x32_bf16 v[168:171], v[112:115], v[190:193], v[76:79]
	v_mfma_f32_16x16x32_bf16 v[172:175], v[164:167], v[190:193], v[72:75]
	s_setprio 0
	s_barrier
	s_nop 0
	ds_read_b128 v[72:75], v152 offset:16384
	ds_read_b128 v[76:79], v152 offset:17408
	ds_read_b128 v[88:91], v151 offset:16384
	ds_read_b128 v[92:95], v151 offset:17408
	ds_read_b128 v[176:179], v150 offset:16384
	ds_read_b128 v[186:189], v150 offset:17408
	ds_read_b128 v[190:193], v149 offset:16384
	ds_read_b128 v[194:197], v149 offset:17408
	s_waitcnt vmcnt(4)
	s_barrier
	s_waitcnt lgkmcnt(0)
	s_setprio 1
	s_waitcnt lgkmcnt(7)
	v_mfma_f32_16x16x32_bf16 v[60:63], v[132:135], v[72:75], v[60:63]
	v_mfma_f32_16x16x32_bf16 v[56:59], v[140:143], v[72:75], v[56:59]
	s_waitcnt lgkmcnt(5)
	v_mfma_f32_16x16x32_bf16 v[52:55], v[132:135], v[88:91], v[52:55]
	v_mfma_f32_16x16x32_bf16 v[48:51], v[140:143], v[88:91], v[48:51]
	s_waitcnt lgkmcnt(1)
	v_mfma_f32_16x16x32_bf16 v[36:39], v[132:135], v[190:193], v[36:39]
	v_mfma_f32_16x16x32_bf16 v[32:35], v[140:143], v[190:193], v[32:35]
	v_mfma_f32_16x16x32_bf16 v[60:63], v[136:139], v[76:79], v[60:63]
	v_mfma_f32_16x16x32_bf16 v[56:59], v[156:159], v[76:79], v[56:59]
	v_mfma_f32_16x16x32_bf16 v[52:55], v[136:139], v[92:95], v[52:55]
	v_mfma_f32_16x16x32_bf16 v[48:51], v[156:159], v[92:95], v[48:51]
	v_mfma_f32_16x16x32_bf16 v[44:47], v[132:135], v[176:179], v[44:47]
	v_mfma_f32_16x16x32_bf16 v[40:43], v[140:143], v[176:179], v[40:43]
	s_waitcnt lgkmcnt(0)
	v_mfma_f32_16x16x32_bf16 v[36:39], v[136:139], v[194:197], v[36:39]
	v_mfma_f32_16x16x32_bf16 v[32:35], v[156:159], v[194:197], v[32:35]
	v_mfma_f32_16x16x32_bf16 v[198:201], v[136:139], v[186:189], v[44:47]
	v_mfma_f32_16x16x32_bf16 v[214:217], v[156:159], v[186:189], v[40:43]
	s_setprio 0
	s_setprio 1
	v_mfma_f32_16x16x32_bf16 v[20:23], v[104:107], v[88:91], v[20:23]
	v_mfma_f32_16x16x32_bf16 v[16:19], v[206:209], v[88:91], v[16:19]
	v_mfma_f32_16x16x32_bf16 v[4:7], v[104:107], v[190:193], v[4:7]
	v_mfma_f32_16x16x32_bf16 v[0:3], v[206:209], v[190:193], v[0:3]
	v_mfma_f32_16x16x32_bf16 v[28:31], v[104:107], v[72:75], v[28:31]
	v_mfma_f32_16x16x32_bf16 v[24:27], v[206:209], v[72:75], v[24:27]
	v_mfma_f32_16x16x32_bf16 v[20:23], v[112:115], v[92:95], v[20:23]
	v_mfma_f32_16x16x32_bf16 v[16:19], v[164:167], v[92:95], v[16:19]
	v_mfma_f32_16x16x32_bf16 v[12:15], v[104:107], v[176:179], v[12:15]
	v_mfma_f32_16x16x32_bf16 v[8:11], v[206:209], v[176:179], v[8:11]
	v_mfma_f32_16x16x32_bf16 v[4:7], v[112:115], v[194:197], v[4:7]
	v_mfma_f32_16x16x32_bf16 v[0:3], v[164:167], v[194:197], v[0:3]
	v_mfma_f32_16x16x32_bf16 v[156:159], v[112:115], v[76:79], v[28:31]
	v_mfma_f32_16x16x32_bf16 v[218:221], v[164:167], v[76:79], v[24:27]
	v_mfma_f32_16x16x32_bf16 v[222:225], v[112:115], v[186:189], v[12:15]
	v_mfma_f32_16x16x32_bf16 v[176:179], v[164:167], v[186:189], v[8:11]
	s_setprio 0
	s_barrier
	s_nop 0
	ds_read_b128 v[8:11], v154
	ds_read_b128 v[12:15], v154 offset:1024
	ds_read_b128 v[164:167], v154 offset:2048
	ds_read_b128 v[186:189], v154 offset:3072
	ds_read_b128 v[24:27], v152 offset:32768
	ds_read_b128 v[28:31], v152 offset:33792
	ds_read_b128 v[40:43], v151 offset:32768
	ds_read_b128 v[44:47], v151 offset:33792
	ds_read_b128 v[190:193], v150 offset:32768
	ds_read_b128 v[194:197], v150 offset:33792
	ds_read_b128 v[206:209], v149 offset:32768
	ds_read_b128 v[226:229], v149 offset:33792
	s_waitcnt vmcnt(2)
	s_barrier
	s_waitcnt lgkmcnt(0)
	s_setprio 1
	s_waitcnt lgkmcnt(7)
	v_mfma_f32_16x16x32_bf16 v[72:75], v[8:11], v[24:27], v[124:127]
	s_waitcnt lgkmcnt(6)
	v_mfma_f32_16x16x32_bf16 v[140:143], v[12:15], v[28:31], v[72:75]
	v_mfma_f32_16x16x32_bf16 v[72:75], v[164:167], v[24:27], v[120:123]
	v_mfma_f32_16x16x32_bf16 v[136:139], v[186:189], v[28:31], v[72:75]
	s_waitcnt lgkmcnt(5)
	v_mfma_f32_16x16x32_bf16 v[72:75], v[8:11], v[40:43], v[116:119]
	s_waitcnt lgkmcnt(4)
	v_mfma_f32_16x16x32_bf16 v[112:115], v[12:15], v[44:47], v[72:75]
	v_mfma_f32_16x16x32_bf16 v[72:75], v[164:167], v[40:43], v[128:131]
	v_mfma_f32_16x16x32_bf16 v[104:107], v[186:189], v[44:47], v[72:75]
	s_waitcnt lgkmcnt(3)
	v_mfma_f32_16x16x32_bf16 v[72:75], v[8:11], v[190:193], v[108:111]
	s_waitcnt lgkmcnt(2)
	v_mfma_f32_16x16x32_bf16 v[92:95], v[12:15], v[194:197], v[72:75]
	v_mfma_f32_16x16x32_bf16 v[72:75], v[164:167], v[190:193], v[202:205]
	v_mfma_f32_16x16x32_bf16 v[88:91], v[186:189], v[194:197], v[72:75]
	s_waitcnt lgkmcnt(1)
	v_mfma_f32_16x16x32_bf16 v[72:75], v[8:11], v[206:209], v[100:103]
	s_waitcnt lgkmcnt(0)
	v_mfma_f32_16x16x32_bf16 v[76:79], v[12:15], v[226:229], v[72:75]
	v_mfma_f32_16x16x32_bf16 v[72:75], v[164:167], v[206:209], v[96:99]
	v_mfma_f32_16x16x32_bf16 v[72:75], v[186:189], v[226:229], v[72:75]
	s_setprio 0
	s_barrier
; #define LDA(dst, b, h) _Pragma("unroll") for (int m = 0; m < 4; ++m) _Pragma("unroll") for (int k = 0; k < 2; ++k) \
;     dst[m][k] = *reinterpret_cast<const bf16x8*>((const char*)SA(b, h) + lds_byte8(wr * 64 + m * 16 + fr, k * 32 + fq * 8))
; #define LDB(dst, b, h) _Pragma("unroll") for (int n = 0; n < 2; ++n) _Pragma("unroll") for (int k = 0; k < 2; ++k) \
;     dst[n][k] = *reinterpret_cast<const bf16x8*>((const char*)SB(b, h) + lds_byte8(wc * 32 + n * 16 + fr, k * 32 + fq * 8))
; #define MMA(ai, bj, At_, Bt_) do { __builtin_amdgcn_s_setprio(1); \
;     _Pragma("unroll") for (int m = 0; m < 4; ++m) _Pragma("unroll") for (int n = 0; n < 2; ++n) _Pragma("unroll") for (int k = 0; k < 2; ++k) \
;       acc[ai][bj][m][n] = MFMA16(Bt_[n][k], At_[m][k], acc[ai][bj][m][n]); \
;     __builtin_amdgcn_s_setprio(0); } while (0)
; #define WAIT_V(n) asm volatile("s_waitcnt vmcnt(" #n ")" ::: "memory")
; #define WAIT_L(n) asm volatile("s_waitcnt lgkmcnt(" #n ")" ::: "memory")
; #define BAR __builtin_amdgcn_s_barrier()
; template <class FL, class FS>
; DI void gemm8_tile(char* shmc, const bf16_t* __restrict__ A, const bf16_t* __restrict__ Bt, const int K, const int brow, const int bcol, FL fl, FS fs) {
;     ...
;     LDB(B1, 1, 1); WAIT_V(0); BAR; WAIT_L(0); MMA(0, 1, At, B1); BAR;
;     LDA(At, 1, 1); BAR; WAIT_L(0); MMA(1, 0, At, B0); MMA(1, 1, At, B1); BAR; }
;   if (wr == 0) BAR;
; template <class FL, class FS>
; DI void gemm_dispatch(const Sub& s, char* lds_all, const bf16_t* A, const bf16_t* Bt, const int nN256, FL fl, FS fs) {
;     ...
;     for (int L = blockIdx.x; L < nM * nN256; L += gridDim.x) {
;       int pm, pn; tile8_order(L, nM, nN256, pm, pn);
;       gemm8_tile(lds_all, A, Bt, D, pm * 256, pn * 256, fl, fs);
	ds_read_b128 v[108:111], v153
	ds_read_b128 v[116:119], v153 offset:1024
	ds_read_b128 v[124:127], v153 offset:2048
	ds_read_b128 v[128:131], v153 offset:3072
	s_waitcnt vmcnt(0)
	s_barrier
	s_waitcnt lgkmcnt(0)
	s_setprio 1
	s_waitcnt lgkmcnt(3)
	v_mfma_f32_16x16x32_bf16 v[96:99], v[108:111], v[24:27], v[210:213]
	s_waitcnt lgkmcnt(1)
	v_mfma_f32_16x16x32_bf16 v[24:27], v[124:127], v[24:27], v[160:163]
	s_waitcnt lgkmcnt(0)
	v_mfma_f32_16x16x32_bf16 v[120:123], v[128:131], v[28:31], v[24:27]
	v_mfma_f32_16x16x32_bf16 v[24:27], v[108:111], v[40:43], v[84:87]
	v_mfma_f32_16x16x32_bf16 v[100:103], v[116:119], v[44:47], v[24:27]
	v_mfma_f32_16x16x32_bf16 v[24:27], v[124:127], v[40:43], v[80:83]
	v_mfma_f32_16x16x32_bf16 v[132:135], v[116:119], v[28:31], v[96:99]
	v_mfma_f32_16x16x32_bf16 v[96:99], v[128:131], v[44:47], v[24:27]
	v_mfma_f32_16x16x32_bf16 v[24:27], v[108:111], v[190:193], v[168:171]
	v_mfma_f32_16x16x32_bf16 v[84:87], v[116:119], v[194:197], v[24:27]
	v_mfma_f32_16x16x32_bf16 v[24:27], v[124:127], v[190:193], v[172:175]
	v_mfma_f32_16x16x32_bf16 v[80:83], v[128:131], v[194:197], v[24:27]
	v_mfma_f32_16x16x32_bf16 v[24:27], v[108:111], v[206:209], v[68:71]
	v_mfma_f32_16x16x32_bf16 v[68:71], v[116:119], v[226:229], v[24:27]
	v_mfma_f32_16x16x32_bf16 v[24:27], v[124:127], v[206:209], v[64:67]
	v_mfma_f32_16x16x32_bf16 v[64:67], v[128:131], v[226:229], v[24:27]
	s_setprio 0
	s_barrier
	ds_read_b128 v[160:163], v152 offset:49152
	ds_read_b128 v[152:155], v152 offset:50176
	ds_read_b128 v[168:171], v151 offset:49152
	ds_read_b128 v[172:175], v151 offset:50176
	ds_read_b128 v[190:193], v150 offset:49152
	ds_read_b128 v[194:197], v150 offset:50176
	ds_read_b128 v[202:205], v149 offset:49152
	ds_read_b128 v[206:209], v149 offset:50176
	s_barrier
	s_waitcnt lgkmcnt(0)
	s_setprio 1
	s_waitcnt lgkmcnt(7)
	v_mfma_f32_16x16x32_bf16 v[24:27], v[8:11], v[160:163], v[60:63]
	s_waitcnt lgkmcnt(6)
	v_mfma_f32_16x16x32_bf16 v[60:63], v[12:15], v[152:155], v[24:27]
	v_mfma_f32_16x16x32_bf16 v[24:27], v[164:167], v[160:163], v[56:59]
	v_mfma_f32_16x16x32_bf16 v[56:59], v[186:189], v[152:155], v[24:27]
	s_waitcnt lgkmcnt(5)
	v_mfma_f32_16x16x32_bf16 v[24:27], v[8:11], v[168:171], v[52:55]
	s_waitcnt lgkmcnt(4)
	v_mfma_f32_16x16x32_bf16 v[44:47], v[12:15], v[172:175], v[24:27]
	v_mfma_f32_16x16x32_bf16 v[24:27], v[164:167], v[168:171], v[48:51]
	v_mfma_f32_16x16x32_bf16 v[40:43], v[186:189], v[172:175], v[24:27]
	s_waitcnt lgkmcnt(3)
	v_mfma_f32_16x16x32_bf16 v[24:27], v[8:11], v[190:193], v[198:201]
	s_waitcnt lgkmcnt(1)
	v_mfma_f32_16x16x32_bf16 v[8:11], v[8:11], v[202:205], v[36:39]
	v_mfma_f32_16x16x32_bf16 v[28:31], v[12:15], v[194:197], v[24:27]
	v_mfma_f32_16x16x32_bf16 v[24:27], v[164:167], v[190:193], v[214:217]
	s_waitcnt lgkmcnt(0)
	v_mfma_f32_16x16x32_bf16 v[12:15], v[12:15], v[206:209], v[8:11]
	v_mfma_f32_16x16x32_bf16 v[8:11], v[164:167], v[202:205], v[32:35]
	v_mfma_f32_16x16x32_bf16 v[24:27], v[186:189], v[194:197], v[24:27]
	v_mfma_f32_16x16x32_bf16 v[8:11], v[186:189], v[206:209], v[8:11]
	s_setprio 0
	s_setprio 1
	v_mfma_f32_16x16x32_bf16 v[32:35], v[108:111], v[160:163], v[156:159]
	v_mfma_f32_16x16x32_bf16 v[52:55], v[116:119], v[152:155], v[32:35]
	v_mfma_f32_16x16x32_bf16 v[32:35], v[124:127], v[160:163], v[218:221]
	v_mfma_f32_16x16x32_bf16 v[16:19], v[124:127], v[168:171], v[16:19]
	v_mfma_f32_16x16x32_bf16 v[48:51], v[128:131], v[152:155], v[32:35]
	v_mfma_f32_16x16x32_bf16 v[20:23], v[108:111], v[168:171], v[20:23]
	v_mfma_f32_16x16x32_bf16 v[32:35], v[128:131], v[172:175], v[16:19]
	v_mfma_f32_16x16x32_bf16 v[16:19], v[108:111], v[190:193], v[222:225]
	v_mfma_f32_16x16x32_bf16 v[36:39], v[116:119], v[172:175], v[20:23]
	v_mfma_f32_16x16x32_bf16 v[20:23], v[116:119], v[194:197], v[16:19]
	v_mfma_f32_16x16x32_bf16 v[16:19], v[124:127], v[190:193], v[176:179]
	v_mfma_f32_16x16x32_bf16 v[4:7], v[108:111], v[202:205], v[4:7]
	v_mfma_f32_16x16x32_bf16 v[0:3], v[124:127], v[202:205], v[0:3]
	v_mfma_f32_16x16x32_bf16 v[16:19], v[128:131], v[194:197], v[16:19]
	v_mfma_f32_16x16x32_bf16 v[4:7], v[116:119], v[206:209], v[4:7]
	v_mfma_f32_16x16x32_bf16 v[0:3], v[128:131], v[206:209], v[0:3]
	s_setprio 0
	v_cmp_gt_u32_e32 vcc, s52, v144
	s_barrier
	s_and_saveexec_b64 s[0:1], vcc
	s_cbranch_execz .Lg2_wr0
	s_barrier
.Lg2_wr0:
	s_or_b64 exec, exec, s[0:1]
	s_mov_b32 s99, s42
	s_mov_b32 s100, s40
	s_mov_b32 s98, 1
	s_nop 4
	v_mov_b32_e32 v228, v132
	v_mov_b32_e32 v229, v133
	v_mov_b32_e32 v230, v134
	v_mov_b32_e32 v231, v135
	v_mov_b32_e32 v232, v136
	v_mov_b32_e32 v233, v137
	v_mov_b32_e32 v234, v138
	v_mov_b32_e32 v235, v139
	v_mov_b32_e32 v236, v140
	v_mov_b32_e32 v237, v141
	v_mov_b32_e32 v238, v142
	v_mov_b32_e32 v239, v143
	v_readlane_b32 s0, v251, 1
	s_add_i32 s53, s53, s0
	s_cmpk_lt_i32 s53, 0x400
	s_cbranch_scc1 .LBB0_684
	s_mov_b32 s101, 1
; DI void st_bf4(bf16_t* p, float a, float b, float c, float d) { uint2 v; v.x = pack2(a, b); v.y = pack2(c, d); *(uint2*)p = v; }
; DI float sigmoidf_(float x) { return __builtin_amdgcn_rcpf(1.0f + __expf(-x)); }
; DI float siluf_(float x) { return x * sigmoidf_(x); }
; DI void phase_g2(const Params& p, const Sub& s, char* lds_all) {
;     ...
;       [&](int row, int col) { const size_t o = (size_t)row * D + col; Ld2 r; const uint2 a = *(const uint2*)(A + o), b = *(const uint2*)(z + o);
;         r.a.x = __uint_as_float(a.x); r.a.y = __uint_as_float(a.y); r.a.z = __uint_as_float(b.x); r.a.w = __uint_as_float(b.y); r.b = *(const float4*)(p.s5_b_glu + col); return r; },
;       [&](int row, int col, f32x4 v, const Ld2& l2) {
;         uint4 ld; ld.x = __float_as_uint(l2.a.x); ld.y = __float_as_uint(l2.a.y); ld.z = __float_as_uint(l2.a.z); ld.w = __float_as_uint(l2.a.w);
;         const size_t o = (size_t)row * D + col;
;         const float y0 = __uint_as_float(ld.x << 16), y1 = __uint_as_float(ld.x & 0xffff0000u), y2_ = __uint_as_float(ld.y << 16), y3 = __uint_as_float(ld.y & 0xffff0000u);
;         const float z0 = __uint_as_float(ld.z << 16), z1 = __uint_as_float(ld.z & 0xffff0000u), z2 = __uint_as_float(ld.w << 16), z3 = __uint_as_float(ld.w & 0xffff0000u);
;         const float4 b4 = l2.b;
;         st_bf4(y2 + o, y0 * sigmoidf_(v[0] + b4.x) * siluf_(z0), y1 * sigmoidf_(v[1] + b4.y) * siluf_(z1),
;                y2_ * sigmoidf_(v[2] + b4.z) * siluf_(z2), y3 * sigmoidf_(v[3] + b4.w) * siluf_(z3));
.Lg2_epi:
	v_and_b32_e32 v169, 15, v182
	v_bfe_u32 v170, v182, 4, 2
	v_bfe_u32 v171, v182, 6, 2
	v_lshrrev_b32_e32 v180, 8, v182
	v_lshl_add_u32 v181, v180, 6, v169
	v_and_b32_e32 v185, 1, v170
	v_lshrrev_b32_e32 v186, 1, v170
	v_lshlrev_b32_e32 v187, 11, v181
	v_lshl_add_u32 v187, v171, 6, v187
	v_lshl_add_u32 v187, v170, 3, v187
	v_lshlrev_b32_e32 v248, 7, v171
	v_lshl_add_u32 v248, v170, 4, v248
	v_lshlrev_b32_e32 v249, 11, v181
	v_lshl_add_u32 v249, v171, 6, v249
	v_lshl_add_u32 v249, v185, 5, v249
	v_lshl_add_u32 v249, v186, 4, v249
	s_lshl_b32 s54, s100, 2
	s_add_u32 s56, s8, s54
	s_addc_u32 s57, s9, 0
	s_lshl_b32 s54, s99, 11
	s_add_u32 s58, s10, s54
	s_addc_u32 s59, s11, 0
	s_lshl_b32 s54, s100, 1
	s_add_u32 s58, s58, s54
	s_addc_u32 s59, s59, 0
	s_lshl_b32 s54, s99, 11
	s_add_u32 s60, s12, s54
	s_addc_u32 s61, s13, 0
	s_lshl_b32 s54, s100, 1
	s_add_u32 s60, s60, s54
	s_addc_u32 s61, s61, 0
	s_lshl_b32 s54, s99, 11
	s_add_u32 s62, s14, s54
	s_addc_u32 s63, s15, 0
	s_lshl_b32 s54, s100, 1
	s_add_u32 s62, s62, s54
	s_addc_u32 s63, s63, 0
	global_load_dwordx4 v[172:175], v248, s[56:57]
	global_load_dwordx4 v[176:179], v248, s[56:57] offset:64
	global_load_dwordx4 v[188:191], v248, s[56:57] offset:512
	global_load_dwordx4 v[192:195], v248, s[56:57] offset:576
	global_load_dwordx2 v[204:205], v187, s[58:59]
	global_load_dwordx2 v[206:207], v187, s[60:61]
	global_load_dwordx2 v[208:209], v187, s[58:59] offset:32
	global_load_dwordx2 v[210:211], v187, s[60:61] offset:32
	global_load_dwordx2 v[212:213], v187, s[58:59] offset:256
	global_load_dwordx2 v[214:215], v187, s[60:61] offset:256
	global_load_dwordx2 v[216:217], v187, s[58:59] offset:288
	global_load_dwordx2 v[218:219], v187, s[60:61] offset:288
	s_add_u32 s58, s58, 0x8000
	s_addc_u32 s59, s59, 0
	s_add_u32 s60, s60, 0x8000
	s_addc_u32 s61, s61, 0
	global_load_dwordx2 v[220:221], v187, s[58:59]
	global_load_dwordx2 v[222:223], v187, s[60:61]
	global_load_dwordx2 v[224:225], v187, s[58:59] offset:32
	global_load_dwordx2 v[226:227], v187, s[60:61] offset:32
	global_load_dwordx2 v[240:241], v187, s[58:59] offset:256
	global_load_dwordx2 v[242:243], v187, s[60:61] offset:256
	global_load_dwordx2 v[244:245], v187, s[58:59] offset:288
	global_load_dwordx2 v[246:247], v187, s[60:61] offset:288
	s_waitcnt vmcnt(8)
	v_pk_add_f32 v[236:237], v[236:237], v[172:173]
	v_pk_add_f32 v[238:239], v[238:239], v[174:175]
	v_mul_f32_e32 v236, 0xbfb8aa3b, v236
	v_mul_f32_e32 v237, 0xbfb8aa3b, v237
	v_mul_f32_e32 v238, 0xbfb8aa3b, v238
	v_mul_f32_e32 v239, 0xbfb8aa3b, v239
	v_exp_f32_e32 v236, v236
	v_exp_f32_e32 v237, v237
	v_exp_f32_e32 v238, v238
	v_exp_f32_e32 v239, v239
	v_lshlrev_b32_e32 v196, 16, v204
	v_and_b32_e32 v197, 0xffff0000, v204
	v_lshlrev_b32_e32 v198, 16, v205
	v_and_b32_e32 v199, 0xffff0000, v205
	v_lshlrev_b32_e32 v200, 16, v206
	v_and_b32_e32 v201, 0xffff0000, v206
	v_lshlrev_b32_e32 v202, 16, v207
	v_and_b32_e32 v203, 0xffff0000, v207
	v_add_f32_e32 v236, 1.0, v236
	v_add_f32_e32 v237, 1.0, v237
	v_add_f32_e32 v238, 1.0, v238
	v_add_f32_e32 v239, 1.0, v239
	v_rcp_f32_e32 v236, v236
	v_rcp_f32_e32 v237, v237
	v_rcp_f32_e32 v238, v238
	v_rcp_f32_e32 v239, v239
	v_mul_f32_e32 v204, 0xbfb8aa3b, v200
	v_mul_f32_e32 v205, 0xbfb8aa3b, v201
	v_mul_f32_e32 v206, 0xbfb8aa3b, v202
	v_mul_f32_e32 v207, 0xbfb8aa3b, v203
	v_exp_f32_e32 v204, v204
	v_exp_f32_e32 v205, v205
	v_exp_f32_e32 v206, v206
	v_exp_f32_e32 v207, v207
	v_pk_mul_f32 v[196:197], v[236:237], v[196:197]
	v_pk_mul_f32 v[198:199], v[238:239], v[198:199]
	v_add_f32_e32 v204, 1.0, v204
	v_add_f32_e32 v205, 1.0, v205
	v_add_f32_e32 v206, 1.0, v206
	v_add_f32_e32 v207, 1.0, v207
	v_rcp_f32_e32 v204, v204
	v_rcp_f32_e32 v205, v205
	v_rcp_f32_e32 v206, v206
	v_rcp_f32_e32 v207, v207
	v_pk_mul_f32 v[200:201], v[204:205], v[200:201]
	v_pk_mul_f32 v[202:203], v[206:207], v[202:203]
	v_pk_mul_f32 v[236:237], v[200:201], v[196:197]
	v_pk_mul_f32 v[238:239], v[202:203], v[198:199]
	v_pk_add_f32 v[232:233], v[232:233], v[176:177]
	v_pk_add_f32 v[234:235], v[234:235], v[178:179]
	v_mul_f32_e32 v232, 0xbfb8aa3b, v232
	v_mul_f32_e32 v233, 0xbfb8aa3b, v233
	v_mul_f32_e32 v234, 0xbfb8aa3b, v234
	v_mul_f32_e32 v235, 0xbfb8aa3b, v235
	v_exp_f32_e32 v232, v232
	v_exp_f32_e32 v233, v233
	v_exp_f32_e32 v234, v234
	v_exp_f32_e32 v235, v235
	v_lshlrev_b32_e32 v196, 16, v208
	v_and_b32_e32 v197, 0xffff0000, v208
	v_lshlrev_b32_e32 v198, 16, v209
	v_and_b32_e32 v199, 0xffff0000, v209
	v_lshlrev_b32_e32 v200, 16, v210
	v_and_b32_e32 v201, 0xffff0000, v210
	v_lshlrev_b32_e32 v202, 16, v211
	v_and_b32_e32 v203, 0xffff0000, v211
	v_add_f32_e32 v232, 1.0, v232
	v_add_f32_e32 v233, 1.0, v233
	v_add_f32_e32 v234, 1.0, v234
	v_add_f32_e32 v235, 1.0, v235
	v_rcp_f32_e32 v232, v232
	v_rcp_f32_e32 v233, v233
	v_rcp_f32_e32 v234, v234
	v_rcp_f32_e32 v235, v235
	v_mul_f32_e32 v208, 0xbfb8aa3b, v200
	v_mul_f32_e32 v209, 0xbfb8aa3b, v201
	v_mul_f32_e32 v210, 0xbfb8aa3b, v202
	v_mul_f32_e32 v211, 0xbfb8aa3b, v203
	v_exp_f32_e32 v208, v208
	v_exp_f32_e32 v209, v209
	v_exp_f32_e32 v210, v210
	v_exp_f32_e32 v211, v211
	v_pk_mul_f32 v[196:197], v[232:233], v[196:197]
	v_pk_mul_f32 v[198:199], v[234:235], v[198:199]
	v_add_f32_e32 v208, 1.0, v208
	v_add_f32_e32 v209, 1.0, v209
	v_add_f32_e32 v210, 1.0, v210
	v_add_f32_e32 v211, 1.0, v211
	v_rcp_f32_e32 v208, v208
	v_rcp_f32_e32 v209, v209
	v_rcp_f32_e32 v210, v210
	v_rcp_f32_e32 v211, v211
	v_pk_mul_f32 v[200:201], v[208:209], v[200:201]
	v_pk_mul_f32 v[202:203], v[210:211], v[202:203]
	v_pk_mul_f32 v[232:233], v[200:201], v[196:197]
	v_pk_mul_f32 v[234:235], v[202:203], v[198:199]
	v_pk_add_f32 v[228:229], v[228:229], v[188:189]
; DI float sigmoidf_(float x) { return __builtin_amdgcn_rcpf(1.0f + __expf(-x)); }
; DI float siluf_(float x) { return x * sigmoidf_(x); }
; template <class FL, class FS>
; DI void gemm8_tile(char* shmc, const bf16_t* __restrict__ A, const bf16_t* __restrict__ Bt, const int K, const int brow, const int bcol, FL fl, FS fs) {
;     ...
; #pragma unroll
;   for (int ai = 0; ai < 2; ++ai)
; #pragma unroll
;     for (int mh = 0; mh < 2; ++mh) {
;       decltype(fl(0, 0)) ld[2][2][2];
; #pragma unroll
;       for (int mm = 0; mm < 2; ++mm)
; #pragma unroll
;         for (int bj = 0; bj < 2; ++bj)
; #pragma unroll
;           for (int n = 0; n < 2; ++n) ld[mm][bj][n] = fl(brow + ai * HALF + wr * 64 + (2 * mh + mm) * 16 + fr, bcol + bj * HALF + wc * 32 + n * 16 + 4 * fq);
; #pragma unroll
;       for (int mm = 0; mm < 2; ++mm)
; #pragma unroll
;         for (int bj = 0; bj < 2; ++bj)
; #pragma unroll
;           for (int n = 0; n < 2; ++n) fs(brow + ai * HALF + wr * 64 + (2 * mh + mm) * 16 + fr, bcol + bj * HALF + wc * 32 + n * 16 + 4 * fq, acc[ai][bj][2 * mh + mm][n], ld[mm][bj][n]);
; DI void phase_g2(const Params& p, const Sub& s, char* lds_all) {
;     ...
;       [&](int row, int col) { const size_t o = (size_t)row * D + col; Ld2 r; const uint2 a = *(const uint2*)(A + o), b = *(const uint2*)(z + o);
;         r.a.x = __uint_as_float(a.x); r.a.y = __uint_as_float(a.y); r.a.z = __uint_as_float(b.x); r.a.w = __uint_as_float(b.y); r.b = *(const float4*)(p.s5_b_glu + col); return r; },
;       [&](int row, int col, f32x4 v, const Ld2& l2) {
;         uint4 ld; ld.x = __float_as_uint(l2.a.x); ld.y = __float_as_uint(l2.a.y); ld.z = __float_as_uint(l2.a.z); ld.w = __float_as_uint(l2.a.w);
;         const size_t o = (size_t)row * D + col;
;         const float y0 = __uint_as_float(ld.x << 16), y1 = __uint_as_float(ld.x & 0xffff0000u), y2_ = __uint_as_float(ld.y << 16), y3 = __uint_as_float(ld.y & 0xffff0000u);
;         const float z0 = __uint_as_float(ld.z << 16), z1 = __uint_as_float(ld.z & 0xffff0000u), z2 = __uint_as_float(ld.w << 16), z3 = __uint_as_float(ld.w & 0xffff0000u);
;         const float4 b4 = l2.b;
;         st_bf4(y2 + o, y0 * sigmoidf_(v[0] + b4.x) * siluf_(z0), y1 * sigmoidf_(v[1] + b4.y) * siluf_(z1),
;                y2_ * sigmoidf_(v[2] + b4.z) * siluf_(z2), y3 * sigmoidf_(v[3] + b4.w) * siluf_(z3));
	v_pk_add_f32 v[230:231], v[230:231], v[190:191]
	v_mul_f32_e32 v228, 0xbfb8aa3b, v228
	v_mul_f32_e32 v229, 0xbfb8aa3b, v229
	v_mul_f32_e32 v230, 0xbfb8aa3b, v230
	v_mul_f32_e32 v231, 0xbfb8aa3b, v231
	v_exp_f32_e32 v228, v228
	v_exp_f32_e32 v229, v229
	v_exp_f32_e32 v230, v230
	v_exp_f32_e32 v231, v231
	v_lshlrev_b32_e32 v196, 16, v212
	v_and_b32_e32 v197, 0xffff0000, v212
	v_lshlrev_b32_e32 v198, 16, v213
	v_and_b32_e32 v199, 0xffff0000, v213
	v_lshlrev_b32_e32 v200, 16, v214
	v_and_b32_e32 v201, 0xffff0000, v214
	v_lshlrev_b32_e32 v202, 16, v215
	v_and_b32_e32 v203, 0xffff0000, v215
	v_add_f32_e32 v228, 1.0, v228
	v_add_f32_e32 v229, 1.0, v229
	v_add_f32_e32 v230, 1.0, v230
	v_add_f32_e32 v231, 1.0, v231
	v_rcp_f32_e32 v228, v228
	v_rcp_f32_e32 v229, v229
	v_rcp_f32_e32 v230, v230
	v_rcp_f32_e32 v231, v231
	v_mul_f32_e32 v212, 0xbfb8aa3b, v200
	v_mul_f32_e32 v213, 0xbfb8aa3b, v201
	v_mul_f32_e32 v214, 0xbfb8aa3b, v202
	v_mul_f32_e32 v215, 0xbfb8aa3b, v203
	v_exp_f32_e32 v212, v212
	v_exp_f32_e32 v213, v213
	v_exp_f32_e32 v214, v214
	v_exp_f32_e32 v215, v215
	v_pk_mul_f32 v[196:197], v[228:229], v[196:197]
	v_pk_mul_f32 v[198:199], v[230:231], v[198:199]
	v_add_f32_e32 v212, 1.0, v212
	v_add_f32_e32 v213, 1.0, v213
	v_add_f32_e32 v214, 1.0, v214
	v_add_f32_e32 v215, 1.0, v215
	v_rcp_f32_e32 v212, v212
	v_rcp_f32_e32 v213, v213
	v_rcp_f32_e32 v214, v214
	v_rcp_f32_e32 v215, v215
	v_pk_mul_f32 v[200:201], v[212:213], v[200:201]
	v_pk_mul_f32 v[202:203], v[214:215], v[202:203]
	v_pk_mul_f32 v[228:229], v[200:201], v[196:197]
	v_pk_mul_f32 v[230:231], v[202:203], v[198:199]
	v_pk_add_f32 v[120:121], v[120:121], v[192:193]
	v_pk_add_f32 v[122:123], v[122:123], v[194:195]
	v_mul_f32_e32 v120, 0xbfb8aa3b, v120
	v_mul_f32_e32 v121, 0xbfb8aa3b, v121
	v_mul_f32_e32 v122, 0xbfb8aa3b, v122
	v_mul_f32_e32 v123, 0xbfb8aa3b, v123
	v_exp_f32_e32 v120, v120
	v_exp_f32_e32 v121, v121
	v_exp_f32_e32 v122, v122
	v_exp_f32_e32 v123, v123
	v_lshlrev_b32_e32 v196, 16, v216
	v_and_b32_e32 v197, 0xffff0000, v216
	v_lshlrev_b32_e32 v198, 16, v217
	v_and_b32_e32 v199, 0xffff0000, v217
	v_lshlrev_b32_e32 v200, 16, v218
	v_and_b32_e32 v201, 0xffff0000, v218
	v_lshlrev_b32_e32 v202, 16, v219
	v_and_b32_e32 v203, 0xffff0000, v219
	v_add_f32_e32 v120, 1.0, v120
	v_add_f32_e32 v121, 1.0, v121
	v_add_f32_e32 v122, 1.0, v122
	v_add_f32_e32 v123, 1.0, v123
	v_rcp_f32_e32 v120, v120
	v_rcp_f32_e32 v121, v121
	v_rcp_f32_e32 v122, v122
	v_rcp_f32_e32 v123, v123
	v_mul_f32_e32 v216, 0xbfb8aa3b, v200
	v_mul_f32_e32 v217, 0xbfb8aa3b, v201
	v_mul_f32_e32 v218, 0xbfb8aa3b, v202
	v_mul_f32_e32 v219, 0xbfb8aa3b, v203
	v_exp_f32_e32 v216, v216
	v_exp_f32_e32 v217, v217
	v_exp_f32_e32 v218, v218
	v_exp_f32_e32 v219, v219
	v_pk_mul_f32 v[196:197], v[120:121], v[196:197]
	v_pk_mul_f32 v[198:199], v[122:123], v[198:199]
	v_add_f32_e32 v216, 1.0, v216
	v_add_f32_e32 v217, 1.0, v217
	v_add_f32_e32 v218, 1.0, v218
	v_add_f32_e32 v219, 1.0, v219
	v_rcp_f32_e32 v216, v216
	v_rcp_f32_e32 v217, v217
	v_rcp_f32_e32 v218, v218
	v_rcp_f32_e32 v219, v219
	v_pk_mul_f32 v[200:201], v[216:217], v[200:201]
	v_pk_mul_f32 v[202:203], v[218:219], v[202:203]
	v_pk_mul_f32 v[120:121], v[200:201], v[196:197]
	v_pk_mul_f32 v[122:123], v[202:203], v[198:199]
	v_cvt_pk_bf16_f32 v236, v236, v237
	v_cvt_pk_bf16_f32 v237, v238, v239
	v_cvt_pk_bf16_f32 v238, v232, v233
	v_cvt_pk_bf16_f32 v239, v234, v235
	v_cvt_pk_bf16_f32 v228, v228, v229
	v_cvt_pk_bf16_f32 v229, v230, v231
	v_cvt_pk_bf16_f32 v230, v120, v121
	v_cvt_pk_bf16_f32 v231, v122, v123
	v_permlane16_swap_b32_e32 v236, v238
	v_permlane16_swap_b32_e32 v237, v239
	global_store_dwordx4 v249, v[236:239], s[62:63]
	v_permlane16_swap_b32_e32 v228, v230
	v_permlane16_swap_b32_e32 v229, v231
	global_store_dwordx4 v249, v[228:231], s[62:63] offset:256
	s_add_u32 s58, s58, 0x8000
	s_addc_u32 s59, s59, 0
	s_add_u32 s60, s60, 0x8000
	s_addc_u32 s61, s61, 0
	global_load_dwordx2 v[204:205], v187, s[58:59]
	global_load_dwordx2 v[206:207], v187, s[60:61]
	global_load_dwordx2 v[208:209], v187, s[58:59] offset:32
	global_load_dwordx2 v[210:211], v187, s[60:61] offset:32
	global_load_dwordx2 v[212:213], v187, s[58:59] offset:256
	global_load_dwordx2 v[214:215], v187, s[60:61] offset:256
	global_load_dwordx2 v[216:217], v187, s[58:59] offset:288
	global_load_dwordx2 v[218:219], v187, s[60:61] offset:288
	s_waitcnt vmcnt(10)
; DI float sigmoidf_(float x) { return __builtin_amdgcn_rcpf(1.0f + __expf(-x)); }
; DI float siluf_(float x) { return x * sigmoidf_(x); }
; template <class FL, class FS>
; DI void gemm8_tile(char* shmc, const bf16_t* __restrict__ A, const bf16_t* __restrict__ Bt, const int K, const int brow, const int bcol, FL fl, FS fs) {
;     ...
; #pragma unroll
;   for (int ai = 0; ai < 2; ++ai)
; #pragma unroll
;     for (int mh = 0; mh < 2; ++mh) {
;       decltype(fl(0, 0)) ld[2][2][2];
; #pragma unroll
;       for (int mm = 0; mm < 2; ++mm)
; #pragma unroll
;         for (int bj = 0; bj < 2; ++bj)
; #pragma unroll
;           for (int n = 0; n < 2; ++n) ld[mm][bj][n] = fl(brow + ai * HALF + wr * 64 + (2 * mh + mm) * 16 + fr, bcol + bj * HALF + wc * 32 + n * 16 + 4 * fq);
; #pragma unroll
;       for (int mm = 0; mm < 2; ++mm)
; #pragma unroll
;         for (int bj = 0; bj < 2; ++bj)
; #pragma unroll
;           for (int n = 0; n < 2; ++n) fs(brow + ai * HALF + wr * 64 + (2 * mh + mm) * 16 + fr, bcol + bj * HALF + wc * 32 + n * 16 + 4 * fq, acc[ai][bj][2 * mh + mm][n], ld[mm][bj][n]);
; DI void phase_g2(const Params& p, const Sub& s, char* lds_all) {
;     ...
;       [&](int row, int col) { const size_t o = (size_t)row * D + col; Ld2 r; const uint2 a = *(const uint2*)(A + o), b = *(const uint2*)(z + o);
;         r.a.x = __uint_as_float(a.x); r.a.y = __uint_as_float(a.y); r.a.z = __uint_as_float(b.x); r.a.w = __uint_as_float(b.y); r.b = *(const float4*)(p.s5_b_glu + col); return r; },
;       [&](int row, int col, f32x4 v, const Ld2& l2) {
;         uint4 ld; ld.x = __float_as_uint(l2.a.x); ld.y = __float_as_uint(l2.a.y); ld.z = __float_as_uint(l2.a.z); ld.w = __float_as_uint(l2.a.w);
;         const size_t o = (size_t)row * D + col;
;         const float y0 = __uint_as_float(ld.x << 16), y1 = __uint_as_float(ld.x & 0xffff0000u), y2_ = __uint_as_float(ld.y << 16), y3 = __uint_as_float(ld.y & 0xffff0000u);
;         const float z0 = __uint_as_float(ld.z << 16), z1 = __uint_as_float(ld.z & 0xffff0000u), z2 = __uint_as_float(ld.w << 16), z3 = __uint_as_float(ld.w & 0xffff0000u);
;         const float4 b4 = l2.b;
;         st_bf4(y2 + o, y0 * sigmoidf_(v[0] + b4.x) * siluf_(z0), y1 * sigmoidf_(v[1] + b4.y) * siluf_(z1),
;                y2_ * sigmoidf_(v[2] + b4.z) * siluf_(z2), y3 * sigmoidf_(v[3] + b4.w) * siluf_(z3));
	v_pk_add_f32 v[112:113], v[112:113], v[172:173]
	v_pk_add_f32 v[114:115], v[114:115], v[174:175]
	v_mul_f32_e32 v112, 0xbfb8aa3b, v112
	v_mul_f32_e32 v113, 0xbfb8aa3b, v113
	v_mul_f32_e32 v114, 0xbfb8aa3b, v114
	v_mul_f32_e32 v115, 0xbfb8aa3b, v115
	v_exp_f32_e32 v112, v112
	v_exp_f32_e32 v113, v113
	v_exp_f32_e32 v114, v114
	v_exp_f32_e32 v115, v115
	v_lshlrev_b32_e32 v196, 16, v220
	v_and_b32_e32 v197, 0xffff0000, v220
	v_lshlrev_b32_e32 v198, 16, v221
	v_and_b32_e32 v199, 0xffff0000, v221
	v_lshlrev_b32_e32 v200, 16, v222
	v_and_b32_e32 v201, 0xffff0000, v222
	v_lshlrev_b32_e32 v202, 16, v223
	v_and_b32_e32 v203, 0xffff0000, v223
	v_add_f32_e32 v112, 1.0, v112
	v_add_f32_e32 v113, 1.0, v113
	v_add_f32_e32 v114, 1.0, v114
	v_add_f32_e32 v115, 1.0, v115
	v_rcp_f32_e32 v112, v112
	v_rcp_f32_e32 v113, v113
	v_rcp_f32_e32 v114, v114
	v_rcp_f32_e32 v115, v115
	v_mul_f32_e32 v220, 0xbfb8aa3b, v200
	v_mul_f32_e32 v221, 0xbfb8aa3b, v201
	v_mul_f32_e32 v222, 0xbfb8aa3b, v202
	v_mul_f32_e32 v223, 0xbfb8aa3b, v203
	v_exp_f32_e32 v220, v220
	v_exp_f32_e32 v221, v221
	v_exp_f32_e32 v222, v222
	v_exp_f32_e32 v223, v223
	v_pk_mul_f32 v[196:197], v[112:113], v[196:197]
	v_pk_mul_f32 v[198:199], v[114:115], v[198:199]
	v_add_f32_e32 v220, 1.0, v220
	v_add_f32_e32 v221, 1.0, v221
	v_add_f32_e32 v222, 1.0, v222
	v_add_f32_e32 v223, 1.0, v223
	v_rcp_f32_e32 v220, v220
	v_rcp_f32_e32 v221, v221
	v_rcp_f32_e32 v222, v222
	v_rcp_f32_e32 v223, v223
	v_pk_mul_f32 v[200:201], v[220:221], v[200:201]
	v_pk_mul_f32 v[202:203], v[222:223], v[202:203]
	v_pk_mul_f32 v[112:113], v[200:201], v[196:197]
	v_pk_mul_f32 v[114:115], v[202:203], v[198:199]
	v_pk_add_f32 v[104:105], v[104:105], v[176:177]
	v_pk_add_f32 v[106:107], v[106:107], v[178:179]
	v_mul_f32_e32 v104, 0xbfb8aa3b, v104
	v_mul_f32_e32 v105, 0xbfb8aa3b, v105
	v_mul_f32_e32 v106, 0xbfb8aa3b, v106
	v_mul_f32_e32 v107, 0xbfb8aa3b, v107
	v_exp_f32_e32 v104, v104
	v_exp_f32_e32 v105, v105
	v_exp_f32_e32 v106, v106
	v_exp_f32_e32 v107, v107
	v_lshlrev_b32_e32 v196, 16, v224
	v_and_b32_e32 v197, 0xffff0000, v224
	v_lshlrev_b32_e32 v198, 16, v225
	v_and_b32_e32 v199, 0xffff0000, v225
	v_lshlrev_b32_e32 v200, 16, v226
	v_and_b32_e32 v201, 0xffff0000, v226
	v_lshlrev_b32_e32 v202, 16, v227
	v_and_b32_e32 v203, 0xffff0000, v227
	v_add_f32_e32 v104, 1.0, v104
	v_add_f32_e32 v105, 1.0, v105
	v_add_f32_e32 v106, 1.0, v106
	v_add_f32_e32 v107, 1.0, v107
	v_rcp_f32_e32 v104, v104
	v_rcp_f32_e32 v105, v105
	v_rcp_f32_e32 v106, v106
	v_rcp_f32_e32 v107, v107
	v_mul_f32_e32 v224, 0xbfb8aa3b, v200
	v_mul_f32_e32 v225, 0xbfb8aa3b, v201
	v_mul_f32_e32 v226, 0xbfb8aa3b, v202
	v_mul_f32_e32 v227, 0xbfb8aa3b, v203
	v_exp_f32_e32 v224, v224
	v_exp_f32_e32 v225, v225
	v_exp_f32_e32 v226, v226
	v_exp_f32_e32 v227, v227
	v_pk_mul_f32 v[196:197], v[104:105], v[196:197]
	v_pk_mul_f32 v[198:199], v[106:107], v[198:199]
	v_add_f32_e32 v224, 1.0, v224
	v_add_f32_e32 v225, 1.0, v225
	v_add_f32_e32 v226, 1.0, v226
	v_add_f32_e32 v227, 1.0, v227
	v_rcp_f32_e32 v224, v224
	v_rcp_f32_e32 v225, v225
	v_rcp_f32_e32 v226, v226
	v_rcp_f32_e32 v227, v227
	v_pk_mul_f32 v[200:201], v[224:225], v[200:201]
	v_pk_mul_f32 v[202:203], v[226:227], v[202:203]
	v_pk_mul_f32 v[104:105], v[200:201], v[196:197]
	v_pk_mul_f32 v[106:107], v[202:203], v[198:199]
	v_pk_add_f32 v[100:101], v[100:101], v[188:189]
	v_pk_add_f32 v[102:103], v[102:103], v[190:191]
	v_mul_f32_e32 v100, 0xbfb8aa3b, v100
	v_mul_f32_e32 v101, 0xbfb8aa3b, v101
	v_mul_f32_e32 v102, 0xbfb8aa3b, v102
	v_mul_f32_e32 v103, 0xbfb8aa3b, v103
	v_exp_f32_e32 v100, v100
	v_exp_f32_e32 v101, v101
	v_exp_f32_e32 v102, v102
	v_exp_f32_e32 v103, v103
	v_lshlrev_b32_e32 v196, 16, v240
	v_and_b32_e32 v197, 0xffff0000, v240
	v_lshlrev_b32_e32 v198, 16, v241
	v_and_b32_e32 v199, 0xffff0000, v241
	v_lshlrev_b32_e32 v200, 16, v242
	v_and_b32_e32 v201, 0xffff0000, v242
	v_lshlrev_b32_e32 v202, 16, v243
	v_and_b32_e32 v203, 0xffff0000, v243
	v_add_f32_e32 v100, 1.0, v100
	v_add_f32_e32 v101, 1.0, v101
	v_add_f32_e32 v102, 1.0, v102
	v_add_f32_e32 v103, 1.0, v103
	v_rcp_f32_e32 v100, v100
	v_rcp_f32_e32 v101, v101
	v_rcp_f32_e32 v102, v102
	v_rcp_f32_e32 v103, v103
	v_mul_f32_e32 v240, 0xbfb8aa3b, v200
	v_mul_f32_e32 v241, 0xbfb8aa3b, v201
	v_mul_f32_e32 v242, 0xbfb8aa3b, v202
	v_mul_f32_e32 v243, 0xbfb8aa3b, v203
	v_exp_f32_e32 v240, v240
	v_exp_f32_e32 v241, v241
	v_exp_f32_e32 v242, v242
	v_exp_f32_e32 v243, v243
	v_pk_mul_f32 v[196:197], v[100:101], v[196:197]
	v_pk_mul_f32 v[198:199], v[102:103], v[198:199]
	v_add_f32_e32 v240, 1.0, v240
	v_add_f32_e32 v241, 1.0, v241
	v_add_f32_e32 v242, 1.0, v242
	v_add_f32_e32 v243, 1.0, v243
	v_rcp_f32_e32 v240, v240
	v_rcp_f32_e32 v241, v241
	v_rcp_f32_e32 v242, v242
	v_rcp_f32_e32 v243, v243
	v_pk_mul_f32 v[200:201], v[240:241], v[200:201]
	v_pk_mul_f32 v[202:203], v[242:243], v[202:203]
	v_pk_mul_f32 v[100:101], v[200:201], v[196:197]
	v_pk_mul_f32 v[102:103], v[202:203], v[198:199]
	v_pk_add_f32 v[96:97], v[96:97], v[192:193]
	v_pk_add_f32 v[98:99], v[98:99], v[194:195]
	v_mul_f32_e32 v96, 0xbfb8aa3b, v96
	v_mul_f32_e32 v97, 0xbfb8aa3b, v97
	v_mul_f32_e32 v98, 0xbfb8aa3b, v98
	v_mul_f32_e32 v99, 0xbfb8aa3b, v99
	v_exp_f32_e32 v96, v96
	v_exp_f32_e32 v97, v97
	v_exp_f32_e32 v98, v98
	v_exp_f32_e32 v99, v99
	v_lshlrev_b32_e32 v196, 16, v244
	v_and_b32_e32 v197, 0xffff0000, v244
	v_lshlrev_b32_e32 v198, 16, v245
	v_and_b32_e32 v199, 0xffff0000, v245
	v_lshlrev_b32_e32 v200, 16, v246
	v_and_b32_e32 v201, 0xffff0000, v246
	v_lshlrev_b32_e32 v202, 16, v247
	v_and_b32_e32 v203, 0xffff0000, v247
	v_add_f32_e32 v96, 1.0, v96
	v_add_f32_e32 v97, 1.0, v97
	v_add_f32_e32 v98, 1.0, v98
; DI float sigmoidf_(float x) { return __builtin_amdgcn_rcpf(1.0f + __expf(-x)); }
; DI float siluf_(float x) { return x * sigmoidf_(x); }
; template <class FL, class FS>
; DI void gemm8_tile(char* shmc, const bf16_t* __restrict__ A, const bf16_t* __restrict__ Bt, const int K, const int brow, const int bcol, FL fl, FS fs) {
;     ...
; #pragma unroll
;   for (int ai = 0; ai < 2; ++ai)
; #pragma unroll
;     for (int mh = 0; mh < 2; ++mh) {
;       decltype(fl(0, 0)) ld[2][2][2];
; #pragma unroll
;       for (int mm = 0; mm < 2; ++mm)
; #pragma unroll
;         for (int bj = 0; bj < 2; ++bj)
; #pragma unroll
;           for (int n = 0; n < 2; ++n) ld[mm][bj][n] = fl(brow + ai * HALF + wr * 64 + (2 * mh + mm) * 16 + fr, bcol + bj * HALF + wc * 32 + n * 16 + 4 * fq);
; #pragma unroll
;       for (int mm = 0; mm < 2; ++mm)
; #pragma unroll
;         for (int bj = 0; bj < 2; ++bj)
; #pragma unroll
;           for (int n = 0; n < 2; ++n) fs(brow + ai * HALF + wr * 64 + (2 * mh + mm) * 16 + fr, bcol + bj * HALF + wc * 32 + n * 16 + 4 * fq, acc[ai][bj][2 * mh + mm][n], ld[mm][bj][n]);
; DI void phase_g2(const Params& p, const Sub& s, char* lds_all) {
;     ...
;       [&](int row, int col) { const size_t o = (size_t)row * D + col; Ld2 r; const uint2 a = *(const uint2*)(A + o), b = *(const uint2*)(z + o);
;         r.a.x = __uint_as_float(a.x); r.a.y = __uint_as_float(a.y); r.a.z = __uint_as_float(b.x); r.a.w = __uint_as_float(b.y); r.b = *(const float4*)(p.s5_b_glu + col); return r; },
;       [&](int row, int col, f32x4 v, const Ld2& l2) {
;         uint4 ld; ld.x = __float_as_uint(l2.a.x); ld.y = __float_as_uint(l2.a.y); ld.z = __float_as_uint(l2.a.z); ld.w = __float_as_uint(l2.a.w);
;         const size_t o = (size_t)row * D + col;
;         const float y0 = __uint_as_float(ld.x << 16), y1 = __uint_as_float(ld.x & 0xffff0000u), y2_ = __uint_as_float(ld.y << 16), y3 = __uint_as_float(ld.y & 0xffff0000u);
;         const float z0 = __uint_as_float(ld.z << 16), z1 = __uint_as_float(ld.z & 0xffff0000u), z2 = __uint_as_float(ld.w << 16), z3 = __uint_as_float(ld.w & 0xffff0000u);
;         const float4 b4 = l2.b;
;         st_bf4(y2 + o, y0 * sigmoidf_(v[0] + b4.x) * siluf_(z0), y1 * sigmoidf_(v[1] + b4.y) * siluf_(z1),
;                y2_ * sigmoidf_(v[2] + b4.z) * siluf_(z2), y3 * sigmoidf_(v[3] + b4.w) * siluf_(z3));
	v_add_f32_e32 v99, 1.0, v99
	v_rcp_f32_e32 v96, v96
	v_rcp_f32_e32 v97, v97
	v_rcp_f32_e32 v98, v98
	v_rcp_f32_e32 v99, v99
	v_mul_f32_e32 v244, 0xbfb8aa3b, v200
	v_mul_f32_e32 v245, 0xbfb8aa3b, v201
	v_mul_f32_e32 v246, 0xbfb8aa3b, v202
	v_mul_f32_e32 v247, 0xbfb8aa3b, v203
	v_exp_f32_e32 v244, v244
	v_exp_f32_e32 v245, v245
	v_exp_f32_e32 v246, v246
	v_exp_f32_e32 v247, v247
	v_pk_mul_f32 v[196:197], v[96:97], v[196:197]
	v_pk_mul_f32 v[198:199], v[98:99], v[198:199]
	v_add_f32_e32 v244, 1.0, v244
	v_add_f32_e32 v245, 1.0, v245
	v_add_f32_e32 v246, 1.0, v246
	v_add_f32_e32 v247, 1.0, v247
	v_rcp_f32_e32 v244, v244
	v_rcp_f32_e32 v245, v245
	v_rcp_f32_e32 v246, v246
	v_rcp_f32_e32 v247, v247
	v_pk_mul_f32 v[200:201], v[244:245], v[200:201]
	v_pk_mul_f32 v[202:203], v[246:247], v[202:203]
	v_pk_mul_f32 v[96:97], v[200:201], v[196:197]
	v_pk_mul_f32 v[98:99], v[202:203], v[198:199]
	v_cvt_pk_bf16_f32 v112, v112, v113
	v_cvt_pk_bf16_f32 v113, v114, v115
	v_cvt_pk_bf16_f32 v114, v104, v105
	v_cvt_pk_bf16_f32 v115, v106, v107
	v_cvt_pk_bf16_f32 v100, v100, v101
	v_cvt_pk_bf16_f32 v101, v102, v103
	v_cvt_pk_bf16_f32 v102, v96, v97
	v_cvt_pk_bf16_f32 v103, v98, v99
	s_add_u32 s62, s62, 0x8000
	s_addc_u32 s63, s63, 0
	v_permlane16_swap_b32_e32 v112, v114
	v_permlane16_swap_b32_e32 v113, v115
	global_store_dwordx4 v249, v[112:115], s[62:63]
	v_permlane16_swap_b32_e32 v100, v102
	v_permlane16_swap_b32_e32 v101, v103
	global_store_dwordx4 v249, v[100:103], s[62:63] offset:256
	s_add_u32 s58, s58, 0x8000
	s_addc_u32 s59, s59, 0
	s_add_u32 s60, s60, 0x8000
	s_addc_u32 s61, s61, 0
	global_load_dwordx2 v[220:221], v187, s[58:59]
	global_load_dwordx2 v[222:223], v187, s[60:61]
	global_load_dwordx2 v[224:225], v187, s[58:59] offset:32
	global_load_dwordx2 v[226:227], v187, s[60:61] offset:32
	global_load_dwordx2 v[240:241], v187, s[58:59] offset:256
	global_load_dwordx2 v[242:243], v187, s[60:61] offset:256
	global_load_dwordx2 v[244:245], v187, s[58:59] offset:288
	global_load_dwordx2 v[246:247], v187, s[60:61] offset:288
	s_waitcnt vmcnt(10)
	v_pk_add_f32 v[92:93], v[92:93], v[172:173]
	v_pk_add_f32 v[94:95], v[94:95], v[174:175]
	v_mul_f32_e32 v92, 0xbfb8aa3b, v92
	v_mul_f32_e32 v93, 0xbfb8aa3b, v93
	v_mul_f32_e32 v94, 0xbfb8aa3b, v94
	v_mul_f32_e32 v95, 0xbfb8aa3b, v95
	v_exp_f32_e32 v92, v92
	v_exp_f32_e32 v93, v93
	v_exp_f32_e32 v94, v94
	v_exp_f32_e32 v95, v95
	v_lshlrev_b32_e32 v196, 16, v204
	v_and_b32_e32 v197, 0xffff0000, v204
	v_lshlrev_b32_e32 v198, 16, v205
	v_and_b32_e32 v199, 0xffff0000, v205
	v_lshlrev_b32_e32 v200, 16, v206
	v_and_b32_e32 v201, 0xffff0000, v206
	v_lshlrev_b32_e32 v202, 16, v207
	v_and_b32_e32 v203, 0xffff0000, v207
	v_add_f32_e32 v92, 1.0, v92
	v_add_f32_e32 v93, 1.0, v93
	v_add_f32_e32 v94, 1.0, v94
	v_add_f32_e32 v95, 1.0, v95
	v_rcp_f32_e32 v92, v92
	v_rcp_f32_e32 v93, v93
	v_rcp_f32_e32 v94, v94
	v_rcp_f32_e32 v95, v95
	v_mul_f32_e32 v204, 0xbfb8aa3b, v200
	v_mul_f32_e32 v205, 0xbfb8aa3b, v201
	v_mul_f32_e32 v206, 0xbfb8aa3b, v202
	v_mul_f32_e32 v207, 0xbfb8aa3b, v203
	v_exp_f32_e32 v204, v204
	v_exp_f32_e32 v205, v205
	v_exp_f32_e32 v206, v206
	v_exp_f32_e32 v207, v207
	v_pk_mul_f32 v[196:197], v[92:93], v[196:197]
	v_pk_mul_f32 v[198:199], v[94:95], v[198:199]
	v_add_f32_e32 v204, 1.0, v204
	v_add_f32_e32 v205, 1.0, v205
	v_add_f32_e32 v206, 1.0, v206
	v_add_f32_e32 v207, 1.0, v207
	v_rcp_f32_e32 v204, v204
	v_rcp_f32_e32 v205, v205
	v_rcp_f32_e32 v206, v206
	v_rcp_f32_e32 v207, v207
	v_pk_mul_f32 v[200:201], v[204:205], v[200:201]
	v_pk_mul_f32 v[202:203], v[206:207], v[202:203]
	v_pk_mul_f32 v[92:93], v[200:201], v[196:197]
	v_pk_mul_f32 v[94:95], v[202:203], v[198:199]
	v_pk_add_f32 v[88:89], v[88:89], v[176:177]
	v_pk_add_f32 v[90:91], v[90:91], v[178:179]
	v_mul_f32_e32 v88, 0xbfb8aa3b, v88
	v_mul_f32_e32 v89, 0xbfb8aa3b, v89
	v_mul_f32_e32 v90, 0xbfb8aa3b, v90
	v_mul_f32_e32 v91, 0xbfb8aa3b, v91
	v_exp_f32_e32 v88, v88
	v_exp_f32_e32 v89, v89
	v_exp_f32_e32 v90, v90
	v_exp_f32_e32 v91, v91
	v_lshlrev_b32_e32 v196, 16, v208
	v_and_b32_e32 v197, 0xffff0000, v208
	v_lshlrev_b32_e32 v198, 16, v209
	v_and_b32_e32 v199, 0xffff0000, v209
	v_lshlrev_b32_e32 v200, 16, v210
	v_and_b32_e32 v201, 0xffff0000, v210
	v_lshlrev_b32_e32 v202, 16, v211
	v_and_b32_e32 v203, 0xffff0000, v211
	v_add_f32_e32 v88, 1.0, v88
	v_add_f32_e32 v89, 1.0, v89
	v_add_f32_e32 v90, 1.0, v90
	v_add_f32_e32 v91, 1.0, v91
	v_rcp_f32_e32 v88, v88
	v_rcp_f32_e32 v89, v89
	v_rcp_f32_e32 v90, v90
	v_rcp_f32_e32 v91, v91
	v_mul_f32_e32 v208, 0xbfb8aa3b, v200
	v_mul_f32_e32 v209, 0xbfb8aa3b, v201
	v_mul_f32_e32 v210, 0xbfb8aa3b, v202
	v_mul_f32_e32 v211, 0xbfb8aa3b, v203
	v_exp_f32_e32 v208, v208
	v_exp_f32_e32 v209, v209
	v_exp_f32_e32 v210, v210
	v_exp_f32_e32 v211, v211
	v_pk_mul_f32 v[196:197], v[88:89], v[196:197]
	v_pk_mul_f32 v[198:199], v[90:91], v[198:199]
	v_add_f32_e32 v208, 1.0, v208
	v_add_f32_e32 v209, 1.0, v209
	v_add_f32_e32 v210, 1.0, v210
	v_add_f32_e32 v211, 1.0, v211
	v_rcp_f32_e32 v208, v208
	v_rcp_f32_e32 v209, v209
	v_rcp_f32_e32 v210, v210
	v_rcp_f32_e32 v211, v211
	v_pk_mul_f32 v[200:201], v[208:209], v[200:201]
	v_pk_mul_f32 v[202:203], v[210:211], v[202:203]
	v_pk_mul_f32 v[88:89], v[200:201], v[196:197]
	v_pk_mul_f32 v[90:91], v[202:203], v[198:199]
	v_pk_add_f32 v[84:85], v[84:85], v[188:189]
	v_pk_add_f32 v[86:87], v[86:87], v[190:191]
	v_mul_f32_e32 v84, 0xbfb8aa3b, v84
	v_mul_f32_e32 v85, 0xbfb8aa3b, v85
	v_mul_f32_e32 v86, 0xbfb8aa3b, v86
	v_mul_f32_e32 v87, 0xbfb8aa3b, v87
	v_exp_f32_e32 v84, v84
	v_exp_f32_e32 v85, v85
	v_exp_f32_e32 v86, v86
	v_exp_f32_e32 v87, v87
	v_lshlrev_b32_e32 v196, 16, v212
; DI float sigmoidf_(float x) { return __builtin_amdgcn_rcpf(1.0f + __expf(-x)); }
; DI float siluf_(float x) { return x * sigmoidf_(x); }
; template <class FL, class FS>
; DI void gemm8_tile(char* shmc, const bf16_t* __restrict__ A, const bf16_t* __restrict__ Bt, const int K, const int brow, const int bcol, FL fl, FS fs) {
;     ...
; #pragma unroll
;   for (int ai = 0; ai < 2; ++ai)
; #pragma unroll
;     for (int mh = 0; mh < 2; ++mh) {
;       decltype(fl(0, 0)) ld[2][2][2];
; #pragma unroll
;       for (int mm = 0; mm < 2; ++mm)
; #pragma unroll
;         for (int bj = 0; bj < 2; ++bj)
; #pragma unroll
;           for (int n = 0; n < 2; ++n) ld[mm][bj][n] = fl(brow + ai * HALF + wr * 64 + (2 * mh + mm) * 16 + fr, bcol + bj * HALF + wc * 32 + n * 16 + 4 * fq);
; #pragma unroll
;       for (int mm = 0; mm < 2; ++mm)
; #pragma unroll
;         for (int bj = 0; bj < 2; ++bj)
; #pragma unroll
;           for (int n = 0; n < 2; ++n) fs(brow + ai * HALF + wr * 64 + (2 * mh + mm) * 16 + fr, bcol + bj * HALF + wc * 32 + n * 16 + 4 * fq, acc[ai][bj][2 * mh + mm][n], ld[mm][bj][n]);
; DI void phase_g2(const Params& p, const Sub& s, char* lds_all) {
;     ...
;       [&](int row, int col) { const size_t o = (size_t)row * D + col; Ld2 r; const uint2 a = *(const uint2*)(A + o), b = *(const uint2*)(z + o);
;         r.a.x = __uint_as_float(a.x); r.a.y = __uint_as_float(a.y); r.a.z = __uint_as_float(b.x); r.a.w = __uint_as_float(b.y); r.b = *(const float4*)(p.s5_b_glu + col); return r; },
;       [&](int row, int col, f32x4 v, const Ld2& l2) {
;         uint4 ld; ld.x = __float_as_uint(l2.a.x); ld.y = __float_as_uint(l2.a.y); ld.z = __float_as_uint(l2.a.z); ld.w = __float_as_uint(l2.a.w);
;         const size_t o = (size_t)row * D + col;
;         const float y0 = __uint_as_float(ld.x << 16), y1 = __uint_as_float(ld.x & 0xffff0000u), y2_ = __uint_as_float(ld.y << 16), y3 = __uint_as_float(ld.y & 0xffff0000u);
;         const float z0 = __uint_as_float(ld.z << 16), z1 = __uint_as_float(ld.z & 0xffff0000u), z2 = __uint_as_float(ld.w << 16), z3 = __uint_as_float(ld.w & 0xffff0000u);
;         const float4 b4 = l2.b;
;         st_bf4(y2 + o, y0 * sigmoidf_(v[0] + b4.x) * siluf_(z0), y1 * sigmoidf_(v[1] + b4.y) * siluf_(z1),
;                y2_ * sigmoidf_(v[2] + b4.z) * siluf_(z2), y3 * sigmoidf_(v[3] + b4.w) * siluf_(z3));
	v_and_b32_e32 v197, 0xffff0000, v212
	v_lshlrev_b32_e32 v198, 16, v213
	v_and_b32_e32 v199, 0xffff0000, v213
	v_lshlrev_b32_e32 v200, 16, v214
	v_and_b32_e32 v201, 0xffff0000, v214
	v_lshlrev_b32_e32 v202, 16, v215
	v_and_b32_e32 v203, 0xffff0000, v215
	v_add_f32_e32 v84, 1.0, v84
	v_add_f32_e32 v85, 1.0, v85
	v_add_f32_e32 v86, 1.0, v86
	v_add_f32_e32 v87, 1.0, v87
	v_rcp_f32_e32 v84, v84
	v_rcp_f32_e32 v85, v85
	v_rcp_f32_e32 v86, v86
	v_rcp_f32_e32 v87, v87
	v_mul_f32_e32 v212, 0xbfb8aa3b, v200
	v_mul_f32_e32 v213, 0xbfb8aa3b, v201
	v_mul_f32_e32 v214, 0xbfb8aa3b, v202
	v_mul_f32_e32 v215, 0xbfb8aa3b, v203
	v_exp_f32_e32 v212, v212
	v_exp_f32_e32 v213, v213
	v_exp_f32_e32 v214, v214
	v_exp_f32_e32 v215, v215
	v_pk_mul_f32 v[196:197], v[84:85], v[196:197]
	v_pk_mul_f32 v[198:199], v[86:87], v[198:199]
	v_add_f32_e32 v212, 1.0, v212
	v_add_f32_e32 v213, 1.0, v213
	v_add_f32_e32 v214, 1.0, v214
	v_add_f32_e32 v215, 1.0, v215
	v_rcp_f32_e32 v212, v212
	v_rcp_f32_e32 v213, v213
	v_rcp_f32_e32 v214, v214
	v_rcp_f32_e32 v215, v215
	v_pk_mul_f32 v[200:201], v[212:213], v[200:201]
	v_pk_mul_f32 v[202:203], v[214:215], v[202:203]
	v_pk_mul_f32 v[84:85], v[200:201], v[196:197]
	v_pk_mul_f32 v[86:87], v[202:203], v[198:199]
	v_pk_add_f32 v[80:81], v[80:81], v[192:193]
	v_pk_add_f32 v[82:83], v[82:83], v[194:195]
	v_mul_f32_e32 v80, 0xbfb8aa3b, v80
	v_mul_f32_e32 v81, 0xbfb8aa3b, v81
	v_mul_f32_e32 v82, 0xbfb8aa3b, v82
	v_mul_f32_e32 v83, 0xbfb8aa3b, v83
	v_exp_f32_e32 v80, v80
	v_exp_f32_e32 v81, v81
	v_exp_f32_e32 v82, v82
	v_exp_f32_e32 v83, v83
	v_lshlrev_b32_e32 v196, 16, v216
	v_and_b32_e32 v197, 0xffff0000, v216
	v_lshlrev_b32_e32 v198, 16, v217
	v_and_b32_e32 v199, 0xffff0000, v217
	v_lshlrev_b32_e32 v200, 16, v218
	v_and_b32_e32 v201, 0xffff0000, v218
	v_lshlrev_b32_e32 v202, 16, v219
	v_and_b32_e32 v203, 0xffff0000, v219
	v_add_f32_e32 v80, 1.0, v80
	v_add_f32_e32 v81, 1.0, v81
	v_add_f32_e32 v82, 1.0, v82
	v_add_f32_e32 v83, 1.0, v83
	v_rcp_f32_e32 v80, v80
	v_rcp_f32_e32 v81, v81
	v_rcp_f32_e32 v82, v82
	v_rcp_f32_e32 v83, v83
	v_mul_f32_e32 v216, 0xbfb8aa3b, v200
	v_mul_f32_e32 v217, 0xbfb8aa3b, v201
	v_mul_f32_e32 v218, 0xbfb8aa3b, v202
	v_mul_f32_e32 v219, 0xbfb8aa3b, v203
	v_exp_f32_e32 v216, v216
	v_exp_f32_e32 v217, v217
	v_exp_f32_e32 v218, v218
	v_exp_f32_e32 v219, v219
	v_pk_mul_f32 v[196:197], v[80:81], v[196:197]
	v_pk_mul_f32 v[198:199], v[82:83], v[198:199]
	v_add_f32_e32 v216, 1.0, v216
	v_add_f32_e32 v217, 1.0, v217
	v_add_f32_e32 v218, 1.0, v218
	v_add_f32_e32 v219, 1.0, v219
	v_rcp_f32_e32 v216, v216
	v_rcp_f32_e32 v217, v217
	v_rcp_f32_e32 v218, v218
	v_rcp_f32_e32 v219, v219
	v_pk_mul_f32 v[200:201], v[216:217], v[200:201]
	v_pk_mul_f32 v[202:203], v[218:219], v[202:203]
	v_pk_mul_f32 v[80:81], v[200:201], v[196:197]
	v_pk_mul_f32 v[82:83], v[202:203], v[198:199]
	v_cvt_pk_bf16_f32 v92, v92, v93
	v_cvt_pk_bf16_f32 v93, v94, v95
	v_cvt_pk_bf16_f32 v94, v88, v89
	v_cvt_pk_bf16_f32 v95, v90, v91
	v_cvt_pk_bf16_f32 v84, v84, v85
	v_cvt_pk_bf16_f32 v85, v86, v87
	v_cvt_pk_bf16_f32 v86, v80, v81
	v_cvt_pk_bf16_f32 v87, v82, v83
	s_add_u32 s62, s62, 0x8000
	s_addc_u32 s63, s63, 0
	v_permlane16_swap_b32_e32 v92, v94
	v_permlane16_swap_b32_e32 v93, v95
	global_store_dwordx4 v249, v[92:95], s[62:63]
	v_permlane16_swap_b32_e32 v84, v86
	v_permlane16_swap_b32_e32 v85, v87
	global_store_dwordx4 v249, v[84:87], s[62:63] offset:256
	s_add_u32 s58, s58, 0x28000
	s_addc_u32 s59, s59, 0
	s_add_u32 s60, s60, 0x28000
	s_addc_u32 s61, s61, 0
	global_load_dwordx2 v[204:205], v187, s[58:59]
	global_load_dwordx2 v[206:207], v187, s[60:61]
	global_load_dwordx2 v[208:209], v187, s[58:59] offset:32
	global_load_dwordx2 v[210:211], v187, s[60:61] offset:32
	global_load_dwordx2 v[212:213], v187, s[58:59] offset:256
	global_load_dwordx2 v[214:215], v187, s[60:61] offset:256
	global_load_dwordx2 v[216:217], v187, s[58:59] offset:288
	global_load_dwordx2 v[218:219], v187, s[60:61] offset:288
	s_waitcnt vmcnt(10)
	v_pk_add_f32 v[76:77], v[76:77], v[172:173]
	v_pk_add_f32 v[78:79], v[78:79], v[174:175]
	v_mul_f32_e32 v76, 0xbfb8aa3b, v76
	v_mul_f32_e32 v77, 0xbfb8aa3b, v77
	v_mul_f32_e32 v78, 0xbfb8aa3b, v78
	v_mul_f32_e32 v79, 0xbfb8aa3b, v79
	v_exp_f32_e32 v76, v76
	v_exp_f32_e32 v77, v77
	v_exp_f32_e32 v78, v78
	v_exp_f32_e32 v79, v79
	v_lshlrev_b32_e32 v196, 16, v220
	v_and_b32_e32 v197, 0xffff0000, v220
	v_lshlrev_b32_e32 v198, 16, v221
	v_and_b32_e32 v199, 0xffff0000, v221
	v_lshlrev_b32_e32 v200, 16, v222
	v_and_b32_e32 v201, 0xffff0000, v222
	v_lshlrev_b32_e32 v202, 16, v223
	v_and_b32_e32 v203, 0xffff0000, v223
	v_add_f32_e32 v76, 1.0, v76
	v_add_f32_e32 v77, 1.0, v77
	v_add_f32_e32 v78, 1.0, v78
	v_add_f32_e32 v79, 1.0, v79
	v_rcp_f32_e32 v76, v76
	v_rcp_f32_e32 v77, v77
	v_rcp_f32_e32 v78, v78
	v_rcp_f32_e32 v79, v79
	v_mul_f32_e32 v220, 0xbfb8aa3b, v200
	v_mul_f32_e32 v221, 0xbfb8aa3b, v201
	v_mul_f32_e32 v222, 0xbfb8aa3b, v202
	v_mul_f32_e32 v223, 0xbfb8aa3b, v203
	v_exp_f32_e32 v220, v220
	v_exp_f32_e32 v221, v221
	v_exp_f32_e32 v222, v222
	v_exp_f32_e32 v223, v223
	v_pk_mul_f32 v[196:197], v[76:77], v[196:197]
	v_pk_mul_f32 v[198:199], v[78:79], v[198:199]
	v_add_f32_e32 v220, 1.0, v220
	v_add_f32_e32 v221, 1.0, v221
	v_add_f32_e32 v222, 1.0, v222
	v_add_f32_e32 v223, 1.0, v223
	v_rcp_f32_e32 v220, v220
	v_rcp_f32_e32 v221, v221
	v_rcp_f32_e32 v222, v222
	v_rcp_f32_e32 v223, v223
	v_pk_mul_f32 v[200:201], v[220:221], v[200:201]
	v_pk_mul_f32 v[202:203], v[222:223], v[202:203]
	v_pk_mul_f32 v[76:77], v[200:201], v[196:197]
	v_pk_mul_f32 v[78:79], v[202:203], v[198:199]
	v_pk_add_f32 v[72:73], v[72:73], v[176:177]
; DI float sigmoidf_(float x) { return __builtin_amdgcn_rcpf(1.0f + __expf(-x)); }
; DI float siluf_(float x) { return x * sigmoidf_(x); }
; template <class FL, class FS>
; DI void gemm8_tile(char* shmc, const bf16_t* __restrict__ A, const bf16_t* __restrict__ Bt, const int K, const int brow, const int bcol, FL fl, FS fs) {
;     ...
; #pragma unroll
;   for (int ai = 0; ai < 2; ++ai)
; #pragma unroll
;     for (int mh = 0; mh < 2; ++mh) {
;       decltype(fl(0, 0)) ld[2][2][2];
; #pragma unroll
;       for (int mm = 0; mm < 2; ++mm)
; #pragma unroll
;         for (int bj = 0; bj < 2; ++bj)
; #pragma unroll
;           for (int n = 0; n < 2; ++n) ld[mm][bj][n] = fl(brow + ai * HALF + wr * 64 + (2 * mh + mm) * 16 + fr, bcol + bj * HALF + wc * 32 + n * 16 + 4 * fq);
; #pragma unroll
;       for (int mm = 0; mm < 2; ++mm)
; #pragma unroll
;         for (int bj = 0; bj < 2; ++bj)
; #pragma unroll
;           for (int n = 0; n < 2; ++n) fs(brow + ai * HALF + wr * 64 + (2 * mh + mm) * 16 + fr, bcol + bj * HALF + wc * 32 + n * 16 + 4 * fq, acc[ai][bj][2 * mh + mm][n], ld[mm][bj][n]);
; DI void phase_g2(const Params& p, const Sub& s, char* lds_all) {
;     ...
;       [&](int row, int col) { const size_t o = (size_t)row * D + col; Ld2 r; const uint2 a = *(const uint2*)(A + o), b = *(const uint2*)(z + o);
;         r.a.x = __uint_as_float(a.x); r.a.y = __uint_as_float(a.y); r.a.z = __uint_as_float(b.x); r.a.w = __uint_as_float(b.y); r.b = *(const float4*)(p.s5_b_glu + col); return r; },
;       [&](int row, int col, f32x4 v, const Ld2& l2) {
;         uint4 ld; ld.x = __float_as_uint(l2.a.x); ld.y = __float_as_uint(l2.a.y); ld.z = __float_as_uint(l2.a.z); ld.w = __float_as_uint(l2.a.w);
;         const size_t o = (size_t)row * D + col;
;         const float y0 = __uint_as_float(ld.x << 16), y1 = __uint_as_float(ld.x & 0xffff0000u), y2_ = __uint_as_float(ld.y << 16), y3 = __uint_as_float(ld.y & 0xffff0000u);
;         const float z0 = __uint_as_float(ld.z << 16), z1 = __uint_as_float(ld.z & 0xffff0000u), z2 = __uint_as_float(ld.w << 16), z3 = __uint_as_float(ld.w & 0xffff0000u);
;         const float4 b4 = l2.b;
;         st_bf4(y2 + o, y0 * sigmoidf_(v[0] + b4.x) * siluf_(z0), y1 * sigmoidf_(v[1] + b4.y) * siluf_(z1),
;                y2_ * sigmoidf_(v[2] + b4.z) * siluf_(z2), y3 * sigmoidf_(v[3] + b4.w) * siluf_(z3));
	v_pk_add_f32 v[74:75], v[74:75], v[178:179]
	v_mul_f32_e32 v72, 0xbfb8aa3b, v72
	v_mul_f32_e32 v73, 0xbfb8aa3b, v73
	v_mul_f32_e32 v74, 0xbfb8aa3b, v74
	v_mul_f32_e32 v75, 0xbfb8aa3b, v75
	v_exp_f32_e32 v72, v72
	v_exp_f32_e32 v73, v73
	v_exp_f32_e32 v74, v74
	v_exp_f32_e32 v75, v75
	v_lshlrev_b32_e32 v196, 16, v224
	v_and_b32_e32 v197, 0xffff0000, v224
	v_lshlrev_b32_e32 v198, 16, v225
	v_and_b32_e32 v199, 0xffff0000, v225
	v_lshlrev_b32_e32 v200, 16, v226
	v_and_b32_e32 v201, 0xffff0000, v226
	v_lshlrev_b32_e32 v202, 16, v227
	v_and_b32_e32 v203, 0xffff0000, v227
	v_add_f32_e32 v72, 1.0, v72
	v_add_f32_e32 v73, 1.0, v73
	v_add_f32_e32 v74, 1.0, v74
	v_add_f32_e32 v75, 1.0, v75
	v_rcp_f32_e32 v72, v72
	v_rcp_f32_e32 v73, v73
	v_rcp_f32_e32 v74, v74
	v_rcp_f32_e32 v75, v75
	v_mul_f32_e32 v224, 0xbfb8aa3b, v200
	v_mul_f32_e32 v225, 0xbfb8aa3b, v201
	v_mul_f32_e32 v226, 0xbfb8aa3b, v202
	v_mul_f32_e32 v227, 0xbfb8aa3b, v203
	v_exp_f32_e32 v224, v224
	v_exp_f32_e32 v225, v225
	v_exp_f32_e32 v226, v226
	v_exp_f32_e32 v227, v227
	v_pk_mul_f32 v[196:197], v[72:73], v[196:197]
	v_pk_mul_f32 v[198:199], v[74:75], v[198:199]
	v_add_f32_e32 v224, 1.0, v224
	v_add_f32_e32 v225, 1.0, v225
	v_add_f32_e32 v226, 1.0, v226
	v_add_f32_e32 v227, 1.0, v227
	v_rcp_f32_e32 v224, v224
	v_rcp_f32_e32 v225, v225
	v_rcp_f32_e32 v226, v226
	v_rcp_f32_e32 v227, v227
	v_pk_mul_f32 v[200:201], v[224:225], v[200:201]
	v_pk_mul_f32 v[202:203], v[226:227], v[202:203]
	v_pk_mul_f32 v[72:73], v[200:201], v[196:197]
	v_pk_mul_f32 v[74:75], v[202:203], v[198:199]
	v_pk_add_f32 v[68:69], v[68:69], v[188:189]
	v_pk_add_f32 v[70:71], v[70:71], v[190:191]
	v_mul_f32_e32 v68, 0xbfb8aa3b, v68
	v_mul_f32_e32 v69, 0xbfb8aa3b, v69
	v_mul_f32_e32 v70, 0xbfb8aa3b, v70
	v_mul_f32_e32 v71, 0xbfb8aa3b, v71
	v_exp_f32_e32 v68, v68
	v_exp_f32_e32 v69, v69
	v_exp_f32_e32 v70, v70
	v_exp_f32_e32 v71, v71
	v_lshlrev_b32_e32 v196, 16, v240
	v_and_b32_e32 v197, 0xffff0000, v240
	v_lshlrev_b32_e32 v198, 16, v241
	v_and_b32_e32 v199, 0xffff0000, v241
	v_lshlrev_b32_e32 v200, 16, v242
	v_and_b32_e32 v201, 0xffff0000, v242
	v_lshlrev_b32_e32 v202, 16, v243
	v_and_b32_e32 v203, 0xffff0000, v243
	v_add_f32_e32 v68, 1.0, v68
	v_add_f32_e32 v69, 1.0, v69
	v_add_f32_e32 v70, 1.0, v70
	v_add_f32_e32 v71, 1.0, v71
	v_rcp_f32_e32 v68, v68
	v_rcp_f32_e32 v69, v69
	v_rcp_f32_e32 v70, v70
	v_rcp_f32_e32 v71, v71
	v_mul_f32_e32 v240, 0xbfb8aa3b, v200
	v_mul_f32_e32 v241, 0xbfb8aa3b, v201
	v_mul_f32_e32 v242, 0xbfb8aa3b, v202
	v_mul_f32_e32 v243, 0xbfb8aa3b, v203
	v_exp_f32_e32 v240, v240
	v_exp_f32_e32 v241, v241
	v_exp_f32_e32 v242, v242
	v_exp_f32_e32 v243, v243
	v_pk_mul_f32 v[196:197], v[68:69], v[196:197]
	v_pk_mul_f32 v[198:199], v[70:71], v[198:199]
	v_add_f32_e32 v240, 1.0, v240
	v_add_f32_e32 v241, 1.0, v241
	v_add_f32_e32 v242, 1.0, v242
	v_add_f32_e32 v243, 1.0, v243
	v_rcp_f32_e32 v240, v240
	v_rcp_f32_e32 v241, v241
	v_rcp_f32_e32 v242, v242
	v_rcp_f32_e32 v243, v243
	v_pk_mul_f32 v[200:201], v[240:241], v[200:201]
	v_pk_mul_f32 v[202:203], v[242:243], v[202:203]
	v_pk_mul_f32 v[68:69], v[200:201], v[196:197]
	v_pk_mul_f32 v[70:71], v[202:203], v[198:199]
	v_pk_add_f32 v[64:65], v[64:65], v[192:193]
	v_pk_add_f32 v[66:67], v[66:67], v[194:195]
	v_mul_f32_e32 v64, 0xbfb8aa3b, v64
	v_mul_f32_e32 v65, 0xbfb8aa3b, v65
	v_mul_f32_e32 v66, 0xbfb8aa3b, v66
	v_mul_f32_e32 v67, 0xbfb8aa3b, v67
	v_exp_f32_e32 v64, v64
	v_exp_f32_e32 v65, v65
	v_exp_f32_e32 v66, v66
	v_exp_f32_e32 v67, v67
	v_lshlrev_b32_e32 v196, 16, v244
	v_and_b32_e32 v197, 0xffff0000, v244
	v_lshlrev_b32_e32 v198, 16, v245
	v_and_b32_e32 v199, 0xffff0000, v245
	v_lshlrev_b32_e32 v200, 16, v246
	v_and_b32_e32 v201, 0xffff0000, v246
	v_lshlrev_b32_e32 v202, 16, v247
	v_and_b32_e32 v203, 0xffff0000, v247
	v_add_f32_e32 v64, 1.0, v64
	v_add_f32_e32 v65, 1.0, v65
	v_add_f32_e32 v66, 1.0, v66
	v_add_f32_e32 v67, 1.0, v67
	v_rcp_f32_e32 v64, v64
	v_rcp_f32_e32 v65, v65
	v_rcp_f32_e32 v66, v66
	v_rcp_f32_e32 v67, v67
	v_mul_f32_e32 v244, 0xbfb8aa3b, v200
	v_mul_f32_e32 v245, 0xbfb8aa3b, v201
	v_mul_f32_e32 v246, 0xbfb8aa3b, v202
	v_mul_f32_e32 v247, 0xbfb8aa3b, v203
	v_exp_f32_e32 v244, v244
	v_exp_f32_e32 v245, v245
	v_exp_f32_e32 v246, v246
	v_exp_f32_e32 v247, v247
	v_pk_mul_f32 v[196:197], v[64:65], v[196:197]
	v_pk_mul_f32 v[198:199], v[66:67], v[198:199]
	v_add_f32_e32 v244, 1.0, v244
	v_add_f32_e32 v245, 1.0, v245
	v_add_f32_e32 v246, 1.0, v246
	v_add_f32_e32 v247, 1.0, v247
	v_rcp_f32_e32 v244, v244
	v_rcp_f32_e32 v245, v245
	v_rcp_f32_e32 v246, v246
	v_rcp_f32_e32 v247, v247
	v_pk_mul_f32 v[200:201], v[244:245], v[200:201]
	v_pk_mul_f32 v[202:203], v[246:247], v[202:203]
	v_pk_mul_f32 v[64:65], v[200:201], v[196:197]
	v_pk_mul_f32 v[66:67], v[202:203], v[198:199]
	v_cvt_pk_bf16_f32 v76, v76, v77
	v_cvt_pk_bf16_f32 v77, v78, v79
	v_cvt_pk_bf16_f32 v78, v72, v73
	v_cvt_pk_bf16_f32 v79, v74, v75
	v_cvt_pk_bf16_f32 v68, v68, v69
	v_cvt_pk_bf16_f32 v69, v70, v71
	v_cvt_pk_bf16_f32 v70, v64, v65
	v_cvt_pk_bf16_f32 v71, v66, v67
	s_add_u32 s62, s62, 0x8000
	s_addc_u32 s63, s63, 0
	v_permlane16_swap_b32_e32 v76, v78
	v_permlane16_swap_b32_e32 v77, v79
	global_store_dwordx4 v249, v[76:79], s[62:63]
	v_permlane16_swap_b32_e32 v68, v70
	v_permlane16_swap_b32_e32 v69, v71
	global_store_dwordx4 v249, v[68:71], s[62:63] offset:256
	s_add_u32 s58, s58, 0x8000
	s_addc_u32 s59, s59, 0
	s_add_u32 s60, s60, 0x8000
	s_addc_u32 s61, s61, 0
	global_load_dwordx2 v[220:221], v187, s[58:59]
	global_load_dwordx2 v[222:223], v187, s[60:61]
	global_load_dwordx2 v[224:225], v187, s[58:59] offset:32
	global_load_dwordx2 v[226:227], v187, s[60:61] offset:32
	global_load_dwordx2 v[240:241], v187, s[58:59] offset:256
	global_load_dwordx2 v[242:243], v187, s[60:61] offset:256
	global_load_dwordx2 v[244:245], v187, s[58:59] offset:288
	global_load_dwordx2 v[246:247], v187, s[60:61] offset:288
	s_waitcnt vmcnt(10)
; DI float sigmoidf_(float x) { return __builtin_amdgcn_rcpf(1.0f + __expf(-x)); }
; DI float siluf_(float x) { return x * sigmoidf_(x); }
; template <class FL, class FS>
; DI void gemm8_tile(char* shmc, const bf16_t* __restrict__ A, const bf16_t* __restrict__ Bt, const int K, const int brow, const int bcol, FL fl, FS fs) {
;     ...
; #pragma unroll
;   for (int ai = 0; ai < 2; ++ai)
; #pragma unroll
;     for (int mh = 0; mh < 2; ++mh) {
;       decltype(fl(0, 0)) ld[2][2][2];
; #pragma unroll
;       for (int mm = 0; mm < 2; ++mm)
; #pragma unroll
;         for (int bj = 0; bj < 2; ++bj)
; #pragma unroll
;           for (int n = 0; n < 2; ++n) ld[mm][bj][n] = fl(brow + ai * HALF + wr * 64 + (2 * mh + mm) * 16 + fr, bcol + bj * HALF + wc * 32 + n * 16 + 4 * fq);
; #pragma unroll
;       for (int mm = 0; mm < 2; ++mm)
; #pragma unroll
;         for (int bj = 0; bj < 2; ++bj)
; #pragma unroll
;           for (int n = 0; n < 2; ++n) fs(brow + ai * HALF + wr * 64 + (2 * mh + mm) * 16 + fr, bcol + bj * HALF + wc * 32 + n * 16 + 4 * fq, acc[ai][bj][2 * mh + mm][n], ld[mm][bj][n]);
; DI void phase_g2(const Params& p, const Sub& s, char* lds_all) {
;     ...
;       [&](int row, int col) { const size_t o = (size_t)row * D + col; Ld2 r; const uint2 a = *(const uint2*)(A + o), b = *(const uint2*)(z + o);
;         r.a.x = __uint_as_float(a.x); r.a.y = __uint_as_float(a.y); r.a.z = __uint_as_float(b.x); r.a.w = __uint_as_float(b.y); r.b = *(const float4*)(p.s5_b_glu + col); return r; },
;       [&](int row, int col, f32x4 v, const Ld2& l2) {
;         uint4 ld; ld.x = __float_as_uint(l2.a.x); ld.y = __float_as_uint(l2.a.y); ld.z = __float_as_uint(l2.a.z); ld.w = __float_as_uint(l2.a.w);
;         const size_t o = (size_t)row * D + col;
;         const float y0 = __uint_as_float(ld.x << 16), y1 = __uint_as_float(ld.x & 0xffff0000u), y2_ = __uint_as_float(ld.y << 16), y3 = __uint_as_float(ld.y & 0xffff0000u);
;         const float z0 = __uint_as_float(ld.z << 16), z1 = __uint_as_float(ld.z & 0xffff0000u), z2 = __uint_as_float(ld.w << 16), z3 = __uint_as_float(ld.w & 0xffff0000u);
;         const float4 b4 = l2.b;
;         st_bf4(y2 + o, y0 * sigmoidf_(v[0] + b4.x) * siluf_(z0), y1 * sigmoidf_(v[1] + b4.y) * siluf_(z1),
;                y2_ * sigmoidf_(v[2] + b4.z) * siluf_(z2), y3 * sigmoidf_(v[3] + b4.w) * siluf_(z3));
	v_pk_add_f32 v[60:61], v[60:61], v[172:173]
	v_pk_add_f32 v[62:63], v[62:63], v[174:175]
	v_mul_f32_e32 v60, 0xbfb8aa3b, v60
	v_mul_f32_e32 v61, 0xbfb8aa3b, v61
	v_mul_f32_e32 v62, 0xbfb8aa3b, v62
	v_mul_f32_e32 v63, 0xbfb8aa3b, v63
	v_exp_f32_e32 v60, v60
	v_exp_f32_e32 v61, v61
	v_exp_f32_e32 v62, v62
	v_exp_f32_e32 v63, v63
	v_lshlrev_b32_e32 v196, 16, v204
	v_and_b32_e32 v197, 0xffff0000, v204
	v_lshlrev_b32_e32 v198, 16, v205
	v_and_b32_e32 v199, 0xffff0000, v205
	v_lshlrev_b32_e32 v200, 16, v206
	v_and_b32_e32 v201, 0xffff0000, v206
	v_lshlrev_b32_e32 v202, 16, v207
	v_and_b32_e32 v203, 0xffff0000, v207
	v_add_f32_e32 v60, 1.0, v60
	v_add_f32_e32 v61, 1.0, v61
	v_add_f32_e32 v62, 1.0, v62
	v_add_f32_e32 v63, 1.0, v63
	v_rcp_f32_e32 v60, v60
	v_rcp_f32_e32 v61, v61
	v_rcp_f32_e32 v62, v62
	v_rcp_f32_e32 v63, v63
	v_mul_f32_e32 v204, 0xbfb8aa3b, v200
	v_mul_f32_e32 v205, 0xbfb8aa3b, v201
	v_mul_f32_e32 v206, 0xbfb8aa3b, v202
	v_mul_f32_e32 v207, 0xbfb8aa3b, v203
	v_exp_f32_e32 v204, v204
	v_exp_f32_e32 v205, v205
	v_exp_f32_e32 v206, v206
	v_exp_f32_e32 v207, v207
	v_pk_mul_f32 v[196:197], v[60:61], v[196:197]
	v_pk_mul_f32 v[198:199], v[62:63], v[198:199]
	v_add_f32_e32 v204, 1.0, v204
	v_add_f32_e32 v205, 1.0, v205
	v_add_f32_e32 v206, 1.0, v206
	v_add_f32_e32 v207, 1.0, v207
	v_rcp_f32_e32 v204, v204
	v_rcp_f32_e32 v205, v205
	v_rcp_f32_e32 v206, v206
	v_rcp_f32_e32 v207, v207
	v_pk_mul_f32 v[200:201], v[204:205], v[200:201]
	v_pk_mul_f32 v[202:203], v[206:207], v[202:203]
	v_pk_mul_f32 v[60:61], v[200:201], v[196:197]
	v_pk_mul_f32 v[62:63], v[202:203], v[198:199]
	v_pk_add_f32 v[56:57], v[56:57], v[176:177]
	v_pk_add_f32 v[58:59], v[58:59], v[178:179]
	v_mul_f32_e32 v56, 0xbfb8aa3b, v56
	v_mul_f32_e32 v57, 0xbfb8aa3b, v57
	v_mul_f32_e32 v58, 0xbfb8aa3b, v58
	v_mul_f32_e32 v59, 0xbfb8aa3b, v59
	v_exp_f32_e32 v56, v56
	v_exp_f32_e32 v57, v57
	v_exp_f32_e32 v58, v58
	v_exp_f32_e32 v59, v59
	v_lshlrev_b32_e32 v196, 16, v208
	v_and_b32_e32 v197, 0xffff0000, v208
	v_lshlrev_b32_e32 v198, 16, v209
	v_and_b32_e32 v199, 0xffff0000, v209
	v_lshlrev_b32_e32 v200, 16, v210
	v_and_b32_e32 v201, 0xffff0000, v210
	v_lshlrev_b32_e32 v202, 16, v211
	v_and_b32_e32 v203, 0xffff0000, v211
	v_add_f32_e32 v56, 1.0, v56
	v_add_f32_e32 v57, 1.0, v57
	v_add_f32_e32 v58, 1.0, v58
	v_add_f32_e32 v59, 1.0, v59
	v_rcp_f32_e32 v56, v56
	v_rcp_f32_e32 v57, v57
	v_rcp_f32_e32 v58, v58
	v_rcp_f32_e32 v59, v59
	v_mul_f32_e32 v208, 0xbfb8aa3b, v200
	v_mul_f32_e32 v209, 0xbfb8aa3b, v201
	v_mul_f32_e32 v210, 0xbfb8aa3b, v202
	v_mul_f32_e32 v211, 0xbfb8aa3b, v203
	v_exp_f32_e32 v208, v208
	v_exp_f32_e32 v209, v209
	v_exp_f32_e32 v210, v210
	v_exp_f32_e32 v211, v211
	v_pk_mul_f32 v[196:197], v[56:57], v[196:197]
	v_pk_mul_f32 v[198:199], v[58:59], v[198:199]
	v_add_f32_e32 v208, 1.0, v208
	v_add_f32_e32 v209, 1.0, v209
	v_add_f32_e32 v210, 1.0, v210
	v_add_f32_e32 v211, 1.0, v211
	v_rcp_f32_e32 v208, v208
	v_rcp_f32_e32 v209, v209
	v_rcp_f32_e32 v210, v210
	v_rcp_f32_e32 v211, v211
	v_pk_mul_f32 v[200:201], v[208:209], v[200:201]
	v_pk_mul_f32 v[202:203], v[210:211], v[202:203]
	v_pk_mul_f32 v[56:57], v[200:201], v[196:197]
	v_pk_mul_f32 v[58:59], v[202:203], v[198:199]
	v_pk_add_f32 v[52:53], v[52:53], v[188:189]
	v_pk_add_f32 v[54:55], v[54:55], v[190:191]
	v_mul_f32_e32 v52, 0xbfb8aa3b, v52
	v_mul_f32_e32 v53, 0xbfb8aa3b, v53
	v_mul_f32_e32 v54, 0xbfb8aa3b, v54
	v_mul_f32_e32 v55, 0xbfb8aa3b, v55
	v_exp_f32_e32 v52, v52
	v_exp_f32_e32 v53, v53
	v_exp_f32_e32 v54, v54
	v_exp_f32_e32 v55, v55
	v_lshlrev_b32_e32 v196, 16, v212
	v_and_b32_e32 v197, 0xffff0000, v212
	v_lshlrev_b32_e32 v198, 16, v213
	v_and_b32_e32 v199, 0xffff0000, v213
	v_lshlrev_b32_e32 v200, 16, v214
	v_and_b32_e32 v201, 0xffff0000, v214
	v_lshlrev_b32_e32 v202, 16, v215
	v_and_b32_e32 v203, 0xffff0000, v215
	v_add_f32_e32 v52, 1.0, v52
	v_add_f32_e32 v53, 1.0, v53
	v_add_f32_e32 v54, 1.0, v54
	v_add_f32_e32 v55, 1.0, v55
	v_rcp_f32_e32 v52, v52
	v_rcp_f32_e32 v53, v53
	v_rcp_f32_e32 v54, v54
	v_rcp_f32_e32 v55, v55
	v_mul_f32_e32 v212, 0xbfb8aa3b, v200
	v_mul_f32_e32 v213, 0xbfb8aa3b, v201
	v_mul_f32_e32 v214, 0xbfb8aa3b, v202
	v_mul_f32_e32 v215, 0xbfb8aa3b, v203
	v_exp_f32_e32 v212, v212
	v_exp_f32_e32 v213, v213
	v_exp_f32_e32 v214, v214
	v_exp_f32_e32 v215, v215
	v_pk_mul_f32 v[196:197], v[52:53], v[196:197]
	v_pk_mul_f32 v[198:199], v[54:55], v[198:199]
	v_add_f32_e32 v212, 1.0, v212
	v_add_f32_e32 v213, 1.0, v213
	v_add_f32_e32 v214, 1.0, v214
	v_add_f32_e32 v215, 1.0, v215
	v_rcp_f32_e32 v212, v212
	v_rcp_f32_e32 v213, v213
	v_rcp_f32_e32 v214, v214
	v_rcp_f32_e32 v215, v215
	v_pk_mul_f32 v[200:201], v[212:213], v[200:201]
	v_pk_mul_f32 v[202:203], v[214:215], v[202:203]
	v_pk_mul_f32 v[52:53], v[200:201], v[196:197]
	v_pk_mul_f32 v[54:55], v[202:203], v[198:199]
	v_pk_add_f32 v[48:49], v[48:49], v[192:193]
	v_pk_add_f32 v[50:51], v[50:51], v[194:195]
	v_mul_f32_e32 v48, 0xbfb8aa3b, v48
	v_mul_f32_e32 v49, 0xbfb8aa3b, v49
	v_mul_f32_e32 v50, 0xbfb8aa3b, v50
	v_mul_f32_e32 v51, 0xbfb8aa3b, v51
	v_exp_f32_e32 v48, v48
	v_exp_f32_e32 v49, v49
	v_exp_f32_e32 v50, v50
	v_exp_f32_e32 v51, v51
	v_lshlrev_b32_e32 v196, 16, v216
	v_and_b32_e32 v197, 0xffff0000, v216
	v_lshlrev_b32_e32 v198, 16, v217
	v_and_b32_e32 v199, 0xffff0000, v217
	v_lshlrev_b32_e32 v200, 16, v218
	v_and_b32_e32 v201, 0xffff0000, v218
	v_lshlrev_b32_e32 v202, 16, v219
	v_and_b32_e32 v203, 0xffff0000, v219
	v_add_f32_e32 v48, 1.0, v48
	v_add_f32_e32 v49, 1.0, v49
	v_add_f32_e32 v50, 1.0, v50
	v_add_f32_e32 v51, 1.0, v51
	v_rcp_f32_e32 v48, v48
	v_rcp_f32_e32 v49, v49
	v_rcp_f32_e32 v50, v50
	v_rcp_f32_e32 v51, v51
; DI float sigmoidf_(float x) { return __builtin_amdgcn_rcpf(1.0f + __expf(-x)); }
; DI float siluf_(float x) { return x * sigmoidf_(x); }
; template <class FL, class FS>
; DI void gemm8_tile(char* shmc, const bf16_t* __restrict__ A, const bf16_t* __restrict__ Bt, const int K, const int brow, const int bcol, FL fl, FS fs) {
;     ...
; #pragma unroll
;   for (int ai = 0; ai < 2; ++ai)
; #pragma unroll
;     for (int mh = 0; mh < 2; ++mh) {
;       decltype(fl(0, 0)) ld[2][2][2];
; #pragma unroll
;       for (int mm = 0; mm < 2; ++mm)
; #pragma unroll
;         for (int bj = 0; bj < 2; ++bj)
; #pragma unroll
;           for (int n = 0; n < 2; ++n) ld[mm][bj][n] = fl(brow + ai * HALF + wr * 64 + (2 * mh + mm) * 16 + fr, bcol + bj * HALF + wc * 32 + n * 16 + 4 * fq);
; #pragma unroll
;       for (int mm = 0; mm < 2; ++mm)
; #pragma unroll
;         for (int bj = 0; bj < 2; ++bj)
; #pragma unroll
;           for (int n = 0; n < 2; ++n) fs(brow + ai * HALF + wr * 64 + (2 * mh + mm) * 16 + fr, bcol + bj * HALF + wc * 32 + n * 16 + 4 * fq, acc[ai][bj][2 * mh + mm][n], ld[mm][bj][n]);
; DI void phase_g2(const Params& p, const Sub& s, char* lds_all) {
;     ...
;       [&](int row, int col) { const size_t o = (size_t)row * D + col; Ld2 r; const uint2 a = *(const uint2*)(A + o), b = *(const uint2*)(z + o);
;         r.a.x = __uint_as_float(a.x); r.a.y = __uint_as_float(a.y); r.a.z = __uint_as_float(b.x); r.a.w = __uint_as_float(b.y); r.b = *(const float4*)(p.s5_b_glu + col); return r; },
;       [&](int row, int col, f32x4 v, const Ld2& l2) {
;         uint4 ld; ld.x = __float_as_uint(l2.a.x); ld.y = __float_as_uint(l2.a.y); ld.z = __float_as_uint(l2.a.z); ld.w = __float_as_uint(l2.a.w);
;         const size_t o = (size_t)row * D + col;
;         const float y0 = __uint_as_float(ld.x << 16), y1 = __uint_as_float(ld.x & 0xffff0000u), y2_ = __uint_as_float(ld.y << 16), y3 = __uint_as_float(ld.y & 0xffff0000u);
;         const float z0 = __uint_as_float(ld.z << 16), z1 = __uint_as_float(ld.z & 0xffff0000u), z2 = __uint_as_float(ld.w << 16), z3 = __uint_as_float(ld.w & 0xffff0000u);
;         const float4 b4 = l2.b;
;         st_bf4(y2 + o, y0 * sigmoidf_(v[0] + b4.x) * siluf_(z0), y1 * sigmoidf_(v[1] + b4.y) * siluf_(z1),
;                y2_ * sigmoidf_(v[2] + b4.z) * siluf_(z2), y3 * sigmoidf_(v[3] + b4.w) * siluf_(z3));
	v_mul_f32_e32 v216, 0xbfb8aa3b, v200
	v_mul_f32_e32 v217, 0xbfb8aa3b, v201
	v_mul_f32_e32 v218, 0xbfb8aa3b, v202
	v_mul_f32_e32 v219, 0xbfb8aa3b, v203
	v_exp_f32_e32 v216, v216
	v_exp_f32_e32 v217, v217
	v_exp_f32_e32 v218, v218
	v_exp_f32_e32 v219, v219
	v_pk_mul_f32 v[196:197], v[48:49], v[196:197]
	v_pk_mul_f32 v[198:199], v[50:51], v[198:199]
	v_add_f32_e32 v216, 1.0, v216
	v_add_f32_e32 v217, 1.0, v217
	v_add_f32_e32 v218, 1.0, v218
	v_add_f32_e32 v219, 1.0, v219
	v_rcp_f32_e32 v216, v216
	v_rcp_f32_e32 v217, v217
	v_rcp_f32_e32 v218, v218
	v_rcp_f32_e32 v219, v219
	v_pk_mul_f32 v[200:201], v[216:217], v[200:201]
	v_pk_mul_f32 v[202:203], v[218:219], v[202:203]
	v_pk_mul_f32 v[48:49], v[200:201], v[196:197]
	v_pk_mul_f32 v[50:51], v[202:203], v[198:199]
	v_cvt_pk_bf16_f32 v60, v60, v61
	v_cvt_pk_bf16_f32 v61, v62, v63
	v_cvt_pk_bf16_f32 v62, v56, v57
	v_cvt_pk_bf16_f32 v63, v58, v59
	v_cvt_pk_bf16_f32 v52, v52, v53
	v_cvt_pk_bf16_f32 v53, v54, v55
	v_cvt_pk_bf16_f32 v54, v48, v49
	v_cvt_pk_bf16_f32 v55, v50, v51
	s_add_u32 s62, s62, 0x28000
	s_addc_u32 s63, s63, 0
	v_permlane16_swap_b32_e32 v60, v62
	v_permlane16_swap_b32_e32 v61, v63
	global_store_dwordx4 v249, v[60:63], s[62:63]
	v_permlane16_swap_b32_e32 v52, v54
	v_permlane16_swap_b32_e32 v53, v55
	global_store_dwordx4 v249, v[52:55], s[62:63] offset:256
	s_add_u32 s58, s58, 0x8000
	s_addc_u32 s59, s59, 0
	s_add_u32 s60, s60, 0x8000
	s_addc_u32 s61, s61, 0
	global_load_dwordx2 v[204:205], v187, s[58:59]
	global_load_dwordx2 v[206:207], v187, s[60:61]
	global_load_dwordx2 v[208:209], v187, s[58:59] offset:32
	global_load_dwordx2 v[210:211], v187, s[60:61] offset:32
	global_load_dwordx2 v[212:213], v187, s[58:59] offset:256
	global_load_dwordx2 v[214:215], v187, s[60:61] offset:256
	global_load_dwordx2 v[216:217], v187, s[58:59] offset:288
	global_load_dwordx2 v[218:219], v187, s[60:61] offset:288
	s_waitcnt vmcnt(10)
	v_pk_add_f32 v[44:45], v[44:45], v[172:173]
	v_pk_add_f32 v[46:47], v[46:47], v[174:175]
	v_mul_f32_e32 v44, 0xbfb8aa3b, v44
	v_mul_f32_e32 v45, 0xbfb8aa3b, v45
	v_mul_f32_e32 v46, 0xbfb8aa3b, v46
	v_mul_f32_e32 v47, 0xbfb8aa3b, v47
	v_exp_f32_e32 v44, v44
	v_exp_f32_e32 v45, v45
	v_exp_f32_e32 v46, v46
	v_exp_f32_e32 v47, v47
	v_lshlrev_b32_e32 v196, 16, v220
	v_and_b32_e32 v197, 0xffff0000, v220
	v_lshlrev_b32_e32 v198, 16, v221
	v_and_b32_e32 v199, 0xffff0000, v221
	v_lshlrev_b32_e32 v200, 16, v222
	v_and_b32_e32 v201, 0xffff0000, v222
	v_lshlrev_b32_e32 v202, 16, v223
	v_and_b32_e32 v203, 0xffff0000, v223
	v_add_f32_e32 v44, 1.0, v44
	v_add_f32_e32 v45, 1.0, v45
	v_add_f32_e32 v46, 1.0, v46
	v_add_f32_e32 v47, 1.0, v47
	v_rcp_f32_e32 v44, v44
	v_rcp_f32_e32 v45, v45
	v_rcp_f32_e32 v46, v46
	v_rcp_f32_e32 v47, v47
	v_mul_f32_e32 v220, 0xbfb8aa3b, v200
	v_mul_f32_e32 v221, 0xbfb8aa3b, v201
	v_mul_f32_e32 v222, 0xbfb8aa3b, v202
	v_mul_f32_e32 v223, 0xbfb8aa3b, v203
	v_exp_f32_e32 v220, v220
	v_exp_f32_e32 v221, v221
	v_exp_f32_e32 v222, v222
	v_exp_f32_e32 v223, v223
	v_pk_mul_f32 v[196:197], v[44:45], v[196:197]
	v_pk_mul_f32 v[198:199], v[46:47], v[198:199]
	v_add_f32_e32 v220, 1.0, v220
	v_add_f32_e32 v221, 1.0, v221
	v_add_f32_e32 v222, 1.0, v222
	v_add_f32_e32 v223, 1.0, v223
	v_rcp_f32_e32 v220, v220
	v_rcp_f32_e32 v221, v221
	v_rcp_f32_e32 v222, v222
	v_rcp_f32_e32 v223, v223
	v_pk_mul_f32 v[200:201], v[220:221], v[200:201]
	v_pk_mul_f32 v[202:203], v[222:223], v[202:203]
	v_pk_mul_f32 v[44:45], v[200:201], v[196:197]
	v_pk_mul_f32 v[46:47], v[202:203], v[198:199]
	v_pk_add_f32 v[40:41], v[40:41], v[176:177]
	v_pk_add_f32 v[42:43], v[42:43], v[178:179]
	v_mul_f32_e32 v40, 0xbfb8aa3b, v40
	v_mul_f32_e32 v41, 0xbfb8aa3b, v41
	v_mul_f32_e32 v42, 0xbfb8aa3b, v42
	v_mul_f32_e32 v43, 0xbfb8aa3b, v43
	v_exp_f32_e32 v40, v40
	v_exp_f32_e32 v41, v41
	v_exp_f32_e32 v42, v42
	v_exp_f32_e32 v43, v43
	v_lshlrev_b32_e32 v196, 16, v224
	v_and_b32_e32 v197, 0xffff0000, v224
	v_lshlrev_b32_e32 v198, 16, v225
	v_and_b32_e32 v199, 0xffff0000, v225
	v_lshlrev_b32_e32 v200, 16, v226
	v_and_b32_e32 v201, 0xffff0000, v226
	v_lshlrev_b32_e32 v202, 16, v227
	v_and_b32_e32 v203, 0xffff0000, v227
	v_add_f32_e32 v40, 1.0, v40
	v_add_f32_e32 v41, 1.0, v41
	v_add_f32_e32 v42, 1.0, v42
	v_add_f32_e32 v43, 1.0, v43
	v_rcp_f32_e32 v40, v40
	v_rcp_f32_e32 v41, v41
	v_rcp_f32_e32 v42, v42
	v_rcp_f32_e32 v43, v43
	v_mul_f32_e32 v224, 0xbfb8aa3b, v200
	v_mul_f32_e32 v225, 0xbfb8aa3b, v201
	v_mul_f32_e32 v226, 0xbfb8aa3b, v202
	v_mul_f32_e32 v227, 0xbfb8aa3b, v203
	v_exp_f32_e32 v224, v224
	v_exp_f32_e32 v225, v225
	v_exp_f32_e32 v226, v226
	v_exp_f32_e32 v227, v227
	v_pk_mul_f32 v[196:197], v[40:41], v[196:197]
	v_pk_mul_f32 v[198:199], v[42:43], v[198:199]
	v_add_f32_e32 v224, 1.0, v224
	v_add_f32_e32 v225, 1.0, v225
	v_add_f32_e32 v226, 1.0, v226
	v_add_f32_e32 v227, 1.0, v227
	v_rcp_f32_e32 v224, v224
	v_rcp_f32_e32 v225, v225
	v_rcp_f32_e32 v226, v226
	v_rcp_f32_e32 v227, v227
	v_pk_mul_f32 v[200:201], v[224:225], v[200:201]
	v_pk_mul_f32 v[202:203], v[226:227], v[202:203]
	v_pk_mul_f32 v[40:41], v[200:201], v[196:197]
	v_pk_mul_f32 v[42:43], v[202:203], v[198:199]
	v_pk_add_f32 v[36:37], v[36:37], v[188:189]
	v_pk_add_f32 v[38:39], v[38:39], v[190:191]
	v_mul_f32_e32 v36, 0xbfb8aa3b, v36
	v_mul_f32_e32 v37, 0xbfb8aa3b, v37
	v_mul_f32_e32 v38, 0xbfb8aa3b, v38
	v_mul_f32_e32 v39, 0xbfb8aa3b, v39
	v_exp_f32_e32 v36, v36
	v_exp_f32_e32 v37, v37
	v_exp_f32_e32 v38, v38
	v_exp_f32_e32 v39, v39
	v_lshlrev_b32_e32 v196, 16, v240
	v_and_b32_e32 v197, 0xffff0000, v240
	v_lshlrev_b32_e32 v198, 16, v241
	v_and_b32_e32 v199, 0xffff0000, v241
	v_lshlrev_b32_e32 v200, 16, v242
	v_and_b32_e32 v201, 0xffff0000, v242
; DI float sigmoidf_(float x) { return __builtin_amdgcn_rcpf(1.0f + __expf(-x)); }
; DI float siluf_(float x) { return x * sigmoidf_(x); }
; template <class FL, class FS>
; DI void gemm8_tile(char* shmc, const bf16_t* __restrict__ A, const bf16_t* __restrict__ Bt, const int K, const int brow, const int bcol, FL fl, FS fs) {
;     ...
; #pragma unroll
;   for (int ai = 0; ai < 2; ++ai)
; #pragma unroll
;     for (int mh = 0; mh < 2; ++mh) {
;       decltype(fl(0, 0)) ld[2][2][2];
; #pragma unroll
;       for (int mm = 0; mm < 2; ++mm)
; #pragma unroll
;         for (int bj = 0; bj < 2; ++bj)
; #pragma unroll
;           for (int n = 0; n < 2; ++n) ld[mm][bj][n] = fl(brow + ai * HALF + wr * 64 + (2 * mh + mm) * 16 + fr, bcol + bj * HALF + wc * 32 + n * 16 + 4 * fq);
; #pragma unroll
;       for (int mm = 0; mm < 2; ++mm)
; #pragma unroll
;         for (int bj = 0; bj < 2; ++bj)
; #pragma unroll
;           for (int n = 0; n < 2; ++n) fs(brow + ai * HALF + wr * 64 + (2 * mh + mm) * 16 + fr, bcol + bj * HALF + wc * 32 + n * 16 + 4 * fq, acc[ai][bj][2 * mh + mm][n], ld[mm][bj][n]);
; DI void phase_g2(const Params& p, const Sub& s, char* lds_all) {
;     ...
;       [&](int row, int col) { const size_t o = (size_t)row * D + col; Ld2 r; const uint2 a = *(const uint2*)(A + o), b = *(const uint2*)(z + o);
;         r.a.x = __uint_as_float(a.x); r.a.y = __uint_as_float(a.y); r.a.z = __uint_as_float(b.x); r.a.w = __uint_as_float(b.y); r.b = *(const float4*)(p.s5_b_glu + col); return r; },
;       [&](int row, int col, f32x4 v, const Ld2& l2) {
;         uint4 ld; ld.x = __float_as_uint(l2.a.x); ld.y = __float_as_uint(l2.a.y); ld.z = __float_as_uint(l2.a.z); ld.w = __float_as_uint(l2.a.w);
;         const size_t o = (size_t)row * D + col;
;         const float y0 = __uint_as_float(ld.x << 16), y1 = __uint_as_float(ld.x & 0xffff0000u), y2_ = __uint_as_float(ld.y << 16), y3 = __uint_as_float(ld.y & 0xffff0000u);
;         const float z0 = __uint_as_float(ld.z << 16), z1 = __uint_as_float(ld.z & 0xffff0000u), z2 = __uint_as_float(ld.w << 16), z3 = __uint_as_float(ld.w & 0xffff0000u);
;         const float4 b4 = l2.b;
;         st_bf4(y2 + o, y0 * sigmoidf_(v[0] + b4.x) * siluf_(z0), y1 * sigmoidf_(v[1] + b4.y) * siluf_(z1),
;                y2_ * sigmoidf_(v[2] + b4.z) * siluf_(z2), y3 * sigmoidf_(v[3] + b4.w) * siluf_(z3));
	v_lshlrev_b32_e32 v202, 16, v243
	v_and_b32_e32 v203, 0xffff0000, v243
	v_add_f32_e32 v36, 1.0, v36
	v_add_f32_e32 v37, 1.0, v37
	v_add_f32_e32 v38, 1.0, v38
	v_add_f32_e32 v39, 1.0, v39
	v_rcp_f32_e32 v36, v36
	v_rcp_f32_e32 v37, v37
	v_rcp_f32_e32 v38, v38
	v_rcp_f32_e32 v39, v39
	v_mul_f32_e32 v240, 0xbfb8aa3b, v200
	v_mul_f32_e32 v241, 0xbfb8aa3b, v201
	v_mul_f32_e32 v242, 0xbfb8aa3b, v202
	v_mul_f32_e32 v243, 0xbfb8aa3b, v203
	v_exp_f32_e32 v240, v240
	v_exp_f32_e32 v241, v241
	v_exp_f32_e32 v242, v242
	v_exp_f32_e32 v243, v243
	v_pk_mul_f32 v[196:197], v[36:37], v[196:197]
	v_pk_mul_f32 v[198:199], v[38:39], v[198:199]
	v_add_f32_e32 v240, 1.0, v240
	v_add_f32_e32 v241, 1.0, v241
	v_add_f32_e32 v242, 1.0, v242
	v_add_f32_e32 v243, 1.0, v243
	v_rcp_f32_e32 v240, v240
	v_rcp_f32_e32 v241, v241
	v_rcp_f32_e32 v242, v242
	v_rcp_f32_e32 v243, v243
	v_pk_mul_f32 v[200:201], v[240:241], v[200:201]
	v_pk_mul_f32 v[202:203], v[242:243], v[202:203]
	v_pk_mul_f32 v[36:37], v[200:201], v[196:197]
	v_pk_mul_f32 v[38:39], v[202:203], v[198:199]
	v_pk_add_f32 v[32:33], v[32:33], v[192:193]
	v_pk_add_f32 v[34:35], v[34:35], v[194:195]
	v_mul_f32_e32 v32, 0xbfb8aa3b, v32
	v_mul_f32_e32 v33, 0xbfb8aa3b, v33
	v_mul_f32_e32 v34, 0xbfb8aa3b, v34
	v_mul_f32_e32 v35, 0xbfb8aa3b, v35
	v_exp_f32_e32 v32, v32
	v_exp_f32_e32 v33, v33
	v_exp_f32_e32 v34, v34
	v_exp_f32_e32 v35, v35
	v_lshlrev_b32_e32 v196, 16, v244
	v_and_b32_e32 v197, 0xffff0000, v244
	v_lshlrev_b32_e32 v198, 16, v245
	v_and_b32_e32 v199, 0xffff0000, v245
	v_lshlrev_b32_e32 v200, 16, v246
	v_and_b32_e32 v201, 0xffff0000, v246
	v_lshlrev_b32_e32 v202, 16, v247
	v_and_b32_e32 v203, 0xffff0000, v247
	v_add_f32_e32 v32, 1.0, v32
	v_add_f32_e32 v33, 1.0, v33
	v_add_f32_e32 v34, 1.0, v34
	v_add_f32_e32 v35, 1.0, v35
	v_rcp_f32_e32 v32, v32
	v_rcp_f32_e32 v33, v33
	v_rcp_f32_e32 v34, v34
	v_rcp_f32_e32 v35, v35
	v_mul_f32_e32 v244, 0xbfb8aa3b, v200
	v_mul_f32_e32 v245, 0xbfb8aa3b, v201
	v_mul_f32_e32 v246, 0xbfb8aa3b, v202
	v_mul_f32_e32 v247, 0xbfb8aa3b, v203
	v_exp_f32_e32 v244, v244
	v_exp_f32_e32 v245, v245
	v_exp_f32_e32 v246, v246
	v_exp_f32_e32 v247, v247
	v_pk_mul_f32 v[196:197], v[32:33], v[196:197]
	v_pk_mul_f32 v[198:199], v[34:35], v[198:199]
	v_add_f32_e32 v244, 1.0, v244
	v_add_f32_e32 v245, 1.0, v245
	v_add_f32_e32 v246, 1.0, v246
	v_add_f32_e32 v247, 1.0, v247
	v_rcp_f32_e32 v244, v244
	v_rcp_f32_e32 v245, v245
	v_rcp_f32_e32 v246, v246
	v_rcp_f32_e32 v247, v247
	v_pk_mul_f32 v[200:201], v[244:245], v[200:201]
	v_pk_mul_f32 v[202:203], v[246:247], v[202:203]
	v_pk_mul_f32 v[32:33], v[200:201], v[196:197]
	v_pk_mul_f32 v[34:35], v[202:203], v[198:199]
	v_cvt_pk_bf16_f32 v44, v44, v45
	v_cvt_pk_bf16_f32 v45, v46, v47
	v_cvt_pk_bf16_f32 v46, v40, v41
	v_cvt_pk_bf16_f32 v47, v42, v43
	v_cvt_pk_bf16_f32 v36, v36, v37
	v_cvt_pk_bf16_f32 v37, v38, v39
	v_cvt_pk_bf16_f32 v38, v32, v33
	v_cvt_pk_bf16_f32 v39, v34, v35
	s_add_u32 s62, s62, 0x8000
	s_addc_u32 s63, s63, 0
	v_permlane16_swap_b32_e32 v44, v46
	v_permlane16_swap_b32_e32 v45, v47
	global_store_dwordx4 v249, v[44:47], s[62:63]
	v_permlane16_swap_b32_e32 v36, v38
	v_permlane16_swap_b32_e32 v37, v39
	global_store_dwordx4 v249, v[36:39], s[62:63] offset:256
	s_add_u32 s58, s58, 0x8000
	s_addc_u32 s59, s59, 0
	s_add_u32 s60, s60, 0x8000
	s_addc_u32 s61, s61, 0
	global_load_dwordx2 v[220:221], v187, s[58:59]
	global_load_dwordx2 v[222:223], v187, s[60:61]
	global_load_dwordx2 v[224:225], v187, s[58:59] offset:32
	global_load_dwordx2 v[226:227], v187, s[60:61] offset:32
	global_load_dwordx2 v[240:241], v187, s[58:59] offset:256
	global_load_dwordx2 v[242:243], v187, s[60:61] offset:256
	global_load_dwordx2 v[244:245], v187, s[58:59] offset:288
	global_load_dwordx2 v[246:247], v187, s[60:61] offset:288
	s_waitcnt vmcnt(10)
	v_pk_add_f32 v[28:29], v[28:29], v[172:173]
	v_pk_add_f32 v[30:31], v[30:31], v[174:175]
	v_mul_f32_e32 v28, 0xbfb8aa3b, v28
	v_mul_f32_e32 v29, 0xbfb8aa3b, v29
	v_mul_f32_e32 v30, 0xbfb8aa3b, v30
	v_mul_f32_e32 v31, 0xbfb8aa3b, v31
	v_exp_f32_e32 v28, v28
	v_exp_f32_e32 v29, v29
	v_exp_f32_e32 v30, v30
	v_exp_f32_e32 v31, v31
	v_lshlrev_b32_e32 v196, 16, v204
	v_and_b32_e32 v197, 0xffff0000, v204
	v_lshlrev_b32_e32 v198, 16, v205
	v_and_b32_e32 v199, 0xffff0000, v205
	v_lshlrev_b32_e32 v200, 16, v206
	v_and_b32_e32 v201, 0xffff0000, v206
	v_lshlrev_b32_e32 v202, 16, v207
	v_and_b32_e32 v203, 0xffff0000, v207
	v_add_f32_e32 v28, 1.0, v28
	v_add_f32_e32 v29, 1.0, v29
	v_add_f32_e32 v30, 1.0, v30
	v_add_f32_e32 v31, 1.0, v31
	v_rcp_f32_e32 v28, v28
	v_rcp_f32_e32 v29, v29
	v_rcp_f32_e32 v30, v30
	v_rcp_f32_e32 v31, v31
	v_mul_f32_e32 v204, 0xbfb8aa3b, v200
	v_mul_f32_e32 v205, 0xbfb8aa3b, v201
	v_mul_f32_e32 v206, 0xbfb8aa3b, v202
	v_mul_f32_e32 v207, 0xbfb8aa3b, v203
	v_exp_f32_e32 v204, v204
	v_exp_f32_e32 v205, v205
	v_exp_f32_e32 v206, v206
	v_exp_f32_e32 v207, v207
	v_pk_mul_f32 v[196:197], v[28:29], v[196:197]
	v_pk_mul_f32 v[198:199], v[30:31], v[198:199]
	v_add_f32_e32 v204, 1.0, v204
	v_add_f32_e32 v205, 1.0, v205
	v_add_f32_e32 v206, 1.0, v206
	v_add_f32_e32 v207, 1.0, v207
	v_rcp_f32_e32 v204, v204
	v_rcp_f32_e32 v205, v205
	v_rcp_f32_e32 v206, v206
	v_rcp_f32_e32 v207, v207
	v_pk_mul_f32 v[200:201], v[204:205], v[200:201]
	v_pk_mul_f32 v[202:203], v[206:207], v[202:203]
	v_pk_mul_f32 v[28:29], v[200:201], v[196:197]
	v_pk_mul_f32 v[30:31], v[202:203], v[198:199]
	v_pk_add_f32 v[24:25], v[24:25], v[176:177]
	v_pk_add_f32 v[26:27], v[26:27], v[178:179]
	v_mul_f32_e32 v24, 0xbfb8aa3b, v24
	v_mul_f32_e32 v25, 0xbfb8aa3b, v25
	v_mul_f32_e32 v26, 0xbfb8aa3b, v26
	v_mul_f32_e32 v27, 0xbfb8aa3b, v27
	v_exp_f32_e32 v24, v24
; DI float sigmoidf_(float x) { return __builtin_amdgcn_rcpf(1.0f + __expf(-x)); }
; DI float siluf_(float x) { return x * sigmoidf_(x); }
; template <class FL, class FS>
; DI void gemm8_tile(char* shmc, const bf16_t* __restrict__ A, const bf16_t* __restrict__ Bt, const int K, const int brow, const int bcol, FL fl, FS fs) {
;     ...
; #pragma unroll
;   for (int ai = 0; ai < 2; ++ai)
; #pragma unroll
;     for (int mh = 0; mh < 2; ++mh) {
;       decltype(fl(0, 0)) ld[2][2][2];
; #pragma unroll
;       for (int mm = 0; mm < 2; ++mm)
; #pragma unroll
;         for (int bj = 0; bj < 2; ++bj)
; #pragma unroll
;           for (int n = 0; n < 2; ++n) ld[mm][bj][n] = fl(brow + ai * HALF + wr * 64 + (2 * mh + mm) * 16 + fr, bcol + bj * HALF + wc * 32 + n * 16 + 4 * fq);
; #pragma unroll
;       for (int mm = 0; mm < 2; ++mm)
; #pragma unroll
;         for (int bj = 0; bj < 2; ++bj)
; #pragma unroll
;           for (int n = 0; n < 2; ++n) fs(brow + ai * HALF + wr * 64 + (2 * mh + mm) * 16 + fr, bcol + bj * HALF + wc * 32 + n * 16 + 4 * fq, acc[ai][bj][2 * mh + mm][n], ld[mm][bj][n]);
; DI void phase_g2(const Params& p, const Sub& s, char* lds_all) {
;     ...
;       [&](int row, int col) { const size_t o = (size_t)row * D + col; Ld2 r; const uint2 a = *(const uint2*)(A + o), b = *(const uint2*)(z + o);
;         r.a.x = __uint_as_float(a.x); r.a.y = __uint_as_float(a.y); r.a.z = __uint_as_float(b.x); r.a.w = __uint_as_float(b.y); r.b = *(const float4*)(p.s5_b_glu + col); return r; },
;       [&](int row, int col, f32x4 v, const Ld2& l2) {
;         uint4 ld; ld.x = __float_as_uint(l2.a.x); ld.y = __float_as_uint(l2.a.y); ld.z = __float_as_uint(l2.a.z); ld.w = __float_as_uint(l2.a.w);
;         const size_t o = (size_t)row * D + col;
;         const float y0 = __uint_as_float(ld.x << 16), y1 = __uint_as_float(ld.x & 0xffff0000u), y2_ = __uint_as_float(ld.y << 16), y3 = __uint_as_float(ld.y & 0xffff0000u);
;         const float z0 = __uint_as_float(ld.z << 16), z1 = __uint_as_float(ld.z & 0xffff0000u), z2 = __uint_as_float(ld.w << 16), z3 = __uint_as_float(ld.w & 0xffff0000u);
;         const float4 b4 = l2.b;
;         st_bf4(y2 + o, y0 * sigmoidf_(v[0] + b4.x) * siluf_(z0), y1 * sigmoidf_(v[1] + b4.y) * siluf_(z1),
;                y2_ * sigmoidf_(v[2] + b4.z) * siluf_(z2), y3 * sigmoidf_(v[3] + b4.w) * siluf_(z3));
	v_exp_f32_e32 v25, v25
	v_exp_f32_e32 v26, v26
	v_exp_f32_e32 v27, v27
	v_lshlrev_b32_e32 v196, 16, v208
	v_and_b32_e32 v197, 0xffff0000, v208
	v_lshlrev_b32_e32 v198, 16, v209
	v_and_b32_e32 v199, 0xffff0000, v209
	v_lshlrev_b32_e32 v200, 16, v210
	v_and_b32_e32 v201, 0xffff0000, v210
	v_lshlrev_b32_e32 v202, 16, v211
	v_and_b32_e32 v203, 0xffff0000, v211
	v_add_f32_e32 v24, 1.0, v24
	v_add_f32_e32 v25, 1.0, v25
	v_add_f32_e32 v26, 1.0, v26
	v_add_f32_e32 v27, 1.0, v27
	v_rcp_f32_e32 v24, v24
	v_rcp_f32_e32 v25, v25
	v_rcp_f32_e32 v26, v26
	v_rcp_f32_e32 v27, v27
	v_mul_f32_e32 v208, 0xbfb8aa3b, v200
	v_mul_f32_e32 v209, 0xbfb8aa3b, v201
	v_mul_f32_e32 v210, 0xbfb8aa3b, v202
	v_mul_f32_e32 v211, 0xbfb8aa3b, v203
	v_exp_f32_e32 v208, v208
	v_exp_f32_e32 v209, v209
	v_exp_f32_e32 v210, v210
	v_exp_f32_e32 v211, v211
	v_pk_mul_f32 v[196:197], v[24:25], v[196:197]
	v_pk_mul_f32 v[198:199], v[26:27], v[198:199]
	v_add_f32_e32 v208, 1.0, v208
	v_add_f32_e32 v209, 1.0, v209
	v_add_f32_e32 v210, 1.0, v210
	v_add_f32_e32 v211, 1.0, v211
	v_rcp_f32_e32 v208, v208
	v_rcp_f32_e32 v209, v209
	v_rcp_f32_e32 v210, v210
	v_rcp_f32_e32 v211, v211
	v_pk_mul_f32 v[200:201], v[208:209], v[200:201]
	v_pk_mul_f32 v[202:203], v[210:211], v[202:203]
	v_pk_mul_f32 v[24:25], v[200:201], v[196:197]
	v_pk_mul_f32 v[26:27], v[202:203], v[198:199]
	v_pk_add_f32 v[20:21], v[20:21], v[188:189]
	v_pk_add_f32 v[22:23], v[22:23], v[190:191]
	v_mul_f32_e32 v20, 0xbfb8aa3b, v20
	v_mul_f32_e32 v21, 0xbfb8aa3b, v21
	v_mul_f32_e32 v22, 0xbfb8aa3b, v22
	v_mul_f32_e32 v23, 0xbfb8aa3b, v23
	v_exp_f32_e32 v20, v20
	v_exp_f32_e32 v21, v21
	v_exp_f32_e32 v22, v22
	v_exp_f32_e32 v23, v23
	v_lshlrev_b32_e32 v196, 16, v212
	v_and_b32_e32 v197, 0xffff0000, v212
	v_lshlrev_b32_e32 v198, 16, v213
	v_and_b32_e32 v199, 0xffff0000, v213
	v_lshlrev_b32_e32 v200, 16, v214
	v_and_b32_e32 v201, 0xffff0000, v214
	v_lshlrev_b32_e32 v202, 16, v215
	v_and_b32_e32 v203, 0xffff0000, v215
	v_add_f32_e32 v20, 1.0, v20
	v_add_f32_e32 v21, 1.0, v21
	v_add_f32_e32 v22, 1.0, v22
	v_add_f32_e32 v23, 1.0, v23
	v_rcp_f32_e32 v20, v20
	v_rcp_f32_e32 v21, v21
	v_rcp_f32_e32 v22, v22
	v_rcp_f32_e32 v23, v23
	v_mul_f32_e32 v212, 0xbfb8aa3b, v200
	v_mul_f32_e32 v213, 0xbfb8aa3b, v201
	v_mul_f32_e32 v214, 0xbfb8aa3b, v202
	v_mul_f32_e32 v215, 0xbfb8aa3b, v203
	v_exp_f32_e32 v212, v212
	v_exp_f32_e32 v213, v213
	v_exp_f32_e32 v214, v214
	v_exp_f32_e32 v215, v215
	v_pk_mul_f32 v[196:197], v[20:21], v[196:197]
	v_pk_mul_f32 v[198:199], v[22:23], v[198:199]
	v_add_f32_e32 v212, 1.0, v212
	v_add_f32_e32 v213, 1.0, v213
	v_add_f32_e32 v214, 1.0, v214
	v_add_f32_e32 v215, 1.0, v215
	v_rcp_f32_e32 v212, v212
	v_rcp_f32_e32 v213, v213
	v_rcp_f32_e32 v214, v214
	v_rcp_f32_e32 v215, v215
	v_pk_mul_f32 v[200:201], v[212:213], v[200:201]
	v_pk_mul_f32 v[202:203], v[214:215], v[202:203]
	v_pk_mul_f32 v[20:21], v[200:201], v[196:197]
	v_pk_mul_f32 v[22:23], v[202:203], v[198:199]
	v_pk_add_f32 v[16:17], v[16:17], v[192:193]
	v_pk_add_f32 v[18:19], v[18:19], v[194:195]
	v_mul_f32_e32 v16, 0xbfb8aa3b, v16
	v_mul_f32_e32 v17, 0xbfb8aa3b, v17
	v_mul_f32_e32 v18, 0xbfb8aa3b, v18
	v_mul_f32_e32 v19, 0xbfb8aa3b, v19
	v_exp_f32_e32 v16, v16
	v_exp_f32_e32 v17, v17
	v_exp_f32_e32 v18, v18
	v_exp_f32_e32 v19, v19
	v_lshlrev_b32_e32 v196, 16, v216
	v_and_b32_e32 v197, 0xffff0000, v216
	v_lshlrev_b32_e32 v198, 16, v217
	v_and_b32_e32 v199, 0xffff0000, v217
	v_lshlrev_b32_e32 v200, 16, v218
	v_and_b32_e32 v201, 0xffff0000, v218
	v_lshlrev_b32_e32 v202, 16, v219
	v_and_b32_e32 v203, 0xffff0000, v219
	v_add_f32_e32 v16, 1.0, v16
	v_add_f32_e32 v17, 1.0, v17
	v_add_f32_e32 v18, 1.0, v18
	v_add_f32_e32 v19, 1.0, v19
	v_rcp_f32_e32 v16, v16
	v_rcp_f32_e32 v17, v17
	v_rcp_f32_e32 v18, v18
	v_rcp_f32_e32 v19, v19
	v_mul_f32_e32 v216, 0xbfb8aa3b, v200
	v_mul_f32_e32 v217, 0xbfb8aa3b, v201
	v_mul_f32_e32 v218, 0xbfb8aa3b, v202
	v_mul_f32_e32 v219, 0xbfb8aa3b, v203
	v_exp_f32_e32 v216, v216
	v_exp_f32_e32 v217, v217
	v_exp_f32_e32 v218, v218
	v_exp_f32_e32 v219, v219
	v_pk_mul_f32 v[196:197], v[16:17], v[196:197]
	v_pk_mul_f32 v[198:199], v[18:19], v[198:199]
	v_add_f32_e32 v216, 1.0, v216
	v_add_f32_e32 v217, 1.0, v217
	v_add_f32_e32 v218, 1.0, v218
	v_add_f32_e32 v219, 1.0, v219
	v_rcp_f32_e32 v216, v216
	v_rcp_f32_e32 v217, v217
	v_rcp_f32_e32 v218, v218
	v_rcp_f32_e32 v219, v219
	v_pk_mul_f32 v[200:201], v[216:217], v[200:201]
	v_pk_mul_f32 v[202:203], v[218:219], v[202:203]
	v_pk_mul_f32 v[16:17], v[200:201], v[196:197]
	v_pk_mul_f32 v[18:19], v[202:203], v[198:199]
	v_cvt_pk_bf16_f32 v28, v28, v29
	v_cvt_pk_bf16_f32 v29, v30, v31
	v_cvt_pk_bf16_f32 v30, v24, v25
	v_cvt_pk_bf16_f32 v31, v26, v27
	v_cvt_pk_bf16_f32 v20, v20, v21
	v_cvt_pk_bf16_f32 v21, v22, v23
	v_cvt_pk_bf16_f32 v22, v16, v17
	v_cvt_pk_bf16_f32 v23, v18, v19
	s_add_u32 s62, s62, 0x8000
	s_addc_u32 s63, s63, 0
	v_permlane16_swap_b32_e32 v28, v30
	v_permlane16_swap_b32_e32 v29, v31
	global_store_dwordx4 v249, v[28:31], s[62:63]
	v_permlane16_swap_b32_e32 v20, v22
	v_permlane16_swap_b32_e32 v21, v23
	global_store_dwordx4 v249, v[20:23], s[62:63] offset:256
	s_waitcnt vmcnt(2)
; DI float sigmoidf_(float x) { return __builtin_amdgcn_rcpf(1.0f + __expf(-x)); }
; DI float siluf_(float x) { return x * sigmoidf_(x); }
; template <class FL, class FS>
; DI void gemm8_tile(char* shmc, const bf16_t* __restrict__ A, const bf16_t* __restrict__ Bt, const int K, const int brow, const int bcol, FL fl, FS fs) {
;     ...
; #pragma unroll
;   for (int ai = 0; ai < 2; ++ai)
; #pragma unroll
;     for (int mh = 0; mh < 2; ++mh) {
;       decltype(fl(0, 0)) ld[2][2][2];
; #pragma unroll
;       for (int mm = 0; mm < 2; ++mm)
; #pragma unroll
;         for (int bj = 0; bj < 2; ++bj)
; #pragma unroll
;           for (int n = 0; n < 2; ++n) ld[mm][bj][n] = fl(brow + ai * HALF + wr * 64 + (2 * mh + mm) * 16 + fr, bcol + bj * HALF + wc * 32 + n * 16 + 4 * fq);
; #pragma unroll
;       for (int mm = 0; mm < 2; ++mm)
; #pragma unroll
;         for (int bj = 0; bj < 2; ++bj)
; #pragma unroll
;           for (int n = 0; n < 2; ++n) fs(brow + ai * HALF + wr * 64 + (2 * mh + mm) * 16 + fr, bcol + bj * HALF + wc * 32 + n * 16 + 4 * fq, acc[ai][bj][2 * mh + mm][n], ld[mm][bj][n]);
; DI void phase_g2(const Params& p, const Sub& s, char* lds_all) {
;     ...
;       [&](int row, int col) { const size_t o = (size_t)row * D + col; Ld2 r; const uint2 a = *(const uint2*)(A + o), b = *(const uint2*)(z + o);
;         r.a.x = __uint_as_float(a.x); r.a.y = __uint_as_float(a.y); r.a.z = __uint_as_float(b.x); r.a.w = __uint_as_float(b.y); r.b = *(const float4*)(p.s5_b_glu + col); return r; },
;       [&](int row, int col, f32x4 v, const Ld2& l2) {
;         uint4 ld; ld.x = __float_as_uint(l2.a.x); ld.y = __float_as_uint(l2.a.y); ld.z = __float_as_uint(l2.a.z); ld.w = __float_as_uint(l2.a.w);
;         const size_t o = (size_t)row * D + col;
;         const float y0 = __uint_as_float(ld.x << 16), y1 = __uint_as_float(ld.x & 0xffff0000u), y2_ = __uint_as_float(ld.y << 16), y3 = __uint_as_float(ld.y & 0xffff0000u);
;         const float z0 = __uint_as_float(ld.z << 16), z1 = __uint_as_float(ld.z & 0xffff0000u), z2 = __uint_as_float(ld.w << 16), z3 = __uint_as_float(ld.w & 0xffff0000u);
;         const float4 b4 = l2.b;
;         st_bf4(y2 + o, y0 * sigmoidf_(v[0] + b4.x) * siluf_(z0), y1 * sigmoidf_(v[1] + b4.y) * siluf_(z1),
;                y2_ * sigmoidf_(v[2] + b4.z) * siluf_(z2), y3 * sigmoidf_(v[3] + b4.w) * siluf_(z3));
	v_pk_add_f32 v[12:13], v[12:13], v[172:173]
	v_pk_add_f32 v[14:15], v[14:15], v[174:175]
	v_mul_f32_e32 v12, 0xbfb8aa3b, v12
	v_mul_f32_e32 v13, 0xbfb8aa3b, v13
	v_mul_f32_e32 v14, 0xbfb8aa3b, v14
	v_mul_f32_e32 v15, 0xbfb8aa3b, v15
	v_exp_f32_e32 v12, v12
	v_exp_f32_e32 v13, v13
	v_exp_f32_e32 v14, v14
	v_exp_f32_e32 v15, v15
	v_lshlrev_b32_e32 v196, 16, v220
	v_and_b32_e32 v197, 0xffff0000, v220
	v_lshlrev_b32_e32 v198, 16, v221
	v_and_b32_e32 v199, 0xffff0000, v221
	v_lshlrev_b32_e32 v200, 16, v222
	v_and_b32_e32 v201, 0xffff0000, v222
	v_lshlrev_b32_e32 v202, 16, v223
	v_and_b32_e32 v203, 0xffff0000, v223
	v_add_f32_e32 v12, 1.0, v12
	v_add_f32_e32 v13, 1.0, v13
	v_add_f32_e32 v14, 1.0, v14
	v_add_f32_e32 v15, 1.0, v15
	v_rcp_f32_e32 v12, v12
	v_rcp_f32_e32 v13, v13
	v_rcp_f32_e32 v14, v14
	v_rcp_f32_e32 v15, v15
	v_mul_f32_e32 v220, 0xbfb8aa3b, v200
	v_mul_f32_e32 v221, 0xbfb8aa3b, v201
	v_mul_f32_e32 v222, 0xbfb8aa3b, v202
	v_mul_f32_e32 v223, 0xbfb8aa3b, v203
	v_exp_f32_e32 v220, v220
	v_exp_f32_e32 v221, v221
	v_exp_f32_e32 v222, v222
	v_exp_f32_e32 v223, v223
	v_pk_mul_f32 v[196:197], v[12:13], v[196:197]
	v_pk_mul_f32 v[198:199], v[14:15], v[198:199]
	v_add_f32_e32 v220, 1.0, v220
	v_add_f32_e32 v221, 1.0, v221
	v_add_f32_e32 v222, 1.0, v222
	v_add_f32_e32 v223, 1.0, v223
	v_rcp_f32_e32 v220, v220
	v_rcp_f32_e32 v221, v221
	v_rcp_f32_e32 v222, v222
	v_rcp_f32_e32 v223, v223
	v_pk_mul_f32 v[200:201], v[220:221], v[200:201]
	v_pk_mul_f32 v[202:203], v[222:223], v[202:203]
	v_pk_mul_f32 v[12:13], v[200:201], v[196:197]
	v_pk_mul_f32 v[14:15], v[202:203], v[198:199]
	v_pk_add_f32 v[8:9], v[8:9], v[176:177]
	v_pk_add_f32 v[10:11], v[10:11], v[178:179]
	v_mul_f32_e32 v8, 0xbfb8aa3b, v8
	v_mul_f32_e32 v9, 0xbfb8aa3b, v9
	v_mul_f32_e32 v10, 0xbfb8aa3b, v10
	v_mul_f32_e32 v11, 0xbfb8aa3b, v11
	v_exp_f32_e32 v8, v8
	v_exp_f32_e32 v9, v9
	v_exp_f32_e32 v10, v10
	v_exp_f32_e32 v11, v11
	v_lshlrev_b32_e32 v196, 16, v224
	v_and_b32_e32 v197, 0xffff0000, v224
	v_lshlrev_b32_e32 v198, 16, v225
	v_and_b32_e32 v199, 0xffff0000, v225
	v_lshlrev_b32_e32 v200, 16, v226
	v_and_b32_e32 v201, 0xffff0000, v226
	v_lshlrev_b32_e32 v202, 16, v227
	v_and_b32_e32 v203, 0xffff0000, v227
	v_add_f32_e32 v8, 1.0, v8
	v_add_f32_e32 v9, 1.0, v9
	v_add_f32_e32 v10, 1.0, v10
	v_add_f32_e32 v11, 1.0, v11
	v_rcp_f32_e32 v8, v8
	v_rcp_f32_e32 v9, v9
	v_rcp_f32_e32 v10, v10
	v_rcp_f32_e32 v11, v11
	v_mul_f32_e32 v224, 0xbfb8aa3b, v200
	v_mul_f32_e32 v225, 0xbfb8aa3b, v201
	v_mul_f32_e32 v226, 0xbfb8aa3b, v202
	v_mul_f32_e32 v227, 0xbfb8aa3b, v203
	v_exp_f32_e32 v224, v224
	v_exp_f32_e32 v225, v225
	v_exp_f32_e32 v226, v226
	v_exp_f32_e32 v227, v227
	v_pk_mul_f32 v[196:197], v[8:9], v[196:197]
	v_pk_mul_f32 v[198:199], v[10:11], v[198:199]
	v_add_f32_e32 v224, 1.0, v224
	v_add_f32_e32 v225, 1.0, v225
	v_add_f32_e32 v226, 1.0, v226
	v_add_f32_e32 v227, 1.0, v227
	v_rcp_f32_e32 v224, v224
	v_rcp_f32_e32 v225, v225
	v_rcp_f32_e32 v226, v226
	v_rcp_f32_e32 v227, v227
	v_pk_mul_f32 v[200:201], v[224:225], v[200:201]
	v_pk_mul_f32 v[202:203], v[226:227], v[202:203]
	v_pk_mul_f32 v[8:9], v[200:201], v[196:197]
	v_pk_mul_f32 v[10:11], v[202:203], v[198:199]
	v_pk_add_f32 v[4:5], v[4:5], v[188:189]
	v_pk_add_f32 v[6:7], v[6:7], v[190:191]
	v_mul_f32_e32 v4, 0xbfb8aa3b, v4
	v_mul_f32_e32 v5, 0xbfb8aa3b, v5
	v_mul_f32_e32 v6, 0xbfb8aa3b, v6
	v_mul_f32_e32 v7, 0xbfb8aa3b, v7
	v_exp_f32_e32 v4, v4
	v_exp_f32_e32 v5, v5
	v_exp_f32_e32 v6, v6
	v_exp_f32_e32 v7, v7
	v_lshlrev_b32_e32 v196, 16, v240
	v_and_b32_e32 v197, 0xffff0000, v240
	v_lshlrev_b32_e32 v198, 16, v241
	v_and_b32_e32 v199, 0xffff0000, v241
	v_lshlrev_b32_e32 v200, 16, v242
	v_and_b32_e32 v201, 0xffff0000, v242
	v_lshlrev_b32_e32 v202, 16, v243
	v_and_b32_e32 v203, 0xffff0000, v243
	v_add_f32_e32 v4, 1.0, v4
	v_add_f32_e32 v5, 1.0, v5
	v_add_f32_e32 v6, 1.0, v6
	v_add_f32_e32 v7, 1.0, v7
	v_rcp_f32_e32 v4, v4
	v_rcp_f32_e32 v5, v5
	v_rcp_f32_e32 v6, v6
	v_rcp_f32_e32 v7, v7
	v_mul_f32_e32 v240, 0xbfb8aa3b, v200
	v_mul_f32_e32 v241, 0xbfb8aa3b, v201
	v_mul_f32_e32 v242, 0xbfb8aa3b, v202
	v_mul_f32_e32 v243, 0xbfb8aa3b, v203
	v_exp_f32_e32 v240, v240
	v_exp_f32_e32 v241, v241
	v_exp_f32_e32 v242, v242
	v_exp_f32_e32 v243, v243
	v_pk_mul_f32 v[196:197], v[4:5], v[196:197]
	v_pk_mul_f32 v[198:199], v[6:7], v[198:199]
	v_add_f32_e32 v240, 1.0, v240
	v_add_f32_e32 v241, 1.0, v241
	v_add_f32_e32 v242, 1.0, v242
	v_add_f32_e32 v243, 1.0, v243
	v_rcp_f32_e32 v240, v240
	v_rcp_f32_e32 v241, v241
	v_rcp_f32_e32 v242, v242
	v_rcp_f32_e32 v243, v243
	v_pk_mul_f32 v[200:201], v[240:241], v[200:201]
	v_pk_mul_f32 v[202:203], v[242:243], v[202:203]
	v_pk_mul_f32 v[4:5], v[200:201], v[196:197]
	v_pk_mul_f32 v[6:7], v[202:203], v[198:199]
	v_pk_add_f32 v[0:1], v[0:1], v[192:193]
	v_pk_add_f32 v[2:3], v[2:3], v[194:195]
	v_mul_f32_e32 v0, 0xbfb8aa3b, v0
	v_mul_f32_e32 v1, 0xbfb8aa3b, v1
	v_mul_f32_e32 v2, 0xbfb8aa3b, v2
	v_mul_f32_e32 v3, 0xbfb8aa3b, v3
	v_exp_f32_e32 v0, v0
	v_exp_f32_e32 v1, v1
	v_exp_f32_e32 v2, v2
	v_exp_f32_e32 v3, v3
	v_lshlrev_b32_e32 v196, 16, v244
	v_and_b32_e32 v197, 0xffff0000, v244
	v_lshlrev_b32_e32 v198, 16, v245
	v_and_b32_e32 v199, 0xffff0000, v245
	v_lshlrev_b32_e32 v200, 16, v246
	v_and_b32_e32 v201, 0xffff0000, v246
	v_lshlrev_b32_e32 v202, 16, v247
	v_and_b32_e32 v203, 0xffff0000, v247
	v_add_f32_e32 v0, 1.0, v0
	v_add_f32_e32 v1, 1.0, v1
	v_add_f32_e32 v2, 1.0, v2
	v_add_f32_e32 v3, 1.0, v3
	v_rcp_f32_e32 v0, v0
	v_rcp_f32_e32 v1, v1
	v_rcp_f32_e32 v2, v2
	v_rcp_f32_e32 v3, v3
	v_mul_f32_e32 v244, 0xbfb8aa3b, v200
	v_mul_f32_e32 v245, 0xbfb8aa3b, v201
	v_mul_f32_e32 v246, 0xbfb8aa3b, v202
	v_mul_f32_e32 v247, 0xbfb8aa3b, v203
	v_exp_f32_e32 v244, v244
	v_exp_f32_e32 v245, v245
	v_exp_f32_e32 v246, v246
	v_exp_f32_e32 v247, v247
	v_pk_mul_f32 v[196:197], v[0:1], v[196:197]
	v_pk_mul_f32 v[198:199], v[2:3], v[198:199]
	v_add_f32_e32 v244, 1.0, v244
	v_add_f32_e32 v245, 1.0, v245
	v_add_f32_e32 v246, 1.0, v246
	v_add_f32_e32 v247, 1.0, v247
	v_rcp_f32_e32 v244, v244
	v_rcp_f32_e32 v245, v245
	v_rcp_f32_e32 v246, v246
	v_rcp_f32_e32 v247, v247
	v_pk_mul_f32 v[200:201], v[244:245], v[200:201]
	v_pk_mul_f32 v[202:203], v[246:247], v[202:203]
	v_pk_mul_f32 v[0:1], v[200:201], v[196:197]
	v_pk_mul_f32 v[2:3], v[202:203], v[198:199]
	v_cvt_pk_bf16_f32 v12, v12, v13
	v_cvt_pk_bf16_f32 v13, v14, v15
	v_cvt_pk_bf16_f32 v14, v8, v9
	v_cvt_pk_bf16_f32 v15, v10, v11
	v_cvt_pk_bf16_f32 v4, v4, v5
	v_cvt_pk_bf16_f32 v5, v6, v7
	v_cvt_pk_bf16_f32 v6, v0, v1
	v_cvt_pk_bf16_f32 v7, v2, v3
	s_add_u32 s62, s62, 0x8000
	s_addc_u32 s63, s63, 0
	v_permlane16_swap_b32_e32 v12, v14
	v_permlane16_swap_b32_e32 v13, v15
	global_store_dwordx4 v249, v[12:15], s[62:63]
	v_permlane16_swap_b32_e32 v4, v6
	v_permlane16_swap_b32_e32 v5, v7
	global_store_dwordx4 v249, v[4:7], s[62:63] offset:256
	s_cmp_eq_u32 s101, 0
	s_cbranch_scc1 .Lg2_epi_ret0
	s_branch .LBB0_690
; DI unsigned xb_ld(unsigned* p) { return __hip_atomic_load(p, __ATOMIC_RELAXED, __HIP_MEMORY_SCOPE_AGENT); }
; DI void xcd_barrier_complete(unsigned* bar, unsigned x, unsigned& nloc, unsigned& nx) {
;   const unsigned G = gridDim.x * gridDim.y * gridDim.z;
;   unsigned sum, cnt, mine, sp = 0u;
;   for (;;) {
;     sum = 0u; cnt = 0u; mine = 0u;
; #pragma unroll
;     for (unsigned j = 0; j < 16; ++j) { const unsigned c = xb_ld(&bar[XB_XCNT(j)]); sum += c; cnt += (c > 0u) ? 1u : 0u; mine = (j == x) ? c : mine; }
; DI void xcd_barrier(const XcdBarrier& b) {
;   asm volatile("s_waitcnt vmcnt(0)" ::: "memory");
;   __syncthreads();
;   if (threadIdx.x == 0) {
;     unsigned* bar = b.bar;
;     __builtin_amdgcn_s_waitcnt(0);
;     unsigned nloc = b.st[0], nx = b.st[1];
;     if (nloc == 0u) { xcd_barrier_complete(bar, b.x, nloc, nx); b.st[0] = nloc; b.st[1] = nx; }
.Lg2_w22:
	s_waitcnt vmcnt(22)
	s_branch .Lg2_wd
.LBB0_690:
	s_getreg_b32 s2, hwreg(HW_REG_XCC_ID, 0, 4)
	s_waitcnt vmcnt(0)
	s_barrier
	s_mov_b64 s[4:5], exec
	v_readlane_b32 s0, v251, 5
	v_readlane_b32 s1, v251, 6
	s_and_b64 s[0:1], s[4:5], s[0:1]
	s_mov_b64 exec, s[0:1]
	s_cbranch_execz .LBB0_742
	s_ashr_i32 s1, s33, 31
	v_readlane_b32 s8, v251, 3
	v_readlane_b32 s9, v251, 4
	s_add_u32 s0, s8, s33
	s_addc_u32 s1, s9, s1
	v_mov_b32_e32 v0, 0x20800
	s_load_dwordx2 s[0:1], s[0:1], 0xf8
	s_waitcnt vmcnt(0) expcnt(0) lgkmcnt(0)
	ds_read_b32 v2, v0
	v_mov_b32_e32 v0, 0x20804
	ds_read_b32 v0, v0
	s_and_b32 s33, s2, 15
	s_waitcnt lgkmcnt(1)
	v_cmp_ne_u32_e32 vcc, 0, v2
	s_cbranch_vccnz .LBB0_706
	s_add_u32 s2, s0, 0x16a4300
	s_addc_u32 s3, s1, 0
	s_add_u32 s8, s0, 0x16a4500
	s_addc_u32 s9, s1, 0
	s_add_u32 s10, s0, 0x16a4600
	s_addc_u32 s11, s1, 0
	s_add_u32 s12, s0, 0x16a4700
	s_addc_u32 s13, s1, 0
	s_add_u32 s14, s0, 0x16a4800
	s_addc_u32 s15, s1, 0
	s_add_u32 s16, s0, 0x16a4900
	s_addc_u32 s17, s1, 0
	s_add_u32 s18, s0, 0x16a4a00
	s_addc_u32 s19, s1, 0
	s_add_u32 s20, s0, 0x16a4b00
	s_addc_u32 s21, s1, 0
	s_add_u32 s22, s0, 0x16a4c00
	s_addc_u32 s23, s1, 0
	s_add_u32 s24, s0, 0x16a4d00
	s_addc_u32 s25, s1, 0
	s_add_u32 s26, s0, 0x16a4e00
	s_addc_u32 s27, s1, 0
	s_add_u32 s28, s0, 0x16a4f00
	s_addc_u32 s29, s1, 0
	s_add_u32 s30, s0, 0x16a5000
	s_addc_u32 s31, s1, 0
	s_add_u32 s34, s0, 0x16a5100
	s_addc_u32 s35, s1, 0
	s_add_u32 s36, s0, 0x16a5200
	s_addc_u32 s37, s1, 0
	s_add_u32 s38, s0, 0x16a5300
	s_addc_u32 s39, s1, 0
	s_add_u32 s40, s0, 0x16a5400
	s_addc_u32 s41, s1, 0
	s_mov_b32 s48, 1
	v_mov_b32_e32 v16, 0
	s_branch .LBB0_694
